# GEMM main loops: LDS-DMA staging loads use SGPR base + 32-bit VGPR offset (per-load 64-bit VALU address adds removed), all 8 GEMM kernels
# speedup vs baseline: 1.0019x; 1.0019x over previous
.LBB1_93:
	s_ashr_i32 s19, s18, 31
	s_lshl_b64 s[20:21], s[18:19], 19
	s_add_u32 s20, s33, s20
	s_addc_u32 s21, s34, s21
	s_and_b64 s[22:23], s[0:1], exec
	s_cselect_b32 s5, s21, s27
	s_cselect_b32 s19, s20, s26
	s_ashr_i32 s17, s16, 31
	s_lshl_b64 s[22:23], s[16:17], 19
	s_add_u32 s22, s35, s22
	s_addc_u32 s23, s36, s23
	s_and_b64 s[30:31], s[0:1], exec
	s_cselect_b32 s17, s23, s29
	s_cselect_b32 s25, s22, s28
	s_add_u32 s26, s26, 0x40080
	s_addc_u32 s27, s27, 0
	s_add_u32 s52, s28, 0x100
	s_addc_u32 s53, s29, 0
	s_mov_b32 s54, -2
	ds_read_b128 v[148:151], v153
	ds_read_b128 v[156:159], v153 offset:1024
	ds_read_b128 v[160:163], v153 offset:2048
	ds_read_b128 v[164:167], v153 offset:3072
	ds_read_b128 v[168:171], v154
	ds_read_b128 v[172:175], v154 offset:1024
	ds_read_b128 v[176:179], v154 offset:2048
	ds_read_b128 v[180:183], v154 offset:3072
	s_add_u32 s28, s26, 0xfffc0080
	s_addc_u32 s29, s27, -1
	s_cmp_eq_u32 s54, 12
	s_cselect_b32 s31, s5, s29
	s_cselect_b32 s30, s19, s28
	s_cselect_b32 s29, s17, s53
	s_cselect_b32 s28, s25, s52
	s_add_i32 m0, s38, 0xc000
	ds_read_b128 v[184:187], v155
	ds_read_b128 v[188:191], v155 offset:1024
	ds_read_b128 v[192:195], v155 offset:2048
	ds_read_b128 v[196:199], v155 offset:3072
	ds_read_b128 v[200:203], v155 offset:4096
	ds_read_b128 v[204:207], v155 offset:5120
	ds_read_b128 v[208:211], v155 offset:6144
	ds_read_b128 v[212:215], v155 offset:7168
	global_load_lds_dwordx4 v140, s[26:27]
	s_add_i32 m0, s38, 0xe000
	s_nop 0
	global_load_lds_dwordx4 v142, s[26:27]
	s_waitcnt vmcnt(8)
	s_waitcnt lgkmcnt(0)
	s_barrier
	s_setprio 1
	s_waitcnt lgkmcnt(0)
	v_mfma_f32_16x16x32_bf16 v[124:127], v[148:151], v[184:187], 0
	v_mfma_f32_16x16x32_bf16 v[120:123], v[160:163], v[184:187], 0
	v_mfma_f32_16x16x32_bf16 v[108:111], v[148:151], v[192:195], 0
	v_mfma_f32_16x16x32_bf16 v[104:107], v[160:163], v[192:195], 0
	v_mfma_f32_16x16x32_bf16 v[92:95], v[148:151], v[200:203], 0
	v_mfma_f32_16x16x32_bf16 v[88:91], v[160:163], v[200:203], 0
	v_mfma_f32_16x16x32_bf16 v[76:79], v[148:151], v[208:211], 0
	v_mfma_f32_16x16x32_bf16 v[72:75], v[160:163], v[208:211], 0
	v_mfma_f32_16x16x32_bf16 v[124:127], v[156:159], v[188:191], v[124:127]
	v_mfma_f32_16x16x32_bf16 v[120:123], v[164:167], v[188:191], v[120:123]
	v_mfma_f32_16x16x32_bf16 v[108:111], v[156:159], v[196:199], v[108:111]
	v_mfma_f32_16x16x32_bf16 v[104:107], v[164:167], v[196:199], v[104:107]
	v_mfma_f32_16x16x32_bf16 v[92:95], v[156:159], v[204:207], v[92:95]
	v_mfma_f32_16x16x32_bf16 v[88:91], v[164:167], v[204:207], v[88:91]
	v_mfma_f32_16x16x32_bf16 v[76:79], v[156:159], v[212:215], v[76:79]
	v_mfma_f32_16x16x32_bf16 v[72:75], v[164:167], v[212:215], v[72:75]
	s_setprio 0
	s_setprio 1
	v_mfma_f32_16x16x32_bf16 v[116:119], v[168:171], v[184:187], 0
	v_mfma_f32_16x16x32_bf16 v[112:115], v[176:179], v[184:187], 0
	v_mfma_f32_16x16x32_bf16 v[100:103], v[168:171], v[192:195], 0
	v_mfma_f32_16x16x32_bf16 v[96:99], v[176:179], v[192:195], 0
	v_mfma_f32_16x16x32_bf16 v[84:87], v[168:171], v[200:203], 0
	v_mfma_f32_16x16x32_bf16 v[80:83], v[176:179], v[200:203], 0
	v_mfma_f32_16x16x32_bf16 v[68:71], v[168:171], v[208:211], 0
	v_mfma_f32_16x16x32_bf16 v[64:67], v[176:179], v[208:211], 0
	v_mfma_f32_16x16x32_bf16 v[116:119], v[172:175], v[188:191], v[116:119]
	v_mfma_f32_16x16x32_bf16 v[112:115], v[180:183], v[188:191], v[112:115]
	v_mfma_f32_16x16x32_bf16 v[100:103], v[172:175], v[196:199], v[100:103]
	v_mfma_f32_16x16x32_bf16 v[96:99], v[180:183], v[196:199], v[96:99]
	v_mfma_f32_16x16x32_bf16 v[84:87], v[172:175], v[204:207], v[84:87]
	v_mfma_f32_16x16x32_bf16 v[80:83], v[180:183], v[204:207], v[80:83]
	v_mfma_f32_16x16x32_bf16 v[68:71], v[172:175], v[212:215], v[68:71]
	v_mfma_f32_16x16x32_bf16 v[64:67], v[180:183], v[212:215], v[64:67]
	s_setprio 0
	s_barrier
	s_add_i32 s55, s48, s37
	s_add_u32 s58, s28, 0x80
	s_addc_u32 s59, s29, 0
	s_mov_b32 m0, s55
	ds_read_b128 v[184:187], v155 offset:16384
	ds_read_b128 v[188:191], v155 offset:17408
	ds_read_b128 v[192:195], v155 offset:18432
	ds_read_b128 v[196:199], v155 offset:19456
	ds_read_b128 v[200:203], v155 offset:20480
	ds_read_b128 v[204:207], v155 offset:21504
	ds_read_b128 v[208:211], v155 offset:22528
	ds_read_b128 v[212:215], v155 offset:23552
	global_load_lds_dwordx4 v130, s[28:29]
	s_add_i32 m0, s55, 0x2000
	s_add_u32 s56, s28, 0x40000
	s_addc_u32 s57, s29, 0
	s_add_i32 s55, s49, s37
	global_load_lds_dwordx4 v134, s[28:29]
	s_mov_b32 m0, s55
	s_add_u32 s60, s30, 0x80
	s_addc_u32 s61, s31, 0
	global_load_lds_dwordx4 v130, s[56:57]
	s_add_i32 m0, s55, 0x2000
	s_nop 0
	global_load_lds_dwordx4 v134, s[56:57]
	s_mov_b32 m0, s38
	s_nop 0
	global_load_lds_dwordx4 v128, s[30:31]
	s_mov_b32 m0, s39
	s_nop 0
	global_load_lds_dwordx4 v132, s[30:31]
	s_waitcnt vmcnt(8)
	s_waitcnt lgkmcnt(0)
	s_barrier
	s_setprio 1
	s_waitcnt lgkmcnt(0)
	v_mfma_f32_16x16x32_bf16 v[60:63], v[148:151], v[184:187], 0
	v_mfma_f32_16x16x32_bf16 v[56:59], v[160:163], v[184:187], 0
	v_mfma_f32_16x16x32_bf16 v[44:47], v[148:151], v[192:195], 0
	v_mfma_f32_16x16x32_bf16 v[40:43], v[160:163], v[192:195], 0
	v_mfma_f32_16x16x32_bf16 v[28:31], v[148:151], v[200:203], 0
	v_mfma_f32_16x16x32_bf16 v[24:27], v[160:163], v[200:203], 0
	v_mfma_f32_16x16x32_bf16 v[12:15], v[148:151], v[208:211], 0
	v_mfma_f32_16x16x32_bf16 v[8:11], v[160:163], v[208:211], 0
	v_mfma_f32_16x16x32_bf16 v[60:63], v[156:159], v[188:191], v[60:63]
	v_mfma_f32_16x16x32_bf16 v[56:59], v[164:167], v[188:191], v[56:59]
	v_mfma_f32_16x16x32_bf16 v[44:47], v[156:159], v[196:199], v[44:47]
	v_mfma_f32_16x16x32_bf16 v[40:43], v[164:167], v[196:199], v[40:43]
	v_mfma_f32_16x16x32_bf16 v[28:31], v[156:159], v[204:207], v[28:31]
	v_mfma_f32_16x16x32_bf16 v[24:27], v[164:167], v[204:207], v[24:27]
	v_mfma_f32_16x16x32_bf16 v[12:15], v[156:159], v[212:215], v[12:15]
	v_mfma_f32_16x16x32_bf16 v[8:11], v[164:167], v[212:215], v[8:11]
	s_setprio 0
	s_setprio 1
	v_mfma_f32_16x16x32_bf16 v[52:55], v[168:171], v[184:187], 0
	v_mfma_f32_16x16x32_bf16 v[48:51], v[176:179], v[184:187], 0
	v_mfma_f32_16x16x32_bf16 v[36:39], v[168:171], v[192:195], 0
	v_mfma_f32_16x16x32_bf16 v[32:35], v[176:179], v[192:195], 0
	v_mfma_f32_16x16x32_bf16 v[20:23], v[168:171], v[200:203], 0
	v_mfma_f32_16x16x32_bf16 v[16:19], v[176:179], v[200:203], 0
	v_mfma_f32_16x16x32_bf16 v[4:7], v[168:171], v[208:211], 0
	v_mfma_f32_16x16x32_bf16 v[0:3], v[176:179], v[208:211], 0
	v_mfma_f32_16x16x32_bf16 v[52:55], v[172:175], v[188:191], v[52:55]
	v_mfma_f32_16x16x32_bf16 v[48:51], v[180:183], v[188:191], v[48:51]
	v_mfma_f32_16x16x32_bf16 v[36:39], v[172:175], v[196:199], v[36:39]
	v_mfma_f32_16x16x32_bf16 v[32:35], v[180:183], v[196:199], v[32:35]
	v_mfma_f32_16x16x32_bf16 v[20:23], v[172:175], v[204:207], v[20:23]
	v_mfma_f32_16x16x32_bf16 v[16:19], v[180:183], v[204:207], v[16:19]
	v_mfma_f32_16x16x32_bf16 v[4:7], v[172:175], v[212:215], v[4:7]
	v_mfma_f32_16x16x32_bf16 v[0:3], v[180:183], v[212:215], v[0:3]
	s_setprio 0
	s_barrier
	s_add_i32 s55, 0, 0x18000
	s_add_i32 s56, 0, 0x1c000
	v_add_u32_e32 v164, s55, v152
	v_add_u32_e32 v180, s56, v152
	ds_read_b128 v[148:151], v164
	ds_read_b128 v[156:159], v164 offset:1024
	ds_read_b128 v[160:163], v164 offset:2048
	ds_read_b128 v[164:167], v164 offset:3072
	ds_read_b128 v[168:171], v180
	ds_read_b128 v[172:175], v180 offset:1024
	ds_read_b128 v[176:179], v180 offset:2048
	ds_read_b128 v[180:183], v180 offset:3072
	s_add_u32 s30, s30, 0x40000
	s_addc_u32 s31, s31, 0
	s_mov_b32 m0, s40
	ds_read_b128 v[184:187], v155 offset:32768
	ds_read_b128 v[188:191], v155 offset:33792
	ds_read_b128 v[192:195], v155 offset:34816
	ds_read_b128 v[196:199], v155 offset:35840
	ds_read_b128 v[200:203], v155 offset:36864
	ds_read_b128 v[204:207], v155 offset:37888
	ds_read_b128 v[208:211], v155 offset:38912
	ds_read_b128 v[212:215], v155 offset:39936
	global_load_lds_dwordx4 v128, s[30:31]
	s_mov_b32 m0, s41
	s_nop 0
	global_load_lds_dwordx4 v132, s[30:31]
	s_waitcnt vmcnt(8)
	s_waitcnt lgkmcnt(0)
	s_barrier
	s_setprio 1
	s_waitcnt lgkmcnt(0)
	v_mfma_f32_16x16x32_bf16 v[124:127], v[148:151], v[184:187], v[124:127]
	v_mfma_f32_16x16x32_bf16 v[120:123], v[160:163], v[184:187], v[120:123]
	v_mfma_f32_16x16x32_bf16 v[108:111], v[148:151], v[192:195], v[108:111]
	v_mfma_f32_16x16x32_bf16 v[104:107], v[160:163], v[192:195], v[104:107]
	v_mfma_f32_16x16x32_bf16 v[92:95], v[148:151], v[200:203], v[92:95]
	v_mfma_f32_16x16x32_bf16 v[88:91], v[160:163], v[200:203], v[88:91]
	v_mfma_f32_16x16x32_bf16 v[76:79], v[148:151], v[208:211], v[76:79]
	v_mfma_f32_16x16x32_bf16 v[72:75], v[160:163], v[208:211], v[72:75]
	v_mfma_f32_16x16x32_bf16 v[124:127], v[156:159], v[188:191], v[124:127]
	v_mfma_f32_16x16x32_bf16 v[120:123], v[164:167], v[188:191], v[120:123]
	v_mfma_f32_16x16x32_bf16 v[108:111], v[156:159], v[196:199], v[108:111]
	v_mfma_f32_16x16x32_bf16 v[104:107], v[164:167], v[196:199], v[104:107]
	v_mfma_f32_16x16x32_bf16 v[92:95], v[156:159], v[204:207], v[92:95]
	v_mfma_f32_16x16x32_bf16 v[88:91], v[164:167], v[204:207], v[88:91]
	v_mfma_f32_16x16x32_bf16 v[76:79], v[156:159], v[212:215], v[76:79]
	v_mfma_f32_16x16x32_bf16 v[72:75], v[164:167], v[212:215], v[72:75]
	s_setprio 0
	s_setprio 1
	v_mfma_f32_16x16x32_bf16 v[116:119], v[168:171], v[184:187], v[116:119]
	v_mfma_f32_16x16x32_bf16 v[112:115], v[176:179], v[184:187], v[112:115]
	v_mfma_f32_16x16x32_bf16 v[100:103], v[168:171], v[192:195], v[100:103]
	v_mfma_f32_16x16x32_bf16 v[96:99], v[176:179], v[192:195], v[96:99]
	v_mfma_f32_16x16x32_bf16 v[84:87], v[168:171], v[200:203], v[84:87]
	v_mfma_f32_16x16x32_bf16 v[80:83], v[176:179], v[200:203], v[80:83]
	v_mfma_f32_16x16x32_bf16 v[68:71], v[168:171], v[208:211], v[68:71]
	v_mfma_f32_16x16x32_bf16 v[64:67], v[176:179], v[208:211], v[64:67]
	v_mfma_f32_16x16x32_bf16 v[116:119], v[172:175], v[188:191], v[116:119]
	v_mfma_f32_16x16x32_bf16 v[112:115], v[180:183], v[188:191], v[112:115]
	v_mfma_f32_16x16x32_bf16 v[100:103], v[172:175], v[196:199], v[100:103]
	v_mfma_f32_16x16x32_bf16 v[96:99], v[180:183], v[196:199], v[96:99]
	v_mfma_f32_16x16x32_bf16 v[84:87], v[172:175], v[204:207], v[84:87]
	v_mfma_f32_16x16x32_bf16 v[80:83], v[180:183], v[204:207], v[80:83]
	v_mfma_f32_16x16x32_bf16 v[68:71], v[172:175], v[212:215], v[68:71]
	v_mfma_f32_16x16x32_bf16 v[64:67], v[180:183], v[212:215], v[64:67]
	s_setprio 0
	s_barrier
	s_add_i32 s30, s55, s37
	s_mov_b32 m0, s30
	ds_read_b128 v[184:187], v155 offset:49152
	ds_read_b128 v[188:191], v155 offset:50176
	ds_read_b128 v[192:195], v155 offset:51200
	ds_read_b128 v[196:199], v155 offset:52224
	ds_read_b128 v[200:203], v155 offset:53248
	ds_read_b128 v[204:207], v155 offset:54272
	ds_read_b128 v[208:211], v155 offset:55296
	ds_read_b128 v[212:215], v155 offset:56320
	global_load_lds_dwordx4 v130, s[58:59]
	s_add_i32 m0, s30, 0x2000
	s_add_u32 s28, s28, 0x40080
	s_addc_u32 s29, s29, 0
	s_add_i32 s30, s56, s37
	global_load_lds_dwordx4 v134, s[58:59]
	s_mov_b32 m0, s30
	s_nop 0
	global_load_lds_dwordx4 v130, s[28:29]
	s_add_i32 m0, s30, 0x2000
	s_nop 0
	global_load_lds_dwordx4 v134, s[28:29]
	s_mov_b32 m0, s43
	s_nop 0
	global_load_lds_dwordx4 v128, s[60:61]
	s_mov_b32 m0, s44
	s_nop 0
	global_load_lds_dwordx4 v132, s[60:61]
	s_waitcnt vmcnt(8)
	s_waitcnt lgkmcnt(0)
	s_barrier
	s_setprio 1
	s_waitcnt lgkmcnt(0)
	v_mfma_f32_16x16x32_bf16 v[60:63], v[148:151], v[184:187], v[60:63]
	v_mfma_f32_16x16x32_bf16 v[56:59], v[160:163], v[184:187], v[56:59]
	v_mfma_f32_16x16x32_bf16 v[44:47], v[148:151], v[192:195], v[44:47]
	v_mfma_f32_16x16x32_bf16 v[40:43], v[160:163], v[192:195], v[40:43]
	v_mfma_f32_16x16x32_bf16 v[28:31], v[148:151], v[200:203], v[28:31]
	v_mfma_f32_16x16x32_bf16 v[24:27], v[160:163], v[200:203], v[24:27]
	v_mfma_f32_16x16x32_bf16 v[12:15], v[148:151], v[208:211], v[12:15]
	v_mfma_f32_16x16x32_bf16 v[8:11], v[160:163], v[208:211], v[8:11]
	v_mfma_f32_16x16x32_bf16 v[60:63], v[156:159], v[188:191], v[60:63]
	v_mfma_f32_16x16x32_bf16 v[56:59], v[164:167], v[188:191], v[56:59]
	v_mfma_f32_16x16x32_bf16 v[44:47], v[156:159], v[196:199], v[44:47]
	v_mfma_f32_16x16x32_bf16 v[40:43], v[164:167], v[196:199], v[40:43]
	v_mfma_f32_16x16x32_bf16 v[28:31], v[156:159], v[204:207], v[28:31]
	v_mfma_f32_16x16x32_bf16 v[24:27], v[164:167], v[204:207], v[24:27]
	v_mfma_f32_16x16x32_bf16 v[12:15], v[156:159], v[212:215], v[12:15]
	v_mfma_f32_16x16x32_bf16 v[8:11], v[164:167], v[212:215], v[8:11]
	s_setprio 0
	s_setprio 1
	v_mfma_f32_16x16x32_bf16 v[52:55], v[168:171], v[184:187], v[52:55]
	v_mfma_f32_16x16x32_bf16 v[48:51], v[176:179], v[184:187], v[48:51]
	v_mfma_f32_16x16x32_bf16 v[36:39], v[168:171], v[192:195], v[36:39]
	v_mfma_f32_16x16x32_bf16 v[32:35], v[176:179], v[192:195], v[32:35]
	v_mfma_f32_16x16x32_bf16 v[20:23], v[168:171], v[200:203], v[20:23]
	v_mfma_f32_16x16x32_bf16 v[16:19], v[176:179], v[200:203], v[16:19]
	v_mfma_f32_16x16x32_bf16 v[4:7], v[168:171], v[208:211], v[4:7]
	v_mfma_f32_16x16x32_bf16 v[0:3], v[176:179], v[208:211], v[0:3]
	v_mfma_f32_16x16x32_bf16 v[52:55], v[172:175], v[188:191], v[52:55]
	v_mfma_f32_16x16x32_bf16 v[48:51], v[180:183], v[188:191], v[48:51]
	v_mfma_f32_16x16x32_bf16 v[36:39], v[172:175], v[196:199], v[36:39]
	v_mfma_f32_16x16x32_bf16 v[32:35], v[180:183], v[196:199], v[32:35]
	v_mfma_f32_16x16x32_bf16 v[20:23], v[172:175], v[204:207], v[20:23]
	v_mfma_f32_16x16x32_bf16 v[16:19], v[180:183], v[204:207], v[16:19]
	v_mfma_f32_16x16x32_bf16 v[4:7], v[172:175], v[212:215], v[4:7]
	v_mfma_f32_16x16x32_bf16 v[0:3], v[180:183], v[212:215], v[0:3]
	s_setprio 0
	s_barrier
	s_add_i32 s54, s54, 2
	s_add_u32 s26, s26, 0x100
	s_addc_u32 s27, s27, 0
	s_add_u32 s52, s52, 0x100
	s_addc_u32 s53, s53, 0
	s_cmp_gt_u32 s54, 13
.LBB1_94:
	ds_read_b128 v[148:151], v153
	ds_read_b128 v[156:159], v153 offset:1024
	ds_read_b128 v[160:163], v153 offset:2048
	ds_read_b128 v[164:167], v153 offset:3072
	ds_read_b128 v[168:171], v154
	ds_read_b128 v[172:175], v154 offset:1024
	ds_read_b128 v[176:179], v154 offset:2048
	ds_read_b128 v[180:183], v154 offset:3072
	s_add_u32 s28, s26, 0xfffc0080
	s_addc_u32 s29, s27, -1
	s_cmp_eq_u32 s54, 12
	s_cselect_b32 s31, s5, s29
	s_cselect_b32 s30, s19, s28
	s_cselect_b32 s29, s17, s53
	s_cselect_b32 s28, s25, s52
	s_add_i32 m0, s38, 0xc000
	ds_read_b128 v[184:187], v155
	ds_read_b128 v[188:191], v155 offset:1024
	ds_read_b128 v[192:195], v155 offset:2048
	ds_read_b128 v[196:199], v155 offset:3072
	ds_read_b128 v[200:203], v155 offset:4096
	ds_read_b128 v[204:207], v155 offset:5120
	ds_read_b128 v[208:211], v155 offset:6144
	ds_read_b128 v[212:215], v155 offset:7168
	global_load_lds_dwordx4 v140, s[26:27]
	s_add_i32 m0, s38, 0xe000
	s_nop 0
	global_load_lds_dwordx4 v142, s[26:27]
	s_waitcnt vmcnt(8)
	s_waitcnt lgkmcnt(0)
	s_barrier
	s_setprio 1
	s_waitcnt lgkmcnt(0)
	v_mfma_f32_16x16x32_bf16 v[124:127], v[148:151], v[184:187], v[124:127]
	v_mfma_f32_16x16x32_bf16 v[120:123], v[160:163], v[184:187], v[120:123]
	v_mfma_f32_16x16x32_bf16 v[108:111], v[148:151], v[192:195], v[108:111]
	v_mfma_f32_16x16x32_bf16 v[104:107], v[160:163], v[192:195], v[104:107]
	v_mfma_f32_16x16x32_bf16 v[92:95], v[148:151], v[200:203], v[92:95]
	v_mfma_f32_16x16x32_bf16 v[88:91], v[160:163], v[200:203], v[88:91]
	v_mfma_f32_16x16x32_bf16 v[76:79], v[148:151], v[208:211], v[76:79]
	v_mfma_f32_16x16x32_bf16 v[72:75], v[160:163], v[208:211], v[72:75]
	v_mfma_f32_16x16x32_bf16 v[124:127], v[156:159], v[188:191], v[124:127]
	v_mfma_f32_16x16x32_bf16 v[120:123], v[164:167], v[188:191], v[120:123]
	v_mfma_f32_16x16x32_bf16 v[108:111], v[156:159], v[196:199], v[108:111]
	v_mfma_f32_16x16x32_bf16 v[104:107], v[164:167], v[196:199], v[104:107]
	v_mfma_f32_16x16x32_bf16 v[92:95], v[156:159], v[204:207], v[92:95]
	v_mfma_f32_16x16x32_bf16 v[88:91], v[164:167], v[204:207], v[88:91]
	v_mfma_f32_16x16x32_bf16 v[76:79], v[156:159], v[212:215], v[76:79]
	v_mfma_f32_16x16x32_bf16 v[72:75], v[164:167], v[212:215], v[72:75]
	s_setprio 0
	s_setprio 1
	v_mfma_f32_16x16x32_bf16 v[116:119], v[168:171], v[184:187], v[116:119]
	v_mfma_f32_16x16x32_bf16 v[112:115], v[176:179], v[184:187], v[112:115]
	v_mfma_f32_16x16x32_bf16 v[100:103], v[168:171], v[192:195], v[100:103]
	v_mfma_f32_16x16x32_bf16 v[96:99], v[176:179], v[192:195], v[96:99]
	v_mfma_f32_16x16x32_bf16 v[84:87], v[168:171], v[200:203], v[84:87]
	v_mfma_f32_16x16x32_bf16 v[80:83], v[176:179], v[200:203], v[80:83]
	v_mfma_f32_16x16x32_bf16 v[68:71], v[168:171], v[208:211], v[68:71]
	v_mfma_f32_16x16x32_bf16 v[64:67], v[176:179], v[208:211], v[64:67]
	v_mfma_f32_16x16x32_bf16 v[116:119], v[172:175], v[188:191], v[116:119]
	v_mfma_f32_16x16x32_bf16 v[112:115], v[180:183], v[188:191], v[112:115]
	v_mfma_f32_16x16x32_bf16 v[100:103], v[172:175], v[196:199], v[100:103]
	v_mfma_f32_16x16x32_bf16 v[96:99], v[180:183], v[196:199], v[96:99]
	v_mfma_f32_16x16x32_bf16 v[84:87], v[172:175], v[204:207], v[84:87]
	v_mfma_f32_16x16x32_bf16 v[80:83], v[180:183], v[204:207], v[80:83]
	v_mfma_f32_16x16x32_bf16 v[68:71], v[172:175], v[212:215], v[68:71]
	v_mfma_f32_16x16x32_bf16 v[64:67], v[180:183], v[212:215], v[64:67]
	s_setprio 0
	s_barrier
	s_add_i32 s55, s48, s37
	s_add_u32 s58, s28, 0x80
	s_addc_u32 s59, s29, 0
	s_mov_b32 m0, s55
	ds_read_b128 v[184:187], v155 offset:16384
	ds_read_b128 v[188:191], v155 offset:17408
	ds_read_b128 v[192:195], v155 offset:18432
	ds_read_b128 v[196:199], v155 offset:19456
	ds_read_b128 v[200:203], v155 offset:20480
	ds_read_b128 v[204:207], v155 offset:21504
	ds_read_b128 v[208:211], v155 offset:22528
	ds_read_b128 v[212:215], v155 offset:23552
	global_load_lds_dwordx4 v130, s[28:29]
	s_add_i32 m0, s55, 0x2000
	s_add_u32 s56, s28, 0x40000
	s_addc_u32 s57, s29, 0
	s_add_i32 s55, s49, s37
	global_load_lds_dwordx4 v134, s[28:29]
	s_mov_b32 m0, s55
	s_add_u32 s60, s30, 0x80
	s_addc_u32 s61, s31, 0
	global_load_lds_dwordx4 v130, s[56:57]
	s_add_i32 m0, s55, 0x2000
	s_nop 0
	global_load_lds_dwordx4 v134, s[56:57]
	s_mov_b32 m0, s38
	s_nop 0
	global_load_lds_dwordx4 v128, s[30:31]
	s_mov_b32 m0, s39
	s_nop 0
	global_load_lds_dwordx4 v132, s[30:31]
	s_waitcnt vmcnt(8)
	s_waitcnt lgkmcnt(0)
	s_barrier
	s_setprio 1
	s_waitcnt lgkmcnt(0)
	v_mfma_f32_16x16x32_bf16 v[60:63], v[148:151], v[184:187], v[60:63]
	v_mfma_f32_16x16x32_bf16 v[56:59], v[160:163], v[184:187], v[56:59]
	v_mfma_f32_16x16x32_bf16 v[44:47], v[148:151], v[192:195], v[44:47]
	v_mfma_f32_16x16x32_bf16 v[40:43], v[160:163], v[192:195], v[40:43]
	v_mfma_f32_16x16x32_bf16 v[28:31], v[148:151], v[200:203], v[28:31]
	v_mfma_f32_16x16x32_bf16 v[24:27], v[160:163], v[200:203], v[24:27]
	v_mfma_f32_16x16x32_bf16 v[12:15], v[148:151], v[208:211], v[12:15]
	v_mfma_f32_16x16x32_bf16 v[8:11], v[160:163], v[208:211], v[8:11]
	v_mfma_f32_16x16x32_bf16 v[60:63], v[156:159], v[188:191], v[60:63]
	v_mfma_f32_16x16x32_bf16 v[56:59], v[164:167], v[188:191], v[56:59]
	v_mfma_f32_16x16x32_bf16 v[44:47], v[156:159], v[196:199], v[44:47]
	v_mfma_f32_16x16x32_bf16 v[40:43], v[164:167], v[196:199], v[40:43]
	v_mfma_f32_16x16x32_bf16 v[28:31], v[156:159], v[204:207], v[28:31]
	v_mfma_f32_16x16x32_bf16 v[24:27], v[164:167], v[204:207], v[24:27]
	v_mfma_f32_16x16x32_bf16 v[12:15], v[156:159], v[212:215], v[12:15]
	v_mfma_f32_16x16x32_bf16 v[8:11], v[164:167], v[212:215], v[8:11]
	s_setprio 0
	s_setprio 1
	v_mfma_f32_16x16x32_bf16 v[52:55], v[168:171], v[184:187], v[52:55]
	v_mfma_f32_16x16x32_bf16 v[48:51], v[176:179], v[184:187], v[48:51]
	v_mfma_f32_16x16x32_bf16 v[36:39], v[168:171], v[192:195], v[36:39]
	v_mfma_f32_16x16x32_bf16 v[32:35], v[176:179], v[192:195], v[32:35]
	v_mfma_f32_16x16x32_bf16 v[20:23], v[168:171], v[200:203], v[20:23]
	v_mfma_f32_16x16x32_bf16 v[16:19], v[176:179], v[200:203], v[16:19]
	v_mfma_f32_16x16x32_bf16 v[4:7], v[168:171], v[208:211], v[4:7]
	v_mfma_f32_16x16x32_bf16 v[0:3], v[176:179], v[208:211], v[0:3]
	v_mfma_f32_16x16x32_bf16 v[52:55], v[172:175], v[188:191], v[52:55]
	v_mfma_f32_16x16x32_bf16 v[48:51], v[180:183], v[188:191], v[48:51]
	v_mfma_f32_16x16x32_bf16 v[36:39], v[172:175], v[196:199], v[36:39]
	v_mfma_f32_16x16x32_bf16 v[32:35], v[180:183], v[196:199], v[32:35]
	v_mfma_f32_16x16x32_bf16 v[20:23], v[172:175], v[204:207], v[20:23]
	v_mfma_f32_16x16x32_bf16 v[16:19], v[180:183], v[204:207], v[16:19]
	v_mfma_f32_16x16x32_bf16 v[4:7], v[172:175], v[212:215], v[4:7]
	v_mfma_f32_16x16x32_bf16 v[0:3], v[180:183], v[212:215], v[0:3]
	s_setprio 0
	s_barrier
	s_add_i32 s55, 0, 0x18000
	s_add_i32 s56, 0, 0x1c000
	v_add_u32_e32 v164, s55, v152
	v_add_u32_e32 v180, s56, v152
	ds_read_b128 v[148:151], v164
	ds_read_b128 v[156:159], v164 offset:1024
	ds_read_b128 v[160:163], v164 offset:2048
	ds_read_b128 v[164:167], v164 offset:3072
	ds_read_b128 v[168:171], v180
	ds_read_b128 v[172:175], v180 offset:1024
	ds_read_b128 v[176:179], v180 offset:2048
	ds_read_b128 v[180:183], v180 offset:3072
	s_add_u32 s30, s30, 0x40000
	s_addc_u32 s31, s31, 0
	s_mov_b32 m0, s40
	ds_read_b128 v[184:187], v155 offset:32768
	ds_read_b128 v[188:191], v155 offset:33792
	ds_read_b128 v[192:195], v155 offset:34816
	ds_read_b128 v[196:199], v155 offset:35840
	ds_read_b128 v[200:203], v155 offset:36864
	ds_read_b128 v[204:207], v155 offset:37888
	ds_read_b128 v[208:211], v155 offset:38912
	ds_read_b128 v[212:215], v155 offset:39936
	global_load_lds_dwordx4 v128, s[30:31]
	s_mov_b32 m0, s41
	s_nop 0
	global_load_lds_dwordx4 v132, s[30:31]
	s_waitcnt vmcnt(8)
	s_waitcnt lgkmcnt(0)
	s_barrier
	s_setprio 1
	s_waitcnt lgkmcnt(0)
	v_mfma_f32_16x16x32_bf16 v[124:127], v[148:151], v[184:187], v[124:127]
	v_mfma_f32_16x16x32_bf16 v[120:123], v[160:163], v[184:187], v[120:123]
	v_mfma_f32_16x16x32_bf16 v[108:111], v[148:151], v[192:195], v[108:111]
	v_mfma_f32_16x16x32_bf16 v[104:107], v[160:163], v[192:195], v[104:107]
	v_mfma_f32_16x16x32_bf16 v[92:95], v[148:151], v[200:203], v[92:95]
	v_mfma_f32_16x16x32_bf16 v[88:91], v[160:163], v[200:203], v[88:91]
	v_mfma_f32_16x16x32_bf16 v[76:79], v[148:151], v[208:211], v[76:79]
	v_mfma_f32_16x16x32_bf16 v[72:75], v[160:163], v[208:211], v[72:75]
	v_mfma_f32_16x16x32_bf16 v[124:127], v[156:159], v[188:191], v[124:127]
	v_mfma_f32_16x16x32_bf16 v[120:123], v[164:167], v[188:191], v[120:123]
	v_mfma_f32_16x16x32_bf16 v[108:111], v[156:159], v[196:199], v[108:111]
	v_mfma_f32_16x16x32_bf16 v[104:107], v[164:167], v[196:199], v[104:107]
	v_mfma_f32_16x16x32_bf16 v[92:95], v[156:159], v[204:207], v[92:95]
	v_mfma_f32_16x16x32_bf16 v[88:91], v[164:167], v[204:207], v[88:91]
	v_mfma_f32_16x16x32_bf16 v[76:79], v[156:159], v[212:215], v[76:79]
	v_mfma_f32_16x16x32_bf16 v[72:75], v[164:167], v[212:215], v[72:75]
	s_setprio 0
	s_setprio 1
	v_mfma_f32_16x16x32_bf16 v[116:119], v[168:171], v[184:187], v[116:119]
	v_mfma_f32_16x16x32_bf16 v[112:115], v[176:179], v[184:187], v[112:115]
	v_mfma_f32_16x16x32_bf16 v[100:103], v[168:171], v[192:195], v[100:103]
	v_mfma_f32_16x16x32_bf16 v[96:99], v[176:179], v[192:195], v[96:99]
	v_mfma_f32_16x16x32_bf16 v[84:87], v[168:171], v[200:203], v[84:87]
	v_mfma_f32_16x16x32_bf16 v[80:83], v[176:179], v[200:203], v[80:83]
	v_mfma_f32_16x16x32_bf16 v[68:71], v[168:171], v[208:211], v[68:71]
	v_mfma_f32_16x16x32_bf16 v[64:67], v[176:179], v[208:211], v[64:67]
	v_mfma_f32_16x16x32_bf16 v[116:119], v[172:175], v[188:191], v[116:119]
	v_mfma_f32_16x16x32_bf16 v[112:115], v[180:183], v[188:191], v[112:115]
	v_mfma_f32_16x16x32_bf16 v[100:103], v[172:175], v[196:199], v[100:103]
	v_mfma_f32_16x16x32_bf16 v[96:99], v[180:183], v[196:199], v[96:99]
	v_mfma_f32_16x16x32_bf16 v[84:87], v[172:175], v[204:207], v[84:87]
	v_mfma_f32_16x16x32_bf16 v[80:83], v[180:183], v[204:207], v[80:83]
	v_mfma_f32_16x16x32_bf16 v[68:71], v[172:175], v[212:215], v[68:71]
	v_mfma_f32_16x16x32_bf16 v[64:67], v[180:183], v[212:215], v[64:67]
	s_setprio 0
	s_barrier
	s_add_i32 s30, s55, s37
	s_mov_b32 m0, s30
	ds_read_b128 v[184:187], v155 offset:49152
	ds_read_b128 v[188:191], v155 offset:50176
	ds_read_b128 v[192:195], v155 offset:51200
	ds_read_b128 v[196:199], v155 offset:52224
	ds_read_b128 v[200:203], v155 offset:53248
	ds_read_b128 v[204:207], v155 offset:54272
	ds_read_b128 v[208:211], v155 offset:55296
	ds_read_b128 v[212:215], v155 offset:56320
	global_load_lds_dwordx4 v130, s[58:59]
	s_add_i32 m0, s30, 0x2000
	s_add_u32 s28, s28, 0x40080
	s_addc_u32 s29, s29, 0
	s_add_i32 s30, s56, s37
	global_load_lds_dwordx4 v134, s[58:59]
	s_mov_b32 m0, s30
	s_nop 0
	global_load_lds_dwordx4 v130, s[28:29]
	s_add_i32 m0, s30, 0x2000
	s_nop 0
	global_load_lds_dwordx4 v134, s[28:29]
	s_mov_b32 m0, s43
	s_nop 0
	global_load_lds_dwordx4 v128, s[60:61]
	s_mov_b32 m0, s44
	s_nop 0
	global_load_lds_dwordx4 v132, s[60:61]
	s_waitcnt vmcnt(8)
	s_waitcnt lgkmcnt(0)
	s_barrier
	s_setprio 1
	s_waitcnt lgkmcnt(0)
	v_mfma_f32_16x16x32_bf16 v[60:63], v[148:151], v[184:187], v[60:63]
	v_mfma_f32_16x16x32_bf16 v[56:59], v[160:163], v[184:187], v[56:59]
	v_mfma_f32_16x16x32_bf16 v[44:47], v[148:151], v[192:195], v[44:47]
	v_mfma_f32_16x16x32_bf16 v[40:43], v[160:163], v[192:195], v[40:43]
	v_mfma_f32_16x16x32_bf16 v[28:31], v[148:151], v[200:203], v[28:31]
	v_mfma_f32_16x16x32_bf16 v[24:27], v[160:163], v[200:203], v[24:27]
	v_mfma_f32_16x16x32_bf16 v[12:15], v[148:151], v[208:211], v[12:15]
	v_mfma_f32_16x16x32_bf16 v[8:11], v[160:163], v[208:211], v[8:11]
	v_mfma_f32_16x16x32_bf16 v[60:63], v[156:159], v[188:191], v[60:63]
	v_mfma_f32_16x16x32_bf16 v[56:59], v[164:167], v[188:191], v[56:59]
	v_mfma_f32_16x16x32_bf16 v[44:47], v[156:159], v[196:199], v[44:47]
	v_mfma_f32_16x16x32_bf16 v[40:43], v[164:167], v[196:199], v[40:43]
	v_mfma_f32_16x16x32_bf16 v[28:31], v[156:159], v[204:207], v[28:31]
	v_mfma_f32_16x16x32_bf16 v[24:27], v[164:167], v[204:207], v[24:27]
	v_mfma_f32_16x16x32_bf16 v[12:15], v[156:159], v[212:215], v[12:15]
	v_mfma_f32_16x16x32_bf16 v[8:11], v[164:167], v[212:215], v[8:11]
	s_setprio 0
	s_setprio 1
	v_mfma_f32_16x16x32_bf16 v[52:55], v[168:171], v[184:187], v[52:55]
	v_mfma_f32_16x16x32_bf16 v[48:51], v[176:179], v[184:187], v[48:51]
	v_mfma_f32_16x16x32_bf16 v[36:39], v[168:171], v[192:195], v[36:39]
	v_mfma_f32_16x16x32_bf16 v[32:35], v[176:179], v[192:195], v[32:35]
	v_mfma_f32_16x16x32_bf16 v[20:23], v[168:171], v[200:203], v[20:23]
	v_mfma_f32_16x16x32_bf16 v[16:19], v[176:179], v[200:203], v[16:19]
	v_mfma_f32_16x16x32_bf16 v[4:7], v[168:171], v[208:211], v[4:7]
	v_mfma_f32_16x16x32_bf16 v[0:3], v[176:179], v[208:211], v[0:3]
	v_mfma_f32_16x16x32_bf16 v[52:55], v[172:175], v[188:191], v[52:55]
	v_mfma_f32_16x16x32_bf16 v[48:51], v[180:183], v[188:191], v[48:51]
	v_mfma_f32_16x16x32_bf16 v[36:39], v[172:175], v[196:199], v[36:39]
	v_mfma_f32_16x16x32_bf16 v[32:35], v[180:183], v[196:199], v[32:35]
	v_mfma_f32_16x16x32_bf16 v[20:23], v[172:175], v[204:207], v[20:23]
	v_mfma_f32_16x16x32_bf16 v[16:19], v[180:183], v[204:207], v[16:19]
	v_mfma_f32_16x16x32_bf16 v[4:7], v[172:175], v[212:215], v[4:7]
	v_mfma_f32_16x16x32_bf16 v[0:3], v[180:183], v[212:215], v[0:3]
	s_setprio 0
	s_barrier
	s_add_i32 s54, s54, 2
	s_add_u32 s26, s26, 0x100
	s_addc_u32 s27, s27, 0
	s_add_u32 s52, s52, 0x100
	s_addc_u32 s53, s53, 0
	s_cmp_gt_u32 s54, 13
	s_cbranch_scc0 .LBB1_94
	s_and_b64 vcc, exec, s[14:15]
	s_cbranch_vccz .LBB1_97
	s_barrier

	.amdhsa_kernel _Z10fwd_kernelILi1ELi2EEv4Args
		.amdhsa_group_segment_fixed_size 0
		.amdhsa_private_segment_fixed_size 0
		.amdhsa_kernarg_size 488
		.amdhsa_user_sgpr_count 2
		.amdhsa_user_sgpr_dispatch_ptr 0
		.amdhsa_user_sgpr_queue_ptr 0
		.amdhsa_user_sgpr_kernarg_segment_ptr 1
		.amdhsa_user_sgpr_dispatch_id 0
		.amdhsa_user_sgpr_kernarg_preload_length 0
		.amdhsa_user_sgpr_kernarg_preload_offset 0
		.amdhsa_user_sgpr_private_segment_size 0
		.amdhsa_uses_dynamic_stack 0
		.amdhsa_enable_private_segment 0
		.amdhsa_system_sgpr_workgroup_id_x 1
		.amdhsa_system_sgpr_workgroup_id_y 0
		.amdhsa_system_sgpr_workgroup_id_z 0
		.amdhsa_system_sgpr_workgroup_info 0
		.amdhsa_system_vgpr_workitem_id 0
		.amdhsa_next_free_vgpr 256
		.amdhsa_next_free_sgpr 66
		.amdhsa_accum_offset 256
		.amdhsa_reserve_vcc 1
		.amdhsa_float_round_mode_32 0
		.amdhsa_float_round_mode_16_64 0
		.amdhsa_float_denorm_mode_32 3
		.amdhsa_float_denorm_mode_16_64 3
		.amdhsa_dx10_clamp 1
		.amdhsa_ieee_mode 1
		.amdhsa_fp16_overflow 0
		.amdhsa_tg_split 0
		.amdhsa_exception_fp_ieee_invalid_op 0
		.amdhsa_exception_fp_denorm_src 0
		.amdhsa_exception_fp_ieee_div_zero 0
		.amdhsa_exception_fp_ieee_overflow 0
		.amdhsa_exception_fp_ieee_underflow 0
		.amdhsa_exception_fp_ieee_inexact 0
		.amdhsa_exception_int_div_zero 0
	.end_amdhsa_kernel

.LBB3_19:
	s_ashr_i32 s17, s16, 31
	s_lshl_b64 s[18:19], s[16:17], 19
	s_add_u32 s18, s33, s18
	v_cmp_lt_i64_e64 s[4:5], s[4:5], v[142:143]
	s_addc_u32 s19, s34, s19
	s_and_b64 s[20:21], s[4:5], exec
	s_cselect_b32 s17, s19, s25
	s_cselect_b32 s53, s18, s24
	s_ashr_i32 s15, s14, 31
	s_lshl_b64 s[20:21], s[14:15], 19
	s_add_u32 s20, s6, s20
	s_addc_u32 s21, s7, s21
	s_and_b64 s[28:29], s[4:5], exec
	s_cselect_b32 s15, s21, s27
	s_cselect_b32 s54, s20, s26
	s_add_u32 s24, s24, 0x40080
	s_addc_u32 s25, s25, 0
	s_add_u32 s55, s26, 0x100
	s_addc_u32 s56, s27, 0
	s_mov_b32 s57, -2
	ds_read_b128 v[152:155], v149
	ds_read_b128 v[156:159], v149 offset:1024
	ds_read_b128 v[160:163], v149 offset:2048
	ds_read_b128 v[164:167], v149 offset:3072
	ds_read_b128 v[168:171], v150
	ds_read_b128 v[172:175], v150 offset:1024
	ds_read_b128 v[176:179], v150 offset:2048
	ds_read_b128 v[180:183], v150 offset:3072
	s_add_u32 s26, s24, 0xfffc0080
	s_addc_u32 s27, s25, -1
	s_cmp_eq_u32 s57, 12
	s_cselect_b32 s29, s17, s27
	s_cselect_b32 s28, s53, s26
	s_cselect_b32 s27, s15, s56
	s_cselect_b32 s26, s54, s55
	s_add_i32 m0, s23, 0xc000
	ds_read_b128 v[184:187], v151
	ds_read_b128 v[188:191], v151 offset:1024
	ds_read_b128 v[192:195], v151 offset:2048
	ds_read_b128 v[196:199], v151 offset:3072
	ds_read_b128 v[200:203], v151 offset:4096
	ds_read_b128 v[204:207], v151 offset:5120
	ds_read_b128 v[208:211], v151 offset:6144
	ds_read_b128 v[212:215], v151 offset:7168
	global_load_lds_dwordx4 v138, s[24:25]
	s_add_i32 m0, s23, 0xe000
	s_nop 0
	global_load_lds_dwordx4 v140, s[24:25]
	s_waitcnt vmcnt(8)
	s_waitcnt lgkmcnt(0)
	s_barrier
	s_setprio 1
	s_waitcnt lgkmcnt(0)
	v_mfma_f32_16x16x32_bf16 v[124:127], v[152:155], v[184:187], 0
	v_mfma_f32_16x16x32_bf16 v[120:123], v[160:163], v[184:187], 0
	v_mfma_f32_16x16x32_bf16 v[116:119], v[152:155], v[192:195], 0
	v_mfma_f32_16x16x32_bf16 v[108:111], v[160:163], v[192:195], 0
	v_mfma_f32_16x16x32_bf16 v[100:103], v[152:155], v[200:203], 0
	v_mfma_f32_16x16x32_bf16 v[92:95], v[160:163], v[200:203], 0
	v_mfma_f32_16x16x32_bf16 v[84:87], v[152:155], v[208:211], 0
	v_mfma_f32_16x16x32_bf16 v[76:79], v[160:163], v[208:211], 0
	v_mfma_f32_16x16x32_bf16 v[124:127], v[156:159], v[188:191], v[124:127]
	v_mfma_f32_16x16x32_bf16 v[120:123], v[164:167], v[188:191], v[120:123]
	v_mfma_f32_16x16x32_bf16 v[116:119], v[156:159], v[196:199], v[116:119]
	v_mfma_f32_16x16x32_bf16 v[108:111], v[164:167], v[196:199], v[108:111]
	v_mfma_f32_16x16x32_bf16 v[100:103], v[156:159], v[204:207], v[100:103]
	v_mfma_f32_16x16x32_bf16 v[92:95], v[164:167], v[204:207], v[92:95]
	v_mfma_f32_16x16x32_bf16 v[84:87], v[156:159], v[212:215], v[84:87]
	v_mfma_f32_16x16x32_bf16 v[76:79], v[164:167], v[212:215], v[76:79]
	s_setprio 0
	s_setprio 1
	v_mfma_f32_16x16x32_bf16 v[112:115], v[168:171], v[184:187], 0
	v_mfma_f32_16x16x32_bf16 v[104:107], v[176:179], v[184:187], 0
	v_mfma_f32_16x16x32_bf16 v[96:99], v[168:171], v[192:195], 0
	v_mfma_f32_16x16x32_bf16 v[88:91], v[176:179], v[192:195], 0
	v_mfma_f32_16x16x32_bf16 v[80:83], v[168:171], v[200:203], 0
	v_mfma_f32_16x16x32_bf16 v[72:75], v[176:179], v[200:203], 0
	v_mfma_f32_16x16x32_bf16 v[68:71], v[168:171], v[208:211], 0
	v_mfma_f32_16x16x32_bf16 v[64:67], v[176:179], v[208:211], 0
	v_mfma_f32_16x16x32_bf16 v[112:115], v[172:175], v[188:191], v[112:115]
	v_mfma_f32_16x16x32_bf16 v[104:107], v[180:183], v[188:191], v[104:107]
	v_mfma_f32_16x16x32_bf16 v[96:99], v[172:175], v[196:199], v[96:99]
	v_mfma_f32_16x16x32_bf16 v[88:91], v[180:183], v[196:199], v[88:91]
	v_mfma_f32_16x16x32_bf16 v[80:83], v[172:175], v[204:207], v[80:83]
	v_mfma_f32_16x16x32_bf16 v[72:75], v[180:183], v[204:207], v[72:75]
	v_mfma_f32_16x16x32_bf16 v[68:71], v[172:175], v[212:215], v[68:71]
	v_mfma_f32_16x16x32_bf16 v[64:67], v[180:183], v[212:215], v[64:67]
	s_setprio 0
	s_barrier
	s_add_i32 s58, s45, s31
	s_add_u32 s62, s26, 0x80
	s_addc_u32 s63, s27, 0
	s_mov_b32 m0, s58
	ds_read_b128 v[184:187], v151 offset:16384
	ds_read_b128 v[188:191], v151 offset:17408
	ds_read_b128 v[192:195], v151 offset:18432
	ds_read_b128 v[196:199], v151 offset:19456
	ds_read_b128 v[200:203], v151 offset:20480
	ds_read_b128 v[204:207], v151 offset:21504
	ds_read_b128 v[208:211], v151 offset:22528
	ds_read_b128 v[212:215], v151 offset:23552
	global_load_lds_dwordx4 v130, s[26:27]
	s_add_i32 m0, s58, 0x2000
	s_add_u32 s58, s26, 0x40000
	s_addc_u32 s59, s27, 0
	s_add_i32 s60, s46, s31
	global_load_lds_dwordx4 v134, s[26:27]
	s_mov_b32 m0, s60
	s_add_u32 s64, s28, 0x80
	s_addc_u32 s65, s29, 0
	global_load_lds_dwordx4 v130, s[58:59]
	s_add_i32 m0, s60, 0x2000
	s_nop 0
	global_load_lds_dwordx4 v134, s[58:59]
	s_mov_b32 m0, s23
	s_nop 0
	global_load_lds_dwordx4 v128, s[28:29]
	s_mov_b32 m0, s35
	s_nop 0
	global_load_lds_dwordx4 v132, s[28:29]
	s_waitcnt vmcnt(8)
	s_waitcnt lgkmcnt(0)
	s_barrier
	s_setprio 1
	s_waitcnt lgkmcnt(0)
	v_mfma_f32_16x16x32_bf16 v[60:63], v[152:155], v[184:187], 0
	v_mfma_f32_16x16x32_bf16 v[56:59], v[160:163], v[184:187], 0
	v_mfma_f32_16x16x32_bf16 v[52:55], v[152:155], v[192:195], 0
	v_mfma_f32_16x16x32_bf16 v[44:47], v[160:163], v[192:195], 0
	v_mfma_f32_16x16x32_bf16 v[36:39], v[152:155], v[200:203], 0
	v_mfma_f32_16x16x32_bf16 v[28:31], v[160:163], v[200:203], 0
	v_mfma_f32_16x16x32_bf16 v[20:23], v[152:155], v[208:211], 0
	v_mfma_f32_16x16x32_bf16 v[12:15], v[160:163], v[208:211], 0
	v_mfma_f32_16x16x32_bf16 v[60:63], v[156:159], v[188:191], v[60:63]
	v_mfma_f32_16x16x32_bf16 v[56:59], v[164:167], v[188:191], v[56:59]
	v_mfma_f32_16x16x32_bf16 v[52:55], v[156:159], v[196:199], v[52:55]
	v_mfma_f32_16x16x32_bf16 v[44:47], v[164:167], v[196:199], v[44:47]
	v_mfma_f32_16x16x32_bf16 v[36:39], v[156:159], v[204:207], v[36:39]
	v_mfma_f32_16x16x32_bf16 v[28:31], v[164:167], v[204:207], v[28:31]
	v_mfma_f32_16x16x32_bf16 v[20:23], v[156:159], v[212:215], v[20:23]
	v_mfma_f32_16x16x32_bf16 v[12:15], v[164:167], v[212:215], v[12:15]
	s_setprio 0
	s_setprio 1
	v_mfma_f32_16x16x32_bf16 v[48:51], v[168:171], v[184:187], 0
	v_mfma_f32_16x16x32_bf16 v[40:43], v[176:179], v[184:187], 0
	v_mfma_f32_16x16x32_bf16 v[32:35], v[168:171], v[192:195], 0
	v_mfma_f32_16x16x32_bf16 v[24:27], v[176:179], v[192:195], 0
	v_mfma_f32_16x16x32_bf16 v[16:19], v[168:171], v[200:203], 0
	v_mfma_f32_16x16x32_bf16 v[8:11], v[176:179], v[200:203], 0
	v_mfma_f32_16x16x32_bf16 v[4:7], v[168:171], v[208:211], 0
	v_mfma_f32_16x16x32_bf16 v[0:3], v[176:179], v[208:211], 0
	v_mfma_f32_16x16x32_bf16 v[48:51], v[172:175], v[188:191], v[48:51]
	v_mfma_f32_16x16x32_bf16 v[40:43], v[180:183], v[188:191], v[40:43]
	v_mfma_f32_16x16x32_bf16 v[32:35], v[172:175], v[196:199], v[32:35]
	v_mfma_f32_16x16x32_bf16 v[24:27], v[180:183], v[196:199], v[24:27]
	v_mfma_f32_16x16x32_bf16 v[16:19], v[172:175], v[204:207], v[16:19]
	v_mfma_f32_16x16x32_bf16 v[8:11], v[180:183], v[204:207], v[8:11]
	v_mfma_f32_16x16x32_bf16 v[4:7], v[172:175], v[212:215], v[4:7]
	v_mfma_f32_16x16x32_bf16 v[0:3], v[180:183], v[212:215], v[0:3]
	s_setprio 0
	s_barrier
	s_add_i32 s58, 0, 0x18000
	s_add_i32 s59, 0, 0x1c000
	v_add_u32_e32 v164, s58, v148
	v_add_u32_e32 v180, s59, v148
	ds_read_b128 v[152:155], v164
	ds_read_b128 v[156:159], v164 offset:1024
	ds_read_b128 v[160:163], v164 offset:2048
	ds_read_b128 v[164:167], v164 offset:3072
	ds_read_b128 v[168:171], v180
	ds_read_b128 v[172:175], v180 offset:1024
	ds_read_b128 v[176:179], v180 offset:2048
	ds_read_b128 v[180:183], v180 offset:3072
	s_add_u32 s28, s28, 0x40000
	s_addc_u32 s29, s29, 0
	s_mov_b32 m0, s36
	ds_read_b128 v[184:187], v151 offset:32768
	ds_read_b128 v[188:191], v151 offset:33792
	ds_read_b128 v[192:195], v151 offset:34816
	ds_read_b128 v[196:199], v151 offset:35840
	ds_read_b128 v[200:203], v151 offset:36864
	ds_read_b128 v[204:207], v151 offset:37888
	ds_read_b128 v[208:211], v151 offset:38912
	ds_read_b128 v[212:215], v151 offset:39936
	global_load_lds_dwordx4 v128, s[28:29]
	s_mov_b32 m0, s37
	s_nop 0
	global_load_lds_dwordx4 v132, s[28:29]
	s_waitcnt vmcnt(8)
	s_waitcnt lgkmcnt(0)
	s_barrier
	s_setprio 1
	s_waitcnt lgkmcnt(0)
	v_mfma_f32_16x16x32_bf16 v[124:127], v[152:155], v[184:187], v[124:127]
	v_mfma_f32_16x16x32_bf16 v[120:123], v[160:163], v[184:187], v[120:123]
	v_mfma_f32_16x16x32_bf16 v[116:119], v[152:155], v[192:195], v[116:119]
	v_mfma_f32_16x16x32_bf16 v[108:111], v[160:163], v[192:195], v[108:111]
	v_mfma_f32_16x16x32_bf16 v[100:103], v[152:155], v[200:203], v[100:103]
	v_mfma_f32_16x16x32_bf16 v[92:95], v[160:163], v[200:203], v[92:95]
	v_mfma_f32_16x16x32_bf16 v[84:87], v[152:155], v[208:211], v[84:87]
	v_mfma_f32_16x16x32_bf16 v[76:79], v[160:163], v[208:211], v[76:79]
	v_mfma_f32_16x16x32_bf16 v[124:127], v[156:159], v[188:191], v[124:127]
	v_mfma_f32_16x16x32_bf16 v[120:123], v[164:167], v[188:191], v[120:123]
	v_mfma_f32_16x16x32_bf16 v[116:119], v[156:159], v[196:199], v[116:119]
	v_mfma_f32_16x16x32_bf16 v[108:111], v[164:167], v[196:199], v[108:111]
	v_mfma_f32_16x16x32_bf16 v[100:103], v[156:159], v[204:207], v[100:103]
	v_mfma_f32_16x16x32_bf16 v[92:95], v[164:167], v[204:207], v[92:95]
	v_mfma_f32_16x16x32_bf16 v[84:87], v[156:159], v[212:215], v[84:87]
	v_mfma_f32_16x16x32_bf16 v[76:79], v[164:167], v[212:215], v[76:79]
	s_setprio 0
	s_setprio 1
	v_mfma_f32_16x16x32_bf16 v[112:115], v[168:171], v[184:187], v[112:115]
	v_mfma_f32_16x16x32_bf16 v[104:107], v[176:179], v[184:187], v[104:107]
	v_mfma_f32_16x16x32_bf16 v[96:99], v[168:171], v[192:195], v[96:99]
	v_mfma_f32_16x16x32_bf16 v[88:91], v[176:179], v[192:195], v[88:91]
	v_mfma_f32_16x16x32_bf16 v[80:83], v[168:171], v[200:203], v[80:83]
	v_mfma_f32_16x16x32_bf16 v[72:75], v[176:179], v[200:203], v[72:75]
	v_mfma_f32_16x16x32_bf16 v[68:71], v[168:171], v[208:211], v[68:71]
	v_mfma_f32_16x16x32_bf16 v[64:67], v[176:179], v[208:211], v[64:67]
	v_mfma_f32_16x16x32_bf16 v[112:115], v[172:175], v[188:191], v[112:115]
	v_mfma_f32_16x16x32_bf16 v[104:107], v[180:183], v[188:191], v[104:107]
	v_mfma_f32_16x16x32_bf16 v[96:99], v[172:175], v[196:199], v[96:99]
	v_mfma_f32_16x16x32_bf16 v[88:91], v[180:183], v[196:199], v[88:91]
	v_mfma_f32_16x16x32_bf16 v[80:83], v[172:175], v[204:207], v[80:83]
	v_mfma_f32_16x16x32_bf16 v[72:75], v[180:183], v[204:207], v[72:75]
	v_mfma_f32_16x16x32_bf16 v[68:71], v[172:175], v[212:215], v[68:71]
	v_mfma_f32_16x16x32_bf16 v[64:67], v[180:183], v[212:215], v[64:67]
	s_setprio 0
	s_barrier
	s_add_i32 s28, s58, s31
	s_mov_b32 m0, s28
	ds_read_b128 v[184:187], v151 offset:49152
	ds_read_b128 v[188:191], v151 offset:50176
	ds_read_b128 v[192:195], v151 offset:51200
	ds_read_b128 v[196:199], v151 offset:52224
	ds_read_b128 v[200:203], v151 offset:53248
	ds_read_b128 v[204:207], v151 offset:54272
	ds_read_b128 v[208:211], v151 offset:55296
	ds_read_b128 v[212:215], v151 offset:56320
	global_load_lds_dwordx4 v130, s[62:63]
	s_add_i32 m0, s28, 0x2000
	s_add_u32 s26, s26, 0x40080
	s_addc_u32 s27, s27, 0
	s_add_i32 s28, s59, s31
	global_load_lds_dwordx4 v134, s[62:63]
	s_mov_b32 m0, s28
	s_nop 0
	global_load_lds_dwordx4 v130, s[26:27]
	s_add_i32 m0, s28, 0x2000
	s_nop 0
	global_load_lds_dwordx4 v134, s[26:27]
	s_mov_b32 m0, s40
	s_nop 0
	global_load_lds_dwordx4 v128, s[64:65]
	s_mov_b32 m0, s41
	s_nop 0
	global_load_lds_dwordx4 v132, s[64:65]
	s_waitcnt vmcnt(8)
	s_waitcnt lgkmcnt(0)
	s_barrier
	s_setprio 1
	s_waitcnt lgkmcnt(0)
	v_mfma_f32_16x16x32_bf16 v[60:63], v[152:155], v[184:187], v[60:63]
	v_mfma_f32_16x16x32_bf16 v[56:59], v[160:163], v[184:187], v[56:59]
	v_mfma_f32_16x16x32_bf16 v[52:55], v[152:155], v[192:195], v[52:55]
	v_mfma_f32_16x16x32_bf16 v[44:47], v[160:163], v[192:195], v[44:47]
	v_mfma_f32_16x16x32_bf16 v[36:39], v[152:155], v[200:203], v[36:39]
	v_mfma_f32_16x16x32_bf16 v[28:31], v[160:163], v[200:203], v[28:31]
	v_mfma_f32_16x16x32_bf16 v[20:23], v[152:155], v[208:211], v[20:23]
	v_mfma_f32_16x16x32_bf16 v[12:15], v[160:163], v[208:211], v[12:15]
	v_mfma_f32_16x16x32_bf16 v[60:63], v[156:159], v[188:191], v[60:63]
	v_mfma_f32_16x16x32_bf16 v[56:59], v[164:167], v[188:191], v[56:59]
	v_mfma_f32_16x16x32_bf16 v[52:55], v[156:159], v[196:199], v[52:55]
	v_mfma_f32_16x16x32_bf16 v[44:47], v[164:167], v[196:199], v[44:47]
	v_mfma_f32_16x16x32_bf16 v[36:39], v[156:159], v[204:207], v[36:39]
	v_mfma_f32_16x16x32_bf16 v[28:31], v[164:167], v[204:207], v[28:31]
	v_mfma_f32_16x16x32_bf16 v[20:23], v[156:159], v[212:215], v[20:23]
	v_mfma_f32_16x16x32_bf16 v[12:15], v[164:167], v[212:215], v[12:15]
	s_setprio 0
	s_setprio 1
	v_mfma_f32_16x16x32_bf16 v[48:51], v[168:171], v[184:187], v[48:51]
	v_mfma_f32_16x16x32_bf16 v[40:43], v[176:179], v[184:187], v[40:43]
	v_mfma_f32_16x16x32_bf16 v[32:35], v[168:171], v[192:195], v[32:35]
	v_mfma_f32_16x16x32_bf16 v[24:27], v[176:179], v[192:195], v[24:27]
	v_mfma_f32_16x16x32_bf16 v[16:19], v[168:171], v[200:203], v[16:19]
	v_mfma_f32_16x16x32_bf16 v[8:11], v[176:179], v[200:203], v[8:11]
	v_mfma_f32_16x16x32_bf16 v[4:7], v[168:171], v[208:211], v[4:7]
	v_mfma_f32_16x16x32_bf16 v[0:3], v[176:179], v[208:211], v[0:3]
	v_mfma_f32_16x16x32_bf16 v[48:51], v[172:175], v[188:191], v[48:51]
	v_mfma_f32_16x16x32_bf16 v[40:43], v[180:183], v[188:191], v[40:43]
	v_mfma_f32_16x16x32_bf16 v[32:35], v[172:175], v[196:199], v[32:35]
	v_mfma_f32_16x16x32_bf16 v[24:27], v[180:183], v[196:199], v[24:27]
	v_mfma_f32_16x16x32_bf16 v[16:19], v[172:175], v[204:207], v[16:19]
	v_mfma_f32_16x16x32_bf16 v[8:11], v[180:183], v[204:207], v[8:11]
	v_mfma_f32_16x16x32_bf16 v[4:7], v[172:175], v[212:215], v[4:7]
	v_mfma_f32_16x16x32_bf16 v[0:3], v[180:183], v[212:215], v[0:3]
	s_setprio 0
	s_barrier
	s_add_i32 s57, s57, 2
	s_add_u32 s24, s24, 0x100
	s_addc_u32 s25, s25, 0
	s_add_u32 s55, s55, 0x100
	s_addc_u32 s56, s56, 0
	s_cmp_gt_u32 s57, 13
.LBB3_20:
	ds_read_b128 v[152:155], v149
	ds_read_b128 v[156:159], v149 offset:1024
	ds_read_b128 v[160:163], v149 offset:2048
	ds_read_b128 v[164:167], v149 offset:3072
	ds_read_b128 v[168:171], v150
	ds_read_b128 v[172:175], v150 offset:1024
	ds_read_b128 v[176:179], v150 offset:2048
	ds_read_b128 v[180:183], v150 offset:3072
	s_add_u32 s26, s24, 0xfffc0080
	s_addc_u32 s27, s25, -1
	s_cmp_eq_u32 s57, 12
	s_cselect_b32 s29, s17, s27
	s_cselect_b32 s28, s53, s26
	s_cselect_b32 s27, s15, s56
	s_cselect_b32 s26, s54, s55
	s_add_i32 m0, s23, 0xc000
	ds_read_b128 v[184:187], v151
	ds_read_b128 v[188:191], v151 offset:1024
	ds_read_b128 v[192:195], v151 offset:2048
	ds_read_b128 v[196:199], v151 offset:3072
	ds_read_b128 v[200:203], v151 offset:4096
	ds_read_b128 v[204:207], v151 offset:5120
	ds_read_b128 v[208:211], v151 offset:6144
	ds_read_b128 v[212:215], v151 offset:7168
	global_load_lds_dwordx4 v138, s[24:25]
	s_add_i32 m0, s23, 0xe000
	s_nop 0
	global_load_lds_dwordx4 v140, s[24:25]
	s_waitcnt vmcnt(8)
	s_waitcnt lgkmcnt(0)
	s_barrier
	s_setprio 1
	s_waitcnt lgkmcnt(0)
	v_mfma_f32_16x16x32_bf16 v[124:127], v[152:155], v[184:187], v[124:127]
	v_mfma_f32_16x16x32_bf16 v[120:123], v[160:163], v[184:187], v[120:123]
	v_mfma_f32_16x16x32_bf16 v[116:119], v[152:155], v[192:195], v[116:119]
	v_mfma_f32_16x16x32_bf16 v[108:111], v[160:163], v[192:195], v[108:111]
	v_mfma_f32_16x16x32_bf16 v[100:103], v[152:155], v[200:203], v[100:103]
	v_mfma_f32_16x16x32_bf16 v[92:95], v[160:163], v[200:203], v[92:95]
	v_mfma_f32_16x16x32_bf16 v[84:87], v[152:155], v[208:211], v[84:87]
	v_mfma_f32_16x16x32_bf16 v[76:79], v[160:163], v[208:211], v[76:79]
	v_mfma_f32_16x16x32_bf16 v[124:127], v[156:159], v[188:191], v[124:127]
	v_mfma_f32_16x16x32_bf16 v[120:123], v[164:167], v[188:191], v[120:123]
	v_mfma_f32_16x16x32_bf16 v[116:119], v[156:159], v[196:199], v[116:119]
	v_mfma_f32_16x16x32_bf16 v[108:111], v[164:167], v[196:199], v[108:111]
	v_mfma_f32_16x16x32_bf16 v[100:103], v[156:159], v[204:207], v[100:103]
	v_mfma_f32_16x16x32_bf16 v[92:95], v[164:167], v[204:207], v[92:95]
	v_mfma_f32_16x16x32_bf16 v[84:87], v[156:159], v[212:215], v[84:87]
	v_mfma_f32_16x16x32_bf16 v[76:79], v[164:167], v[212:215], v[76:79]
	s_setprio 0
	s_setprio 1
	v_mfma_f32_16x16x32_bf16 v[112:115], v[168:171], v[184:187], v[112:115]
	v_mfma_f32_16x16x32_bf16 v[104:107], v[176:179], v[184:187], v[104:107]
	v_mfma_f32_16x16x32_bf16 v[96:99], v[168:171], v[192:195], v[96:99]
	v_mfma_f32_16x16x32_bf16 v[88:91], v[176:179], v[192:195], v[88:91]
	v_mfma_f32_16x16x32_bf16 v[80:83], v[168:171], v[200:203], v[80:83]
	v_mfma_f32_16x16x32_bf16 v[72:75], v[176:179], v[200:203], v[72:75]
	v_mfma_f32_16x16x32_bf16 v[68:71], v[168:171], v[208:211], v[68:71]
	v_mfma_f32_16x16x32_bf16 v[64:67], v[176:179], v[208:211], v[64:67]
	v_mfma_f32_16x16x32_bf16 v[112:115], v[172:175], v[188:191], v[112:115]
	v_mfma_f32_16x16x32_bf16 v[104:107], v[180:183], v[188:191], v[104:107]
	v_mfma_f32_16x16x32_bf16 v[96:99], v[172:175], v[196:199], v[96:99]
	v_mfma_f32_16x16x32_bf16 v[88:91], v[180:183], v[196:199], v[88:91]
	v_mfma_f32_16x16x32_bf16 v[80:83], v[172:175], v[204:207], v[80:83]
	v_mfma_f32_16x16x32_bf16 v[72:75], v[180:183], v[204:207], v[72:75]
	v_mfma_f32_16x16x32_bf16 v[68:71], v[172:175], v[212:215], v[68:71]
	v_mfma_f32_16x16x32_bf16 v[64:67], v[180:183], v[212:215], v[64:67]
	s_setprio 0
	s_barrier
	s_add_i32 s58, s45, s31
	s_add_u32 s62, s26, 0x80
	s_addc_u32 s63, s27, 0
	s_mov_b32 m0, s58
	ds_read_b128 v[184:187], v151 offset:16384
	ds_read_b128 v[188:191], v151 offset:17408
	ds_read_b128 v[192:195], v151 offset:18432
	ds_read_b128 v[196:199], v151 offset:19456
	ds_read_b128 v[200:203], v151 offset:20480
	ds_read_b128 v[204:207], v151 offset:21504
	ds_read_b128 v[208:211], v151 offset:22528
	ds_read_b128 v[212:215], v151 offset:23552
	global_load_lds_dwordx4 v130, s[26:27]
	s_add_i32 m0, s58, 0x2000
	s_add_u32 s58, s26, 0x40000
	s_addc_u32 s59, s27, 0
	s_add_i32 s60, s46, s31
	global_load_lds_dwordx4 v134, s[26:27]
	s_mov_b32 m0, s60
	s_add_u32 s64, s28, 0x80
	s_addc_u32 s65, s29, 0
	global_load_lds_dwordx4 v130, s[58:59]
	s_add_i32 m0, s60, 0x2000
	s_nop 0
	global_load_lds_dwordx4 v134, s[58:59]
	s_mov_b32 m0, s23
	s_nop 0
	global_load_lds_dwordx4 v128, s[28:29]
	s_mov_b32 m0, s35
	s_nop 0
	global_load_lds_dwordx4 v132, s[28:29]
	s_waitcnt vmcnt(8)
	s_waitcnt lgkmcnt(0)
	s_barrier
	s_setprio 1
	s_waitcnt lgkmcnt(0)
	v_mfma_f32_16x16x32_bf16 v[60:63], v[152:155], v[184:187], v[60:63]
	v_mfma_f32_16x16x32_bf16 v[56:59], v[160:163], v[184:187], v[56:59]
	v_mfma_f32_16x16x32_bf16 v[52:55], v[152:155], v[192:195], v[52:55]
	v_mfma_f32_16x16x32_bf16 v[44:47], v[160:163], v[192:195], v[44:47]
	v_mfma_f32_16x16x32_bf16 v[36:39], v[152:155], v[200:203], v[36:39]
	v_mfma_f32_16x16x32_bf16 v[28:31], v[160:163], v[200:203], v[28:31]
	v_mfma_f32_16x16x32_bf16 v[20:23], v[152:155], v[208:211], v[20:23]
	v_mfma_f32_16x16x32_bf16 v[12:15], v[160:163], v[208:211], v[12:15]
	v_mfma_f32_16x16x32_bf16 v[60:63], v[156:159], v[188:191], v[60:63]
	v_mfma_f32_16x16x32_bf16 v[56:59], v[164:167], v[188:191], v[56:59]
	v_mfma_f32_16x16x32_bf16 v[52:55], v[156:159], v[196:199], v[52:55]
	v_mfma_f32_16x16x32_bf16 v[44:47], v[164:167], v[196:199], v[44:47]
	v_mfma_f32_16x16x32_bf16 v[36:39], v[156:159], v[204:207], v[36:39]
	v_mfma_f32_16x16x32_bf16 v[28:31], v[164:167], v[204:207], v[28:31]
	v_mfma_f32_16x16x32_bf16 v[20:23], v[156:159], v[212:215], v[20:23]
	v_mfma_f32_16x16x32_bf16 v[12:15], v[164:167], v[212:215], v[12:15]
	s_setprio 0
	s_setprio 1
	v_mfma_f32_16x16x32_bf16 v[48:51], v[168:171], v[184:187], v[48:51]
	v_mfma_f32_16x16x32_bf16 v[40:43], v[176:179], v[184:187], v[40:43]
	v_mfma_f32_16x16x32_bf16 v[32:35], v[168:171], v[192:195], v[32:35]
	v_mfma_f32_16x16x32_bf16 v[24:27], v[176:179], v[192:195], v[24:27]
	v_mfma_f32_16x16x32_bf16 v[16:19], v[168:171], v[200:203], v[16:19]
	v_mfma_f32_16x16x32_bf16 v[8:11], v[176:179], v[200:203], v[8:11]
	v_mfma_f32_16x16x32_bf16 v[4:7], v[168:171], v[208:211], v[4:7]
	v_mfma_f32_16x16x32_bf16 v[0:3], v[176:179], v[208:211], v[0:3]
	v_mfma_f32_16x16x32_bf16 v[48:51], v[172:175], v[188:191], v[48:51]
	v_mfma_f32_16x16x32_bf16 v[40:43], v[180:183], v[188:191], v[40:43]
	v_mfma_f32_16x16x32_bf16 v[32:35], v[172:175], v[196:199], v[32:35]
	v_mfma_f32_16x16x32_bf16 v[24:27], v[180:183], v[196:199], v[24:27]
	v_mfma_f32_16x16x32_bf16 v[16:19], v[172:175], v[204:207], v[16:19]
	v_mfma_f32_16x16x32_bf16 v[8:11], v[180:183], v[204:207], v[8:11]
	v_mfma_f32_16x16x32_bf16 v[4:7], v[172:175], v[212:215], v[4:7]
	v_mfma_f32_16x16x32_bf16 v[0:3], v[180:183], v[212:215], v[0:3]
	s_setprio 0
	s_barrier
	s_add_i32 s58, 0, 0x18000
	s_add_i32 s59, 0, 0x1c000
	v_add_u32_e32 v164, s58, v148
	v_add_u32_e32 v180, s59, v148
	ds_read_b128 v[152:155], v164
	ds_read_b128 v[156:159], v164 offset:1024
	ds_read_b128 v[160:163], v164 offset:2048
	ds_read_b128 v[164:167], v164 offset:3072
	ds_read_b128 v[168:171], v180
	ds_read_b128 v[172:175], v180 offset:1024
	ds_read_b128 v[176:179], v180 offset:2048
	ds_read_b128 v[180:183], v180 offset:3072
	s_add_u32 s28, s28, 0x40000
	s_addc_u32 s29, s29, 0
	s_mov_b32 m0, s36
	ds_read_b128 v[184:187], v151 offset:32768
	ds_read_b128 v[188:191], v151 offset:33792
	ds_read_b128 v[192:195], v151 offset:34816
	ds_read_b128 v[196:199], v151 offset:35840
	ds_read_b128 v[200:203], v151 offset:36864
	ds_read_b128 v[204:207], v151 offset:37888
	ds_read_b128 v[208:211], v151 offset:38912
	ds_read_b128 v[212:215], v151 offset:39936
	global_load_lds_dwordx4 v128, s[28:29]
	s_mov_b32 m0, s37
	s_nop 0
	global_load_lds_dwordx4 v132, s[28:29]
	s_waitcnt vmcnt(8)
	s_waitcnt lgkmcnt(0)
	s_barrier
	s_setprio 1
	s_waitcnt lgkmcnt(0)
	v_mfma_f32_16x16x32_bf16 v[124:127], v[152:155], v[184:187], v[124:127]
	v_mfma_f32_16x16x32_bf16 v[120:123], v[160:163], v[184:187], v[120:123]
	v_mfma_f32_16x16x32_bf16 v[116:119], v[152:155], v[192:195], v[116:119]
	v_mfma_f32_16x16x32_bf16 v[108:111], v[160:163], v[192:195], v[108:111]
	v_mfma_f32_16x16x32_bf16 v[100:103], v[152:155], v[200:203], v[100:103]
	v_mfma_f32_16x16x32_bf16 v[92:95], v[160:163], v[200:203], v[92:95]
	v_mfma_f32_16x16x32_bf16 v[84:87], v[152:155], v[208:211], v[84:87]
	v_mfma_f32_16x16x32_bf16 v[76:79], v[160:163], v[208:211], v[76:79]
	v_mfma_f32_16x16x32_bf16 v[124:127], v[156:159], v[188:191], v[124:127]
	v_mfma_f32_16x16x32_bf16 v[120:123], v[164:167], v[188:191], v[120:123]
	v_mfma_f32_16x16x32_bf16 v[116:119], v[156:159], v[196:199], v[116:119]
	v_mfma_f32_16x16x32_bf16 v[108:111], v[164:167], v[196:199], v[108:111]
	v_mfma_f32_16x16x32_bf16 v[100:103], v[156:159], v[204:207], v[100:103]
	v_mfma_f32_16x16x32_bf16 v[92:95], v[164:167], v[204:207], v[92:95]
	v_mfma_f32_16x16x32_bf16 v[84:87], v[156:159], v[212:215], v[84:87]
	v_mfma_f32_16x16x32_bf16 v[76:79], v[164:167], v[212:215], v[76:79]
	s_setprio 0
	s_setprio 1
	v_mfma_f32_16x16x32_bf16 v[112:115], v[168:171], v[184:187], v[112:115]
	v_mfma_f32_16x16x32_bf16 v[104:107], v[176:179], v[184:187], v[104:107]
	v_mfma_f32_16x16x32_bf16 v[96:99], v[168:171], v[192:195], v[96:99]
	v_mfma_f32_16x16x32_bf16 v[88:91], v[176:179], v[192:195], v[88:91]
	v_mfma_f32_16x16x32_bf16 v[80:83], v[168:171], v[200:203], v[80:83]
	v_mfma_f32_16x16x32_bf16 v[72:75], v[176:179], v[200:203], v[72:75]
	v_mfma_f32_16x16x32_bf16 v[68:71], v[168:171], v[208:211], v[68:71]
	v_mfma_f32_16x16x32_bf16 v[64:67], v[176:179], v[208:211], v[64:67]
	v_mfma_f32_16x16x32_bf16 v[112:115], v[172:175], v[188:191], v[112:115]
	v_mfma_f32_16x16x32_bf16 v[104:107], v[180:183], v[188:191], v[104:107]
	v_mfma_f32_16x16x32_bf16 v[96:99], v[172:175], v[196:199], v[96:99]
	v_mfma_f32_16x16x32_bf16 v[88:91], v[180:183], v[196:199], v[88:91]
	v_mfma_f32_16x16x32_bf16 v[80:83], v[172:175], v[204:207], v[80:83]
	v_mfma_f32_16x16x32_bf16 v[72:75], v[180:183], v[204:207], v[72:75]
	v_mfma_f32_16x16x32_bf16 v[68:71], v[172:175], v[212:215], v[68:71]
	v_mfma_f32_16x16x32_bf16 v[64:67], v[180:183], v[212:215], v[64:67]
	s_setprio 0
	s_barrier
	s_add_i32 s28, s58, s31
	s_mov_b32 m0, s28
	ds_read_b128 v[184:187], v151 offset:49152
	ds_read_b128 v[188:191], v151 offset:50176
	ds_read_b128 v[192:195], v151 offset:51200
	ds_read_b128 v[196:199], v151 offset:52224
	ds_read_b128 v[200:203], v151 offset:53248
	ds_read_b128 v[204:207], v151 offset:54272
	ds_read_b128 v[208:211], v151 offset:55296
	ds_read_b128 v[212:215], v151 offset:56320
	global_load_lds_dwordx4 v130, s[62:63]
	s_add_i32 m0, s28, 0x2000
	s_add_u32 s26, s26, 0x40080
	s_addc_u32 s27, s27, 0
	s_add_i32 s28, s59, s31
	global_load_lds_dwordx4 v134, s[62:63]
	s_mov_b32 m0, s28
	s_nop 0
	global_load_lds_dwordx4 v130, s[26:27]
	s_add_i32 m0, s28, 0x2000
	s_nop 0
	global_load_lds_dwordx4 v134, s[26:27]
	s_mov_b32 m0, s40
	s_nop 0
	global_load_lds_dwordx4 v128, s[64:65]
	s_mov_b32 m0, s41
	s_nop 0
	global_load_lds_dwordx4 v132, s[64:65]
	s_waitcnt vmcnt(8)
	s_waitcnt lgkmcnt(0)
	s_barrier
	s_setprio 1
	s_waitcnt lgkmcnt(0)
	v_mfma_f32_16x16x32_bf16 v[60:63], v[152:155], v[184:187], v[60:63]
	v_mfma_f32_16x16x32_bf16 v[56:59], v[160:163], v[184:187], v[56:59]
	v_mfma_f32_16x16x32_bf16 v[52:55], v[152:155], v[192:195], v[52:55]
	v_mfma_f32_16x16x32_bf16 v[44:47], v[160:163], v[192:195], v[44:47]
	v_mfma_f32_16x16x32_bf16 v[36:39], v[152:155], v[200:203], v[36:39]
	v_mfma_f32_16x16x32_bf16 v[28:31], v[160:163], v[200:203], v[28:31]
	v_mfma_f32_16x16x32_bf16 v[20:23], v[152:155], v[208:211], v[20:23]
	v_mfma_f32_16x16x32_bf16 v[12:15], v[160:163], v[208:211], v[12:15]
	v_mfma_f32_16x16x32_bf16 v[60:63], v[156:159], v[188:191], v[60:63]
	v_mfma_f32_16x16x32_bf16 v[56:59], v[164:167], v[188:191], v[56:59]
	v_mfma_f32_16x16x32_bf16 v[52:55], v[156:159], v[196:199], v[52:55]
	v_mfma_f32_16x16x32_bf16 v[44:47], v[164:167], v[196:199], v[44:47]
	v_mfma_f32_16x16x32_bf16 v[36:39], v[156:159], v[204:207], v[36:39]
	v_mfma_f32_16x16x32_bf16 v[28:31], v[164:167], v[204:207], v[28:31]
	v_mfma_f32_16x16x32_bf16 v[20:23], v[156:159], v[212:215], v[20:23]
	v_mfma_f32_16x16x32_bf16 v[12:15], v[164:167], v[212:215], v[12:15]
	s_setprio 0
	s_setprio 1
	v_mfma_f32_16x16x32_bf16 v[48:51], v[168:171], v[184:187], v[48:51]
	v_mfma_f32_16x16x32_bf16 v[40:43], v[176:179], v[184:187], v[40:43]
	v_mfma_f32_16x16x32_bf16 v[32:35], v[168:171], v[192:195], v[32:35]
	v_mfma_f32_16x16x32_bf16 v[24:27], v[176:179], v[192:195], v[24:27]
	v_mfma_f32_16x16x32_bf16 v[16:19], v[168:171], v[200:203], v[16:19]
	v_mfma_f32_16x16x32_bf16 v[8:11], v[176:179], v[200:203], v[8:11]
	v_mfma_f32_16x16x32_bf16 v[4:7], v[168:171], v[208:211], v[4:7]
	v_mfma_f32_16x16x32_bf16 v[0:3], v[176:179], v[208:211], v[0:3]
	v_mfma_f32_16x16x32_bf16 v[48:51], v[172:175], v[188:191], v[48:51]
	v_mfma_f32_16x16x32_bf16 v[40:43], v[180:183], v[188:191], v[40:43]
	v_mfma_f32_16x16x32_bf16 v[32:35], v[172:175], v[196:199], v[32:35]
	v_mfma_f32_16x16x32_bf16 v[24:27], v[180:183], v[196:199], v[24:27]
	v_mfma_f32_16x16x32_bf16 v[16:19], v[172:175], v[204:207], v[16:19]
	v_mfma_f32_16x16x32_bf16 v[8:11], v[180:183], v[204:207], v[8:11]
	v_mfma_f32_16x16x32_bf16 v[4:7], v[172:175], v[212:215], v[4:7]
	v_mfma_f32_16x16x32_bf16 v[0:3], v[180:183], v[212:215], v[0:3]
	s_setprio 0
	s_barrier
	s_add_i32 s57, s57, 2
	s_add_u32 s24, s24, 0x100
	s_addc_u32 s25, s25, 0
	s_add_u32 s55, s55, 0x100
	s_addc_u32 s56, s56, 0
	s_cmp_gt_u32 s57, 13
	s_cbranch_scc0 .LBB3_20
	s_mov_b64 vcc, s[0:1]
	s_cbranch_vccz .LBB3_23
	s_barrier

	.amdhsa_kernel _Z10fwd_kernelILi3ELi4EEv4Args
		.amdhsa_group_segment_fixed_size 0
		.amdhsa_private_segment_fixed_size 0
		.amdhsa_kernarg_size 488
		.amdhsa_user_sgpr_count 2
		.amdhsa_user_sgpr_dispatch_ptr 0
		.amdhsa_user_sgpr_queue_ptr 0
		.amdhsa_user_sgpr_kernarg_segment_ptr 1
		.amdhsa_user_sgpr_dispatch_id 0
		.amdhsa_user_sgpr_kernarg_preload_length 0
		.amdhsa_user_sgpr_kernarg_preload_offset 0
		.amdhsa_user_sgpr_private_segment_size 0
		.amdhsa_uses_dynamic_stack 0
		.amdhsa_enable_private_segment 0
		.amdhsa_system_sgpr_workgroup_id_x 1
		.amdhsa_system_sgpr_workgroup_id_y 0
		.amdhsa_system_sgpr_workgroup_id_z 0
		.amdhsa_system_sgpr_workgroup_info 0
		.amdhsa_system_vgpr_workitem_id 0
		.amdhsa_next_free_vgpr 240
		.amdhsa_next_free_sgpr 70
		.amdhsa_accum_offset 240
		.amdhsa_reserve_vcc 1
		.amdhsa_float_round_mode_32 0
		.amdhsa_float_round_mode_16_64 0
		.amdhsa_float_denorm_mode_32 3
		.amdhsa_float_denorm_mode_16_64 3
		.amdhsa_dx10_clamp 1
		.amdhsa_ieee_mode 1
		.amdhsa_fp16_overflow 0
		.amdhsa_tg_split 0
		.amdhsa_exception_fp_ieee_invalid_op 0
		.amdhsa_exception_fp_denorm_src 0
		.amdhsa_exception_fp_ieee_div_zero 0
		.amdhsa_exception_fp_ieee_overflow 0
		.amdhsa_exception_fp_ieee_underflow 0
		.amdhsa_exception_fp_ieee_inexact 0
		.amdhsa_exception_int_div_zero 0
	.end_amdhsa_kernel

.LBB5_8:
	s_ashr_i32 s15, s14, 31
	s_lshl_b64 s[16:17], s[14:15], 19
	s_add_u32 s16, s28, s16
	v_cmp_lt_i64_e64 s[4:5], s[4:5], v[142:143]
	s_addc_u32 s17, s29, s17
	s_and_b64 s[18:19], s[4:5], exec
	s_cselect_b32 s15, s17, s23
	s_cselect_b32 s54, s16, s22
	s_ashr_i32 s13, s12, 31
	s_lshl_b64 s[18:19], s[12:13], 19
	s_add_u32 s18, s30, s18
	s_addc_u32 s19, s31, s19
	s_and_b64 s[26:27], s[4:5], exec
	s_cselect_b32 s13, s19, s25
	s_cselect_b32 s55, s18, s24
	s_add_u32 s22, s22, 0x40080
	s_addc_u32 s23, s23, 0
	s_add_u32 s56, s24, 0x100
	s_addc_u32 s57, s25, 0
	s_mov_b32 s58, -2
	ds_read_b128 v[152:155], v149
	ds_read_b128 v[156:159], v149 offset:1024
	ds_read_b128 v[160:163], v149 offset:2048
	ds_read_b128 v[164:167], v149 offset:3072
	ds_read_b128 v[168:171], v150
	ds_read_b128 v[172:175], v150 offset:1024
	ds_read_b128 v[176:179], v150 offset:2048
	ds_read_b128 v[180:183], v150 offset:3072
	s_add_u32 s24, s22, 0xfffc0080
	s_addc_u32 s25, s23, -1
	s_cmp_eq_u32 s58, 12
	s_cselect_b32 s27, s15, s25
	s_cselect_b32 s26, s54, s24
	s_cselect_b32 s25, s13, s57
	s_cselect_b32 s24, s55, s56
	s_add_i32 m0, s21, 0xc000
	ds_read_b128 v[184:187], v151
	ds_read_b128 v[188:191], v151 offset:1024
	ds_read_b128 v[192:195], v151 offset:2048
	ds_read_b128 v[196:199], v151 offset:3072
	ds_read_b128 v[200:203], v151 offset:4096
	ds_read_b128 v[204:207], v151 offset:5120
	ds_read_b128 v[208:211], v151 offset:6144
	ds_read_b128 v[212:215], v151 offset:7168
	global_load_lds_dwordx4 v138, s[22:23]
	s_add_i32 m0, s21, 0xe000
	s_nop 0
	global_load_lds_dwordx4 v140, s[22:23]
	s_waitcnt vmcnt(8)
	s_waitcnt lgkmcnt(0)
	s_barrier
	s_setprio 1
	s_waitcnt lgkmcnt(0)
	v_mfma_f32_16x16x32_bf16 v[124:127], v[152:155], v[184:187], 0
	v_mfma_f32_16x16x32_bf16 v[120:123], v[160:163], v[184:187], 0
	v_mfma_f32_16x16x32_bf16 v[108:111], v[152:155], v[192:195], 0
	v_mfma_f32_16x16x32_bf16 v[104:107], v[160:163], v[192:195], 0
	v_mfma_f32_16x16x32_bf16 v[92:95], v[152:155], v[200:203], 0
	v_mfma_f32_16x16x32_bf16 v[88:91], v[160:163], v[200:203], 0
	v_mfma_f32_16x16x32_bf16 v[76:79], v[152:155], v[208:211], 0
	v_mfma_f32_16x16x32_bf16 v[72:75], v[160:163], v[208:211], 0
	v_mfma_f32_16x16x32_bf16 v[124:127], v[156:159], v[188:191], v[124:127]
	v_mfma_f32_16x16x32_bf16 v[120:123], v[164:167], v[188:191], v[120:123]
	v_mfma_f32_16x16x32_bf16 v[108:111], v[156:159], v[196:199], v[108:111]
	v_mfma_f32_16x16x32_bf16 v[104:107], v[164:167], v[196:199], v[104:107]
	v_mfma_f32_16x16x32_bf16 v[92:95], v[156:159], v[204:207], v[92:95]
	v_mfma_f32_16x16x32_bf16 v[88:91], v[164:167], v[204:207], v[88:91]
	v_mfma_f32_16x16x32_bf16 v[76:79], v[156:159], v[212:215], v[76:79]
	v_mfma_f32_16x16x32_bf16 v[72:75], v[164:167], v[212:215], v[72:75]
	s_setprio 0
	s_setprio 1
	v_mfma_f32_16x16x32_bf16 v[116:119], v[168:171], v[184:187], 0
	v_mfma_f32_16x16x32_bf16 v[112:115], v[176:179], v[184:187], 0
	v_mfma_f32_16x16x32_bf16 v[100:103], v[168:171], v[192:195], 0
	v_mfma_f32_16x16x32_bf16 v[96:99], v[176:179], v[192:195], 0
	v_mfma_f32_16x16x32_bf16 v[84:87], v[168:171], v[200:203], 0
	v_mfma_f32_16x16x32_bf16 v[80:83], v[176:179], v[200:203], 0
	v_mfma_f32_16x16x32_bf16 v[68:71], v[168:171], v[208:211], 0
	v_mfma_f32_16x16x32_bf16 v[64:67], v[176:179], v[208:211], 0
	v_mfma_f32_16x16x32_bf16 v[116:119], v[172:175], v[188:191], v[116:119]
	v_mfma_f32_16x16x32_bf16 v[112:115], v[180:183], v[188:191], v[112:115]
	v_mfma_f32_16x16x32_bf16 v[100:103], v[172:175], v[196:199], v[100:103]
	v_mfma_f32_16x16x32_bf16 v[96:99], v[180:183], v[196:199], v[96:99]
	v_mfma_f32_16x16x32_bf16 v[84:87], v[172:175], v[204:207], v[84:87]
	v_mfma_f32_16x16x32_bf16 v[80:83], v[180:183], v[204:207], v[80:83]
	v_mfma_f32_16x16x32_bf16 v[68:71], v[172:175], v[212:215], v[68:71]
	v_mfma_f32_16x16x32_bf16 v[64:67], v[180:183], v[212:215], v[64:67]
	s_setprio 0
	s_barrier
	s_add_i32 s59, s43, s33
	s_add_u32 s62, s24, 0x80
	s_addc_u32 s63, s25, 0
	s_mov_b32 m0, s59
	ds_read_b128 v[184:187], v151 offset:16384
	ds_read_b128 v[188:191], v151 offset:17408
	ds_read_b128 v[192:195], v151 offset:18432
	ds_read_b128 v[196:199], v151 offset:19456
	ds_read_b128 v[200:203], v151 offset:20480
	ds_read_b128 v[204:207], v151 offset:21504
	ds_read_b128 v[208:211], v151 offset:22528
	ds_read_b128 v[212:215], v151 offset:23552
	global_load_lds_dwordx4 v132, s[24:25]
	s_add_i32 m0, s59, 0x2000
	s_add_u32 s60, s24, 0x40000
	s_addc_u32 s61, s25, 0
	s_add_i32 s59, s44, s33
	global_load_lds_dwordx4 v128, s[24:25]
	s_mov_b32 m0, s59
	s_add_u32 s64, s26, 0x80
	s_addc_u32 s65, s27, 0
	global_load_lds_dwordx4 v132, s[60:61]
	s_add_i32 m0, s59, 0x2000
	s_nop 0
	global_load_lds_dwordx4 v128, s[60:61]
	s_mov_b32 m0, s21
	s_nop 0
	global_load_lds_dwordx4 v134, s[26:27]
	s_mov_b32 m0, s36
	s_nop 0
	global_load_lds_dwordx4 v130, s[26:27]
	s_waitcnt vmcnt(8)
	s_waitcnt lgkmcnt(0)
	s_barrier
	s_setprio 1
	s_waitcnt lgkmcnt(0)
	v_mfma_f32_16x16x32_bf16 v[60:63], v[152:155], v[184:187], 0
	v_mfma_f32_16x16x32_bf16 v[56:59], v[160:163], v[184:187], 0
	v_mfma_f32_16x16x32_bf16 v[44:47], v[152:155], v[192:195], 0
	v_mfma_f32_16x16x32_bf16 v[40:43], v[160:163], v[192:195], 0
	v_mfma_f32_16x16x32_bf16 v[28:31], v[152:155], v[200:203], 0
	v_mfma_f32_16x16x32_bf16 v[24:27], v[160:163], v[200:203], 0
	v_mfma_f32_16x16x32_bf16 v[12:15], v[152:155], v[208:211], 0
	v_mfma_f32_16x16x32_bf16 v[8:11], v[160:163], v[208:211], 0
	v_mfma_f32_16x16x32_bf16 v[60:63], v[156:159], v[188:191], v[60:63]
	v_mfma_f32_16x16x32_bf16 v[56:59], v[164:167], v[188:191], v[56:59]
	v_mfma_f32_16x16x32_bf16 v[44:47], v[156:159], v[196:199], v[44:47]
	v_mfma_f32_16x16x32_bf16 v[40:43], v[164:167], v[196:199], v[40:43]
	v_mfma_f32_16x16x32_bf16 v[28:31], v[156:159], v[204:207], v[28:31]
	v_mfma_f32_16x16x32_bf16 v[24:27], v[164:167], v[204:207], v[24:27]
	v_mfma_f32_16x16x32_bf16 v[12:15], v[156:159], v[212:215], v[12:15]
	v_mfma_f32_16x16x32_bf16 v[8:11], v[164:167], v[212:215], v[8:11]
	s_setprio 0
	s_setprio 1
	v_mfma_f32_16x16x32_bf16 v[52:55], v[168:171], v[184:187], 0
	v_mfma_f32_16x16x32_bf16 v[48:51], v[176:179], v[184:187], 0
	v_mfma_f32_16x16x32_bf16 v[36:39], v[168:171], v[192:195], 0
	v_mfma_f32_16x16x32_bf16 v[32:35], v[176:179], v[192:195], 0
	v_mfma_f32_16x16x32_bf16 v[20:23], v[168:171], v[200:203], 0
	v_mfma_f32_16x16x32_bf16 v[16:19], v[176:179], v[200:203], 0
	v_mfma_f32_16x16x32_bf16 v[4:7], v[168:171], v[208:211], 0
	v_mfma_f32_16x16x32_bf16 v[0:3], v[176:179], v[208:211], 0
	v_mfma_f32_16x16x32_bf16 v[52:55], v[172:175], v[188:191], v[52:55]
	v_mfma_f32_16x16x32_bf16 v[48:51], v[180:183], v[188:191], v[48:51]
	v_mfma_f32_16x16x32_bf16 v[36:39], v[172:175], v[196:199], v[36:39]
	v_mfma_f32_16x16x32_bf16 v[32:35], v[180:183], v[196:199], v[32:35]
	v_mfma_f32_16x16x32_bf16 v[20:23], v[172:175], v[204:207], v[20:23]
	v_mfma_f32_16x16x32_bf16 v[16:19], v[180:183], v[204:207], v[16:19]
	v_mfma_f32_16x16x32_bf16 v[4:7], v[172:175], v[212:215], v[4:7]
	v_mfma_f32_16x16x32_bf16 v[0:3], v[180:183], v[212:215], v[0:3]
	s_setprio 0
	s_barrier
	s_add_i32 s59, 0, 0x18000
	s_add_i32 s60, 0, 0x1c000
	v_add_u32_e32 v164, s59, v148
	v_add_u32_e32 v180, s60, v148
	ds_read_b128 v[152:155], v164
	ds_read_b128 v[156:159], v164 offset:1024
	ds_read_b128 v[160:163], v164 offset:2048
	ds_read_b128 v[164:167], v164 offset:3072
	ds_read_b128 v[168:171], v180
	ds_read_b128 v[172:175], v180 offset:1024
	ds_read_b128 v[176:179], v180 offset:2048
	ds_read_b128 v[180:183], v180 offset:3072
	s_add_u32 s26, s26, 0x40000
	s_addc_u32 s27, s27, 0
	s_mov_b32 m0, s37
	ds_read_b128 v[184:187], v151 offset:32768
	ds_read_b128 v[188:191], v151 offset:33792
	ds_read_b128 v[192:195], v151 offset:34816
	ds_read_b128 v[196:199], v151 offset:35840
	ds_read_b128 v[200:203], v151 offset:36864
	ds_read_b128 v[204:207], v151 offset:37888
	ds_read_b128 v[208:211], v151 offset:38912
	ds_read_b128 v[212:215], v151 offset:39936
	global_load_lds_dwordx4 v134, s[26:27]
	s_mov_b32 m0, s38
	s_nop 0
	global_load_lds_dwordx4 v130, s[26:27]
	s_waitcnt vmcnt(8)
	s_waitcnt lgkmcnt(0)
	s_barrier
	s_setprio 1
	s_waitcnt lgkmcnt(0)
	v_mfma_f32_16x16x32_bf16 v[124:127], v[152:155], v[184:187], v[124:127]
	v_mfma_f32_16x16x32_bf16 v[120:123], v[160:163], v[184:187], v[120:123]
	v_mfma_f32_16x16x32_bf16 v[108:111], v[152:155], v[192:195], v[108:111]
	v_mfma_f32_16x16x32_bf16 v[104:107], v[160:163], v[192:195], v[104:107]
	v_mfma_f32_16x16x32_bf16 v[92:95], v[152:155], v[200:203], v[92:95]
	v_mfma_f32_16x16x32_bf16 v[88:91], v[160:163], v[200:203], v[88:91]
	v_mfma_f32_16x16x32_bf16 v[76:79], v[152:155], v[208:211], v[76:79]
	v_mfma_f32_16x16x32_bf16 v[72:75], v[160:163], v[208:211], v[72:75]
	v_mfma_f32_16x16x32_bf16 v[124:127], v[156:159], v[188:191], v[124:127]
	v_mfma_f32_16x16x32_bf16 v[120:123], v[164:167], v[188:191], v[120:123]
	v_mfma_f32_16x16x32_bf16 v[108:111], v[156:159], v[196:199], v[108:111]
	v_mfma_f32_16x16x32_bf16 v[104:107], v[164:167], v[196:199], v[104:107]
	v_mfma_f32_16x16x32_bf16 v[92:95], v[156:159], v[204:207], v[92:95]
	v_mfma_f32_16x16x32_bf16 v[88:91], v[164:167], v[204:207], v[88:91]
	v_mfma_f32_16x16x32_bf16 v[76:79], v[156:159], v[212:215], v[76:79]
	v_mfma_f32_16x16x32_bf16 v[72:75], v[164:167], v[212:215], v[72:75]
	s_setprio 0
	s_setprio 1
	v_mfma_f32_16x16x32_bf16 v[116:119], v[168:171], v[184:187], v[116:119]
	v_mfma_f32_16x16x32_bf16 v[112:115], v[176:179], v[184:187], v[112:115]
	v_mfma_f32_16x16x32_bf16 v[100:103], v[168:171], v[192:195], v[100:103]
	v_mfma_f32_16x16x32_bf16 v[96:99], v[176:179], v[192:195], v[96:99]
	v_mfma_f32_16x16x32_bf16 v[84:87], v[168:171], v[200:203], v[84:87]
	v_mfma_f32_16x16x32_bf16 v[80:83], v[176:179], v[200:203], v[80:83]
	v_mfma_f32_16x16x32_bf16 v[68:71], v[168:171], v[208:211], v[68:71]
	v_mfma_f32_16x16x32_bf16 v[64:67], v[176:179], v[208:211], v[64:67]
	v_mfma_f32_16x16x32_bf16 v[116:119], v[172:175], v[188:191], v[116:119]
	v_mfma_f32_16x16x32_bf16 v[112:115], v[180:183], v[188:191], v[112:115]
	v_mfma_f32_16x16x32_bf16 v[100:103], v[172:175], v[196:199], v[100:103]
	v_mfma_f32_16x16x32_bf16 v[96:99], v[180:183], v[196:199], v[96:99]
	v_mfma_f32_16x16x32_bf16 v[84:87], v[172:175], v[204:207], v[84:87]
	v_mfma_f32_16x16x32_bf16 v[80:83], v[180:183], v[204:207], v[80:83]
	v_mfma_f32_16x16x32_bf16 v[68:71], v[172:175], v[212:215], v[68:71]
	v_mfma_f32_16x16x32_bf16 v[64:67], v[180:183], v[212:215], v[64:67]
	s_setprio 0
	s_barrier
	s_add_i32 s26, s59, s33
	s_mov_b32 m0, s26
	ds_read_b128 v[184:187], v151 offset:49152
	ds_read_b128 v[188:191], v151 offset:50176
	ds_read_b128 v[192:195], v151 offset:51200
	ds_read_b128 v[196:199], v151 offset:52224
	ds_read_b128 v[200:203], v151 offset:53248
	ds_read_b128 v[204:207], v151 offset:54272
	ds_read_b128 v[208:211], v151 offset:55296
	ds_read_b128 v[212:215], v151 offset:56320
	global_load_lds_dwordx4 v132, s[62:63]
	s_add_i32 m0, s26, 0x2000
	s_add_u32 s24, s24, 0x40080
	s_addc_u32 s25, s25, 0
	s_add_i32 s26, s60, s33
	global_load_lds_dwordx4 v128, s[62:63]
	s_mov_b32 m0, s26
	s_nop 0
	global_load_lds_dwordx4 v132, s[24:25]
	s_add_i32 m0, s26, 0x2000
	s_nop 0
	global_load_lds_dwordx4 v128, s[24:25]
	s_mov_b32 m0, s40
	s_nop 0
	global_load_lds_dwordx4 v134, s[64:65]
	s_mov_b32 m0, s41
	s_nop 0
	global_load_lds_dwordx4 v130, s[64:65]
	s_waitcnt vmcnt(8)
	s_waitcnt lgkmcnt(0)
	s_barrier
	s_setprio 1
	s_waitcnt lgkmcnt(0)
	v_mfma_f32_16x16x32_bf16 v[60:63], v[152:155], v[184:187], v[60:63]
	v_mfma_f32_16x16x32_bf16 v[56:59], v[160:163], v[184:187], v[56:59]
	v_mfma_f32_16x16x32_bf16 v[44:47], v[152:155], v[192:195], v[44:47]
	v_mfma_f32_16x16x32_bf16 v[40:43], v[160:163], v[192:195], v[40:43]
	v_mfma_f32_16x16x32_bf16 v[28:31], v[152:155], v[200:203], v[28:31]
	v_mfma_f32_16x16x32_bf16 v[24:27], v[160:163], v[200:203], v[24:27]
	v_mfma_f32_16x16x32_bf16 v[12:15], v[152:155], v[208:211], v[12:15]
	v_mfma_f32_16x16x32_bf16 v[8:11], v[160:163], v[208:211], v[8:11]
	v_mfma_f32_16x16x32_bf16 v[60:63], v[156:159], v[188:191], v[60:63]
	v_mfma_f32_16x16x32_bf16 v[56:59], v[164:167], v[188:191], v[56:59]
	v_mfma_f32_16x16x32_bf16 v[44:47], v[156:159], v[196:199], v[44:47]
	v_mfma_f32_16x16x32_bf16 v[40:43], v[164:167], v[196:199], v[40:43]
	v_mfma_f32_16x16x32_bf16 v[28:31], v[156:159], v[204:207], v[28:31]
	v_mfma_f32_16x16x32_bf16 v[24:27], v[164:167], v[204:207], v[24:27]
	v_mfma_f32_16x16x32_bf16 v[12:15], v[156:159], v[212:215], v[12:15]
	v_mfma_f32_16x16x32_bf16 v[8:11], v[164:167], v[212:215], v[8:11]
	s_setprio 0
	s_setprio 1
	v_mfma_f32_16x16x32_bf16 v[52:55], v[168:171], v[184:187], v[52:55]
	v_mfma_f32_16x16x32_bf16 v[48:51], v[176:179], v[184:187], v[48:51]
	v_mfma_f32_16x16x32_bf16 v[36:39], v[168:171], v[192:195], v[36:39]
	v_mfma_f32_16x16x32_bf16 v[32:35], v[176:179], v[192:195], v[32:35]
	v_mfma_f32_16x16x32_bf16 v[20:23], v[168:171], v[200:203], v[20:23]
	v_mfma_f32_16x16x32_bf16 v[16:19], v[176:179], v[200:203], v[16:19]
	v_mfma_f32_16x16x32_bf16 v[4:7], v[168:171], v[208:211], v[4:7]
	v_mfma_f32_16x16x32_bf16 v[0:3], v[176:179], v[208:211], v[0:3]
	v_mfma_f32_16x16x32_bf16 v[52:55], v[172:175], v[188:191], v[52:55]
	v_mfma_f32_16x16x32_bf16 v[48:51], v[180:183], v[188:191], v[48:51]
	v_mfma_f32_16x16x32_bf16 v[36:39], v[172:175], v[196:199], v[36:39]
	v_mfma_f32_16x16x32_bf16 v[32:35], v[180:183], v[196:199], v[32:35]
	v_mfma_f32_16x16x32_bf16 v[20:23], v[172:175], v[204:207], v[20:23]
	v_mfma_f32_16x16x32_bf16 v[16:19], v[180:183], v[204:207], v[16:19]
	v_mfma_f32_16x16x32_bf16 v[4:7], v[172:175], v[212:215], v[4:7]
	v_mfma_f32_16x16x32_bf16 v[0:3], v[180:183], v[212:215], v[0:3]
	s_setprio 0
	s_barrier
	s_add_i32 s58, s58, 2
	s_add_u32 s22, s22, 0x100
	s_addc_u32 s23, s23, 0
	s_add_u32 s56, s56, 0x100
	s_addc_u32 s57, s57, 0
	s_cmp_gt_u32 s58, 13
.LBB5_9:
	ds_read_b128 v[152:155], v149
	ds_read_b128 v[156:159], v149 offset:1024
	ds_read_b128 v[160:163], v149 offset:2048
	ds_read_b128 v[164:167], v149 offset:3072
	ds_read_b128 v[168:171], v150
	ds_read_b128 v[172:175], v150 offset:1024
	ds_read_b128 v[176:179], v150 offset:2048
	ds_read_b128 v[180:183], v150 offset:3072
	s_add_u32 s24, s22, 0xfffc0080
	s_addc_u32 s25, s23, -1
	s_cmp_eq_u32 s58, 12
	s_cselect_b32 s27, s15, s25
	s_cselect_b32 s26, s54, s24
	s_cselect_b32 s25, s13, s57
	s_cselect_b32 s24, s55, s56
	s_add_i32 m0, s21, 0xc000
	ds_read_b128 v[184:187], v151
	ds_read_b128 v[188:191], v151 offset:1024
	ds_read_b128 v[192:195], v151 offset:2048
	ds_read_b128 v[196:199], v151 offset:3072
	ds_read_b128 v[200:203], v151 offset:4096
	ds_read_b128 v[204:207], v151 offset:5120
	ds_read_b128 v[208:211], v151 offset:6144
	ds_read_b128 v[212:215], v151 offset:7168
	global_load_lds_dwordx4 v138, s[22:23]
	s_add_i32 m0, s21, 0xe000
	s_nop 0
	global_load_lds_dwordx4 v140, s[22:23]
	s_waitcnt vmcnt(8)
	s_waitcnt lgkmcnt(0)
	s_barrier
	s_setprio 1
	s_waitcnt lgkmcnt(0)
	v_mfma_f32_16x16x32_bf16 v[124:127], v[152:155], v[184:187], v[124:127]
	v_mfma_f32_16x16x32_bf16 v[120:123], v[160:163], v[184:187], v[120:123]
	v_mfma_f32_16x16x32_bf16 v[108:111], v[152:155], v[192:195], v[108:111]
	v_mfma_f32_16x16x32_bf16 v[104:107], v[160:163], v[192:195], v[104:107]
	v_mfma_f32_16x16x32_bf16 v[92:95], v[152:155], v[200:203], v[92:95]
	v_mfma_f32_16x16x32_bf16 v[88:91], v[160:163], v[200:203], v[88:91]
	v_mfma_f32_16x16x32_bf16 v[76:79], v[152:155], v[208:211], v[76:79]
	v_mfma_f32_16x16x32_bf16 v[72:75], v[160:163], v[208:211], v[72:75]
	v_mfma_f32_16x16x32_bf16 v[124:127], v[156:159], v[188:191], v[124:127]
	v_mfma_f32_16x16x32_bf16 v[120:123], v[164:167], v[188:191], v[120:123]
	v_mfma_f32_16x16x32_bf16 v[108:111], v[156:159], v[196:199], v[108:111]
	v_mfma_f32_16x16x32_bf16 v[104:107], v[164:167], v[196:199], v[104:107]
	v_mfma_f32_16x16x32_bf16 v[92:95], v[156:159], v[204:207], v[92:95]
	v_mfma_f32_16x16x32_bf16 v[88:91], v[164:167], v[204:207], v[88:91]
	v_mfma_f32_16x16x32_bf16 v[76:79], v[156:159], v[212:215], v[76:79]
	v_mfma_f32_16x16x32_bf16 v[72:75], v[164:167], v[212:215], v[72:75]
	s_setprio 0
	s_setprio 1
	v_mfma_f32_16x16x32_bf16 v[116:119], v[168:171], v[184:187], v[116:119]
	v_mfma_f32_16x16x32_bf16 v[112:115], v[176:179], v[184:187], v[112:115]
	v_mfma_f32_16x16x32_bf16 v[100:103], v[168:171], v[192:195], v[100:103]
	v_mfma_f32_16x16x32_bf16 v[96:99], v[176:179], v[192:195], v[96:99]
	v_mfma_f32_16x16x32_bf16 v[84:87], v[168:171], v[200:203], v[84:87]
	v_mfma_f32_16x16x32_bf16 v[80:83], v[176:179], v[200:203], v[80:83]
	v_mfma_f32_16x16x32_bf16 v[68:71], v[168:171], v[208:211], v[68:71]
	v_mfma_f32_16x16x32_bf16 v[64:67], v[176:179], v[208:211], v[64:67]
	v_mfma_f32_16x16x32_bf16 v[116:119], v[172:175], v[188:191], v[116:119]
	v_mfma_f32_16x16x32_bf16 v[112:115], v[180:183], v[188:191], v[112:115]
	v_mfma_f32_16x16x32_bf16 v[100:103], v[172:175], v[196:199], v[100:103]
	v_mfma_f32_16x16x32_bf16 v[96:99], v[180:183], v[196:199], v[96:99]
	v_mfma_f32_16x16x32_bf16 v[84:87], v[172:175], v[204:207], v[84:87]
	v_mfma_f32_16x16x32_bf16 v[80:83], v[180:183], v[204:207], v[80:83]
	v_mfma_f32_16x16x32_bf16 v[68:71], v[172:175], v[212:215], v[68:71]
	v_mfma_f32_16x16x32_bf16 v[64:67], v[180:183], v[212:215], v[64:67]
	s_setprio 0
	s_barrier
	s_add_i32 s59, s43, s33
	s_add_u32 s62, s24, 0x80
	s_addc_u32 s63, s25, 0
	s_mov_b32 m0, s59
	ds_read_b128 v[184:187], v151 offset:16384
	ds_read_b128 v[188:191], v151 offset:17408
	ds_read_b128 v[192:195], v151 offset:18432
	ds_read_b128 v[196:199], v151 offset:19456
	ds_read_b128 v[200:203], v151 offset:20480
	ds_read_b128 v[204:207], v151 offset:21504
	ds_read_b128 v[208:211], v151 offset:22528
	ds_read_b128 v[212:215], v151 offset:23552
	global_load_lds_dwordx4 v132, s[24:25]
	s_add_i32 m0, s59, 0x2000
	s_add_u32 s60, s24, 0x40000
	s_addc_u32 s61, s25, 0
	s_add_i32 s59, s44, s33
	global_load_lds_dwordx4 v128, s[24:25]
	s_mov_b32 m0, s59
	s_add_u32 s64, s26, 0x80
	s_addc_u32 s65, s27, 0
	global_load_lds_dwordx4 v132, s[60:61]
	s_add_i32 m0, s59, 0x2000
	s_nop 0
	global_load_lds_dwordx4 v128, s[60:61]
	s_mov_b32 m0, s21
	s_nop 0
	global_load_lds_dwordx4 v134, s[26:27]
	s_mov_b32 m0, s36
	s_nop 0
	global_load_lds_dwordx4 v130, s[26:27]
	s_waitcnt vmcnt(8)
	s_waitcnt lgkmcnt(0)
	s_barrier
	s_setprio 1
	s_waitcnt lgkmcnt(0)
	v_mfma_f32_16x16x32_bf16 v[60:63], v[152:155], v[184:187], v[60:63]
	v_mfma_f32_16x16x32_bf16 v[56:59], v[160:163], v[184:187], v[56:59]
	v_mfma_f32_16x16x32_bf16 v[44:47], v[152:155], v[192:195], v[44:47]
	v_mfma_f32_16x16x32_bf16 v[40:43], v[160:163], v[192:195], v[40:43]
	v_mfma_f32_16x16x32_bf16 v[28:31], v[152:155], v[200:203], v[28:31]
	v_mfma_f32_16x16x32_bf16 v[24:27], v[160:163], v[200:203], v[24:27]
	v_mfma_f32_16x16x32_bf16 v[12:15], v[152:155], v[208:211], v[12:15]
	v_mfma_f32_16x16x32_bf16 v[8:11], v[160:163], v[208:211], v[8:11]
	v_mfma_f32_16x16x32_bf16 v[60:63], v[156:159], v[188:191], v[60:63]
	v_mfma_f32_16x16x32_bf16 v[56:59], v[164:167], v[188:191], v[56:59]
	v_mfma_f32_16x16x32_bf16 v[44:47], v[156:159], v[196:199], v[44:47]
	v_mfma_f32_16x16x32_bf16 v[40:43], v[164:167], v[196:199], v[40:43]
	v_mfma_f32_16x16x32_bf16 v[28:31], v[156:159], v[204:207], v[28:31]
	v_mfma_f32_16x16x32_bf16 v[24:27], v[164:167], v[204:207], v[24:27]
	v_mfma_f32_16x16x32_bf16 v[12:15], v[156:159], v[212:215], v[12:15]
	v_mfma_f32_16x16x32_bf16 v[8:11], v[164:167], v[212:215], v[8:11]
	s_setprio 0
	s_setprio 1
	v_mfma_f32_16x16x32_bf16 v[52:55], v[168:171], v[184:187], v[52:55]
	v_mfma_f32_16x16x32_bf16 v[48:51], v[176:179], v[184:187], v[48:51]
	v_mfma_f32_16x16x32_bf16 v[36:39], v[168:171], v[192:195], v[36:39]
	v_mfma_f32_16x16x32_bf16 v[32:35], v[176:179], v[192:195], v[32:35]
	v_mfma_f32_16x16x32_bf16 v[20:23], v[168:171], v[200:203], v[20:23]
	v_mfma_f32_16x16x32_bf16 v[16:19], v[176:179], v[200:203], v[16:19]
	v_mfma_f32_16x16x32_bf16 v[4:7], v[168:171], v[208:211], v[4:7]
	v_mfma_f32_16x16x32_bf16 v[0:3], v[176:179], v[208:211], v[0:3]
	v_mfma_f32_16x16x32_bf16 v[52:55], v[172:175], v[188:191], v[52:55]
	v_mfma_f32_16x16x32_bf16 v[48:51], v[180:183], v[188:191], v[48:51]
	v_mfma_f32_16x16x32_bf16 v[36:39], v[172:175], v[196:199], v[36:39]
	v_mfma_f32_16x16x32_bf16 v[32:35], v[180:183], v[196:199], v[32:35]
	v_mfma_f32_16x16x32_bf16 v[20:23], v[172:175], v[204:207], v[20:23]
	v_mfma_f32_16x16x32_bf16 v[16:19], v[180:183], v[204:207], v[16:19]
	v_mfma_f32_16x16x32_bf16 v[4:7], v[172:175], v[212:215], v[4:7]
	v_mfma_f32_16x16x32_bf16 v[0:3], v[180:183], v[212:215], v[0:3]
	s_setprio 0
	s_barrier
	s_add_i32 s59, 0, 0x18000
	s_add_i32 s60, 0, 0x1c000
	v_add_u32_e32 v164, s59, v148
	v_add_u32_e32 v180, s60, v148
	ds_read_b128 v[152:155], v164
	ds_read_b128 v[156:159], v164 offset:1024
	ds_read_b128 v[160:163], v164 offset:2048
	ds_read_b128 v[164:167], v164 offset:3072
	ds_read_b128 v[168:171], v180
	ds_read_b128 v[172:175], v180 offset:1024
	ds_read_b128 v[176:179], v180 offset:2048
	ds_read_b128 v[180:183], v180 offset:3072
	s_add_u32 s26, s26, 0x40000
	s_addc_u32 s27, s27, 0
	s_mov_b32 m0, s37
	ds_read_b128 v[184:187], v151 offset:32768
	ds_read_b128 v[188:191], v151 offset:33792
	ds_read_b128 v[192:195], v151 offset:34816
	ds_read_b128 v[196:199], v151 offset:35840
	ds_read_b128 v[200:203], v151 offset:36864
	ds_read_b128 v[204:207], v151 offset:37888
	ds_read_b128 v[208:211], v151 offset:38912
	ds_read_b128 v[212:215], v151 offset:39936
	global_load_lds_dwordx4 v134, s[26:27]
	s_mov_b32 m0, s38
	s_nop 0
	global_load_lds_dwordx4 v130, s[26:27]
	s_waitcnt vmcnt(8)
	s_waitcnt lgkmcnt(0)
	s_barrier
	s_setprio 1
	s_waitcnt lgkmcnt(0)
	v_mfma_f32_16x16x32_bf16 v[124:127], v[152:155], v[184:187], v[124:127]
	v_mfma_f32_16x16x32_bf16 v[120:123], v[160:163], v[184:187], v[120:123]
	v_mfma_f32_16x16x32_bf16 v[108:111], v[152:155], v[192:195], v[108:111]
	v_mfma_f32_16x16x32_bf16 v[104:107], v[160:163], v[192:195], v[104:107]
	v_mfma_f32_16x16x32_bf16 v[92:95], v[152:155], v[200:203], v[92:95]
	v_mfma_f32_16x16x32_bf16 v[88:91], v[160:163], v[200:203], v[88:91]
	v_mfma_f32_16x16x32_bf16 v[76:79], v[152:155], v[208:211], v[76:79]
	v_mfma_f32_16x16x32_bf16 v[72:75], v[160:163], v[208:211], v[72:75]
	v_mfma_f32_16x16x32_bf16 v[124:127], v[156:159], v[188:191], v[124:127]
	v_mfma_f32_16x16x32_bf16 v[120:123], v[164:167], v[188:191], v[120:123]
	v_mfma_f32_16x16x32_bf16 v[108:111], v[156:159], v[196:199], v[108:111]
	v_mfma_f32_16x16x32_bf16 v[104:107], v[164:167], v[196:199], v[104:107]
	v_mfma_f32_16x16x32_bf16 v[92:95], v[156:159], v[204:207], v[92:95]
	v_mfma_f32_16x16x32_bf16 v[88:91], v[164:167], v[204:207], v[88:91]
	v_mfma_f32_16x16x32_bf16 v[76:79], v[156:159], v[212:215], v[76:79]
	v_mfma_f32_16x16x32_bf16 v[72:75], v[164:167], v[212:215], v[72:75]
	s_setprio 0
	s_setprio 1
	v_mfma_f32_16x16x32_bf16 v[116:119], v[168:171], v[184:187], v[116:119]
	v_mfma_f32_16x16x32_bf16 v[112:115], v[176:179], v[184:187], v[112:115]
	v_mfma_f32_16x16x32_bf16 v[100:103], v[168:171], v[192:195], v[100:103]
	v_mfma_f32_16x16x32_bf16 v[96:99], v[176:179], v[192:195], v[96:99]
	v_mfma_f32_16x16x32_bf16 v[84:87], v[168:171], v[200:203], v[84:87]
	v_mfma_f32_16x16x32_bf16 v[80:83], v[176:179], v[200:203], v[80:83]
	v_mfma_f32_16x16x32_bf16 v[68:71], v[168:171], v[208:211], v[68:71]
	v_mfma_f32_16x16x32_bf16 v[64:67], v[176:179], v[208:211], v[64:67]
	v_mfma_f32_16x16x32_bf16 v[116:119], v[172:175], v[188:191], v[116:119]
	v_mfma_f32_16x16x32_bf16 v[112:115], v[180:183], v[188:191], v[112:115]
	v_mfma_f32_16x16x32_bf16 v[100:103], v[172:175], v[196:199], v[100:103]
	v_mfma_f32_16x16x32_bf16 v[96:99], v[180:183], v[196:199], v[96:99]
	v_mfma_f32_16x16x32_bf16 v[84:87], v[172:175], v[204:207], v[84:87]
	v_mfma_f32_16x16x32_bf16 v[80:83], v[180:183], v[204:207], v[80:83]
	v_mfma_f32_16x16x32_bf16 v[68:71], v[172:175], v[212:215], v[68:71]
	v_mfma_f32_16x16x32_bf16 v[64:67], v[180:183], v[212:215], v[64:67]
	s_setprio 0
	s_barrier
	s_add_i32 s26, s59, s33
	s_mov_b32 m0, s26
	ds_read_b128 v[184:187], v151 offset:49152
	ds_read_b128 v[188:191], v151 offset:50176
	ds_read_b128 v[192:195], v151 offset:51200
	ds_read_b128 v[196:199], v151 offset:52224
	ds_read_b128 v[200:203], v151 offset:53248
	ds_read_b128 v[204:207], v151 offset:54272
	ds_read_b128 v[208:211], v151 offset:55296
	ds_read_b128 v[212:215], v151 offset:56320
	global_load_lds_dwordx4 v132, s[62:63]
	s_add_i32 m0, s26, 0x2000
	s_add_u32 s24, s24, 0x40080
	s_addc_u32 s25, s25, 0
	s_add_i32 s26, s60, s33
	global_load_lds_dwordx4 v128, s[62:63]
	s_mov_b32 m0, s26
	s_nop 0
	global_load_lds_dwordx4 v132, s[24:25]
	s_add_i32 m0, s26, 0x2000
	s_nop 0
	global_load_lds_dwordx4 v128, s[24:25]
	s_mov_b32 m0, s40
	s_nop 0
	global_load_lds_dwordx4 v134, s[64:65]
	s_mov_b32 m0, s41
	s_nop 0
	global_load_lds_dwordx4 v130, s[64:65]
	s_waitcnt vmcnt(8)
	s_waitcnt lgkmcnt(0)
	s_barrier
	s_setprio 1
	s_waitcnt lgkmcnt(0)
	v_mfma_f32_16x16x32_bf16 v[60:63], v[152:155], v[184:187], v[60:63]
	v_mfma_f32_16x16x32_bf16 v[56:59], v[160:163], v[184:187], v[56:59]
	v_mfma_f32_16x16x32_bf16 v[44:47], v[152:155], v[192:195], v[44:47]
	v_mfma_f32_16x16x32_bf16 v[40:43], v[160:163], v[192:195], v[40:43]
	v_mfma_f32_16x16x32_bf16 v[28:31], v[152:155], v[200:203], v[28:31]
	v_mfma_f32_16x16x32_bf16 v[24:27], v[160:163], v[200:203], v[24:27]
	v_mfma_f32_16x16x32_bf16 v[12:15], v[152:155], v[208:211], v[12:15]
	v_mfma_f32_16x16x32_bf16 v[8:11], v[160:163], v[208:211], v[8:11]
	v_mfma_f32_16x16x32_bf16 v[60:63], v[156:159], v[188:191], v[60:63]
	v_mfma_f32_16x16x32_bf16 v[56:59], v[164:167], v[188:191], v[56:59]
	v_mfma_f32_16x16x32_bf16 v[44:47], v[156:159], v[196:199], v[44:47]
	v_mfma_f32_16x16x32_bf16 v[40:43], v[164:167], v[196:199], v[40:43]
	v_mfma_f32_16x16x32_bf16 v[28:31], v[156:159], v[204:207], v[28:31]
	v_mfma_f32_16x16x32_bf16 v[24:27], v[164:167], v[204:207], v[24:27]
	v_mfma_f32_16x16x32_bf16 v[12:15], v[156:159], v[212:215], v[12:15]
	v_mfma_f32_16x16x32_bf16 v[8:11], v[164:167], v[212:215], v[8:11]
	s_setprio 0
	s_setprio 1
	v_mfma_f32_16x16x32_bf16 v[52:55], v[168:171], v[184:187], v[52:55]
	v_mfma_f32_16x16x32_bf16 v[48:51], v[176:179], v[184:187], v[48:51]
	v_mfma_f32_16x16x32_bf16 v[36:39], v[168:171], v[192:195], v[36:39]
	v_mfma_f32_16x16x32_bf16 v[32:35], v[176:179], v[192:195], v[32:35]
	v_mfma_f32_16x16x32_bf16 v[20:23], v[168:171], v[200:203], v[20:23]
	v_mfma_f32_16x16x32_bf16 v[16:19], v[176:179], v[200:203], v[16:19]
	v_mfma_f32_16x16x32_bf16 v[4:7], v[168:171], v[208:211], v[4:7]
	v_mfma_f32_16x16x32_bf16 v[0:3], v[176:179], v[208:211], v[0:3]
	v_mfma_f32_16x16x32_bf16 v[52:55], v[172:175], v[188:191], v[52:55]
	v_mfma_f32_16x16x32_bf16 v[48:51], v[180:183], v[188:191], v[48:51]
	v_mfma_f32_16x16x32_bf16 v[36:39], v[172:175], v[196:199], v[36:39]
	v_mfma_f32_16x16x32_bf16 v[32:35], v[180:183], v[196:199], v[32:35]
	v_mfma_f32_16x16x32_bf16 v[20:23], v[172:175], v[204:207], v[20:23]
	v_mfma_f32_16x16x32_bf16 v[16:19], v[180:183], v[204:207], v[16:19]
	v_mfma_f32_16x16x32_bf16 v[4:7], v[172:175], v[212:215], v[4:7]
	v_mfma_f32_16x16x32_bf16 v[0:3], v[180:183], v[212:215], v[0:3]
	s_setprio 0
	s_barrier
	s_add_i32 s58, s58, 2
	s_add_u32 s22, s22, 0x100
	s_addc_u32 s23, s23, 0
	s_add_u32 s56, s56, 0x100
	s_addc_u32 s57, s57, 0
	s_cmp_gt_u32 s58, 13
	s_cbranch_scc0 .LBB5_9
	s_mov_b64 vcc, s[0:1]
	s_cbranch_vccz .LBB5_12
	s_barrier

	.amdhsa_kernel _Z10fwd_kernelILi5ELi6EEv4Args
		.amdhsa_group_segment_fixed_size 0
		.amdhsa_private_segment_fixed_size 0
		.amdhsa_kernarg_size 488
		.amdhsa_user_sgpr_count 2
		.amdhsa_user_sgpr_dispatch_ptr 0
		.amdhsa_user_sgpr_queue_ptr 0
		.amdhsa_user_sgpr_kernarg_segment_ptr 1
		.amdhsa_user_sgpr_dispatch_id 0
		.amdhsa_user_sgpr_kernarg_preload_length 0
		.amdhsa_user_sgpr_kernarg_preload_offset 0
		.amdhsa_user_sgpr_private_segment_size 0
		.amdhsa_uses_dynamic_stack 0
		.amdhsa_enable_private_segment 0
		.amdhsa_system_sgpr_workgroup_id_x 1
		.amdhsa_system_sgpr_workgroup_id_y 0
		.amdhsa_system_sgpr_workgroup_id_z 0
		.amdhsa_system_sgpr_workgroup_info 0
		.amdhsa_system_vgpr_workitem_id 0
		.amdhsa_next_free_vgpr 256
		.amdhsa_next_free_sgpr 70
		.amdhsa_accum_offset 256
		.amdhsa_reserve_vcc 1
		.amdhsa_float_round_mode_32 0
		.amdhsa_float_round_mode_16_64 0
		.amdhsa_float_denorm_mode_32 3
		.amdhsa_float_denorm_mode_16_64 3
		.amdhsa_dx10_clamp 1
		.amdhsa_ieee_mode 1
		.amdhsa_fp16_overflow 0
		.amdhsa_tg_split 0
		.amdhsa_exception_fp_ieee_invalid_op 0
		.amdhsa_exception_fp_denorm_src 0
		.amdhsa_exception_fp_ieee_div_zero 0
		.amdhsa_exception_fp_ieee_overflow 0
		.amdhsa_exception_fp_ieee_underflow 0
		.amdhsa_exception_fp_ieee_inexact 0
		.amdhsa_exception_int_div_zero 0
	.end_amdhsa_kernel

.LBB6_19:
	s_ashr_i32 s17, s16, 31
	s_lshl_b64 s[18:19], s[16:17], 21
	s_add_u32 s18, s33, s18
	v_cmp_lt_i64_e64 s[4:5], s[4:5], v[142:143]
	s_addc_u32 s19, s34, s19
	s_and_b64 s[20:21], s[4:5], exec
	s_cselect_b32 s17, s19, s25
	s_cselect_b32 s53, s18, s24
	s_ashr_i32 s15, s14, 31
	s_lshl_b64 s[20:21], s[14:15], 21
	s_add_u32 s20, s6, s20
	s_addc_u32 s21, s7, s21
	s_and_b64 s[28:29], s[4:5], exec
	s_cselect_b32 s15, s21, s27
	s_cselect_b32 s54, s20, s26
	s_add_u32 s24, s24, 0x100080
	s_addc_u32 s25, s25, 0
	s_add_u32 s55, s26, 0x100
	s_addc_u32 s56, s27, 0
	s_mov_b32 s57, -2
	ds_read_b128 v[152:155], v149
	ds_read_b128 v[156:159], v149 offset:1024
	ds_read_b128 v[160:163], v149 offset:2048
	ds_read_b128 v[164:167], v149 offset:3072
	ds_read_b128 v[168:171], v150
	ds_read_b128 v[172:175], v150 offset:1024
	ds_read_b128 v[176:179], v150 offset:2048
	ds_read_b128 v[180:183], v150 offset:3072
	s_add_u32 s26, s24, 0xfff00080
	s_addc_u32 s27, s25, -1
	s_cmp_eq_u32 s57, 60
	s_cselect_b32 s29, s17, s27
	s_cselect_b32 s28, s53, s26
	s_cselect_b32 s27, s15, s56
	s_cselect_b32 s26, s54, s55
	s_add_i32 m0, s23, 0xc000
	ds_read_b128 v[184:187], v151
	ds_read_b128 v[188:191], v151 offset:1024
	ds_read_b128 v[192:195], v151 offset:2048
	ds_read_b128 v[196:199], v151 offset:3072
	ds_read_b128 v[200:203], v151 offset:4096
	ds_read_b128 v[204:207], v151 offset:5120
	ds_read_b128 v[208:211], v151 offset:6144
	ds_read_b128 v[212:215], v151 offset:7168
	global_load_lds_dwordx4 v138, s[24:25]
	s_add_i32 m0, s23, 0xe000
	s_nop 0
	global_load_lds_dwordx4 v140, s[24:25]
	s_waitcnt vmcnt(8)
	s_waitcnt lgkmcnt(0)
	s_barrier
	s_setprio 1
	s_waitcnt lgkmcnt(0)
	v_mfma_f32_16x16x32_bf16 v[124:127], v[152:155], v[184:187], 0
	v_mfma_f32_16x16x32_bf16 v[120:123], v[160:163], v[184:187], 0
	v_mfma_f32_16x16x32_bf16 v[116:119], v[152:155], v[192:195], 0
	v_mfma_f32_16x16x32_bf16 v[108:111], v[160:163], v[192:195], 0
	v_mfma_f32_16x16x32_bf16 v[100:103], v[152:155], v[200:203], 0
	v_mfma_f32_16x16x32_bf16 v[92:95], v[160:163], v[200:203], 0
	v_mfma_f32_16x16x32_bf16 v[84:87], v[152:155], v[208:211], 0
	v_mfma_f32_16x16x32_bf16 v[76:79], v[160:163], v[208:211], 0
	v_mfma_f32_16x16x32_bf16 v[124:127], v[156:159], v[188:191], v[124:127]
	v_mfma_f32_16x16x32_bf16 v[120:123], v[164:167], v[188:191], v[120:123]
	v_mfma_f32_16x16x32_bf16 v[116:119], v[156:159], v[196:199], v[116:119]
	v_mfma_f32_16x16x32_bf16 v[108:111], v[164:167], v[196:199], v[108:111]
	v_mfma_f32_16x16x32_bf16 v[100:103], v[156:159], v[204:207], v[100:103]
	v_mfma_f32_16x16x32_bf16 v[92:95], v[164:167], v[204:207], v[92:95]
	v_mfma_f32_16x16x32_bf16 v[84:87], v[156:159], v[212:215], v[84:87]
	v_mfma_f32_16x16x32_bf16 v[76:79], v[164:167], v[212:215], v[76:79]
	s_setprio 0
	s_setprio 1
	v_mfma_f32_16x16x32_bf16 v[112:115], v[168:171], v[184:187], 0
	v_mfma_f32_16x16x32_bf16 v[104:107], v[176:179], v[184:187], 0
	v_mfma_f32_16x16x32_bf16 v[96:99], v[168:171], v[192:195], 0
	v_mfma_f32_16x16x32_bf16 v[88:91], v[176:179], v[192:195], 0
	v_mfma_f32_16x16x32_bf16 v[80:83], v[168:171], v[200:203], 0
	v_mfma_f32_16x16x32_bf16 v[72:75], v[176:179], v[200:203], 0
	v_mfma_f32_16x16x32_bf16 v[68:71], v[168:171], v[208:211], 0
	v_mfma_f32_16x16x32_bf16 v[64:67], v[176:179], v[208:211], 0
	v_mfma_f32_16x16x32_bf16 v[112:115], v[172:175], v[188:191], v[112:115]
	v_mfma_f32_16x16x32_bf16 v[104:107], v[180:183], v[188:191], v[104:107]
	v_mfma_f32_16x16x32_bf16 v[96:99], v[172:175], v[196:199], v[96:99]
	v_mfma_f32_16x16x32_bf16 v[88:91], v[180:183], v[196:199], v[88:91]
	v_mfma_f32_16x16x32_bf16 v[80:83], v[172:175], v[204:207], v[80:83]
	v_mfma_f32_16x16x32_bf16 v[72:75], v[180:183], v[204:207], v[72:75]
	v_mfma_f32_16x16x32_bf16 v[68:71], v[172:175], v[212:215], v[68:71]
	v_mfma_f32_16x16x32_bf16 v[64:67], v[180:183], v[212:215], v[64:67]
	s_setprio 0
	s_barrier
	s_add_i32 s58, s45, s31
	s_add_u32 s62, s26, 0x80
	s_addc_u32 s63, s27, 0
	s_mov_b32 m0, s58
	ds_read_b128 v[184:187], v151 offset:16384
	ds_read_b128 v[188:191], v151 offset:17408
	ds_read_b128 v[192:195], v151 offset:18432
	ds_read_b128 v[196:199], v151 offset:19456
	ds_read_b128 v[200:203], v151 offset:20480
	ds_read_b128 v[204:207], v151 offset:21504
	ds_read_b128 v[208:211], v151 offset:22528
	ds_read_b128 v[212:215], v151 offset:23552
	global_load_lds_dwordx4 v130, s[26:27]
	s_add_i32 m0, s58, 0x2000
	s_add_u32 s58, s26, 0x100000
	s_addc_u32 s59, s27, 0
	s_add_i32 s60, s46, s31
	global_load_lds_dwordx4 v134, s[26:27]
	s_mov_b32 m0, s60
	s_add_u32 s64, s28, 0x80
	s_addc_u32 s65, s29, 0
	global_load_lds_dwordx4 v130, s[58:59]
	s_add_i32 m0, s60, 0x2000
	s_nop 0
	global_load_lds_dwordx4 v134, s[58:59]
	s_mov_b32 m0, s23
	s_nop 0
	global_load_lds_dwordx4 v128, s[28:29]
	s_mov_b32 m0, s35
	s_nop 0
	global_load_lds_dwordx4 v132, s[28:29]
	s_waitcnt vmcnt(8)
	s_waitcnt lgkmcnt(0)
	s_barrier
	s_setprio 1
	s_waitcnt lgkmcnt(0)
	v_mfma_f32_16x16x32_bf16 v[60:63], v[152:155], v[184:187], 0
	v_mfma_f32_16x16x32_bf16 v[56:59], v[160:163], v[184:187], 0
	v_mfma_f32_16x16x32_bf16 v[52:55], v[152:155], v[192:195], 0
	v_mfma_f32_16x16x32_bf16 v[44:47], v[160:163], v[192:195], 0
	v_mfma_f32_16x16x32_bf16 v[36:39], v[152:155], v[200:203], 0
	v_mfma_f32_16x16x32_bf16 v[28:31], v[160:163], v[200:203], 0
	v_mfma_f32_16x16x32_bf16 v[20:23], v[152:155], v[208:211], 0
	v_mfma_f32_16x16x32_bf16 v[12:15], v[160:163], v[208:211], 0
	v_mfma_f32_16x16x32_bf16 v[60:63], v[156:159], v[188:191], v[60:63]
	v_mfma_f32_16x16x32_bf16 v[56:59], v[164:167], v[188:191], v[56:59]
	v_mfma_f32_16x16x32_bf16 v[52:55], v[156:159], v[196:199], v[52:55]
	v_mfma_f32_16x16x32_bf16 v[44:47], v[164:167], v[196:199], v[44:47]
	v_mfma_f32_16x16x32_bf16 v[36:39], v[156:159], v[204:207], v[36:39]
	v_mfma_f32_16x16x32_bf16 v[28:31], v[164:167], v[204:207], v[28:31]
	v_mfma_f32_16x16x32_bf16 v[20:23], v[156:159], v[212:215], v[20:23]
	v_mfma_f32_16x16x32_bf16 v[12:15], v[164:167], v[212:215], v[12:15]
	s_setprio 0
	s_setprio 1
	v_mfma_f32_16x16x32_bf16 v[48:51], v[168:171], v[184:187], 0
	v_mfma_f32_16x16x32_bf16 v[40:43], v[176:179], v[184:187], 0
	v_mfma_f32_16x16x32_bf16 v[32:35], v[168:171], v[192:195], 0
	v_mfma_f32_16x16x32_bf16 v[24:27], v[176:179], v[192:195], 0
	v_mfma_f32_16x16x32_bf16 v[16:19], v[168:171], v[200:203], 0
	v_mfma_f32_16x16x32_bf16 v[8:11], v[176:179], v[200:203], 0
	v_mfma_f32_16x16x32_bf16 v[4:7], v[168:171], v[208:211], 0
	v_mfma_f32_16x16x32_bf16 v[0:3], v[176:179], v[208:211], 0
	v_mfma_f32_16x16x32_bf16 v[48:51], v[172:175], v[188:191], v[48:51]
	v_mfma_f32_16x16x32_bf16 v[40:43], v[180:183], v[188:191], v[40:43]
	v_mfma_f32_16x16x32_bf16 v[32:35], v[172:175], v[196:199], v[32:35]
	v_mfma_f32_16x16x32_bf16 v[24:27], v[180:183], v[196:199], v[24:27]
	v_mfma_f32_16x16x32_bf16 v[16:19], v[172:175], v[204:207], v[16:19]
	v_mfma_f32_16x16x32_bf16 v[8:11], v[180:183], v[204:207], v[8:11]
	v_mfma_f32_16x16x32_bf16 v[4:7], v[172:175], v[212:215], v[4:7]
	v_mfma_f32_16x16x32_bf16 v[0:3], v[180:183], v[212:215], v[0:3]
	s_setprio 0
	s_barrier
	s_add_i32 s58, 0, 0x18000
	s_add_i32 s59, 0, 0x1c000
	v_add_u32_e32 v164, s58, v148
	v_add_u32_e32 v180, s59, v148
	ds_read_b128 v[152:155], v164
	ds_read_b128 v[156:159], v164 offset:1024
	ds_read_b128 v[160:163], v164 offset:2048
	ds_read_b128 v[164:167], v164 offset:3072
	ds_read_b128 v[168:171], v180
	ds_read_b128 v[172:175], v180 offset:1024
	ds_read_b128 v[176:179], v180 offset:2048
	ds_read_b128 v[180:183], v180 offset:3072
	s_add_u32 s28, s28, 0x100000
	s_addc_u32 s29, s29, 0
	s_mov_b32 m0, s36
	ds_read_b128 v[184:187], v151 offset:32768
	ds_read_b128 v[188:191], v151 offset:33792
	ds_read_b128 v[192:195], v151 offset:34816
	ds_read_b128 v[196:199], v151 offset:35840
	ds_read_b128 v[200:203], v151 offset:36864
	ds_read_b128 v[204:207], v151 offset:37888
	ds_read_b128 v[208:211], v151 offset:38912
	ds_read_b128 v[212:215], v151 offset:39936
	global_load_lds_dwordx4 v128, s[28:29]
	s_mov_b32 m0, s37
	s_nop 0
	global_load_lds_dwordx4 v132, s[28:29]
	s_waitcnt vmcnt(8)
	s_waitcnt lgkmcnt(0)
	s_barrier
	s_setprio 1
	s_waitcnt lgkmcnt(0)
	v_mfma_f32_16x16x32_bf16 v[124:127], v[152:155], v[184:187], v[124:127]
	v_mfma_f32_16x16x32_bf16 v[120:123], v[160:163], v[184:187], v[120:123]
	v_mfma_f32_16x16x32_bf16 v[116:119], v[152:155], v[192:195], v[116:119]
	v_mfma_f32_16x16x32_bf16 v[108:111], v[160:163], v[192:195], v[108:111]
	v_mfma_f32_16x16x32_bf16 v[100:103], v[152:155], v[200:203], v[100:103]
	v_mfma_f32_16x16x32_bf16 v[92:95], v[160:163], v[200:203], v[92:95]
	v_mfma_f32_16x16x32_bf16 v[84:87], v[152:155], v[208:211], v[84:87]
	v_mfma_f32_16x16x32_bf16 v[76:79], v[160:163], v[208:211], v[76:79]
	v_mfma_f32_16x16x32_bf16 v[124:127], v[156:159], v[188:191], v[124:127]
	v_mfma_f32_16x16x32_bf16 v[120:123], v[164:167], v[188:191], v[120:123]
	v_mfma_f32_16x16x32_bf16 v[116:119], v[156:159], v[196:199], v[116:119]
	v_mfma_f32_16x16x32_bf16 v[108:111], v[164:167], v[196:199], v[108:111]
	v_mfma_f32_16x16x32_bf16 v[100:103], v[156:159], v[204:207], v[100:103]
	v_mfma_f32_16x16x32_bf16 v[92:95], v[164:167], v[204:207], v[92:95]
	v_mfma_f32_16x16x32_bf16 v[84:87], v[156:159], v[212:215], v[84:87]
	v_mfma_f32_16x16x32_bf16 v[76:79], v[164:167], v[212:215], v[76:79]
	s_setprio 0
	s_setprio 1
	v_mfma_f32_16x16x32_bf16 v[112:115], v[168:171], v[184:187], v[112:115]
	v_mfma_f32_16x16x32_bf16 v[104:107], v[176:179], v[184:187], v[104:107]
	v_mfma_f32_16x16x32_bf16 v[96:99], v[168:171], v[192:195], v[96:99]
	v_mfma_f32_16x16x32_bf16 v[88:91], v[176:179], v[192:195], v[88:91]
	v_mfma_f32_16x16x32_bf16 v[80:83], v[168:171], v[200:203], v[80:83]
	v_mfma_f32_16x16x32_bf16 v[72:75], v[176:179], v[200:203], v[72:75]
	v_mfma_f32_16x16x32_bf16 v[68:71], v[168:171], v[208:211], v[68:71]
	v_mfma_f32_16x16x32_bf16 v[64:67], v[176:179], v[208:211], v[64:67]
	v_mfma_f32_16x16x32_bf16 v[112:115], v[172:175], v[188:191], v[112:115]
	v_mfma_f32_16x16x32_bf16 v[104:107], v[180:183], v[188:191], v[104:107]
	v_mfma_f32_16x16x32_bf16 v[96:99], v[172:175], v[196:199], v[96:99]
	v_mfma_f32_16x16x32_bf16 v[88:91], v[180:183], v[196:199], v[88:91]
	v_mfma_f32_16x16x32_bf16 v[80:83], v[172:175], v[204:207], v[80:83]
	v_mfma_f32_16x16x32_bf16 v[72:75], v[180:183], v[204:207], v[72:75]
	v_mfma_f32_16x16x32_bf16 v[68:71], v[172:175], v[212:215], v[68:71]
	v_mfma_f32_16x16x32_bf16 v[64:67], v[180:183], v[212:215], v[64:67]
	s_setprio 0
	s_barrier
	s_add_i32 s28, s58, s31
	s_mov_b32 m0, s28
	ds_read_b128 v[184:187], v151 offset:49152
	ds_read_b128 v[188:191], v151 offset:50176
	ds_read_b128 v[192:195], v151 offset:51200
	ds_read_b128 v[196:199], v151 offset:52224
	ds_read_b128 v[200:203], v151 offset:53248
	ds_read_b128 v[204:207], v151 offset:54272
	ds_read_b128 v[208:211], v151 offset:55296
	ds_read_b128 v[212:215], v151 offset:56320
	global_load_lds_dwordx4 v130, s[62:63]
	s_add_i32 m0, s28, 0x2000
	s_add_u32 s26, s26, 0x100080
	s_addc_u32 s27, s27, 0
	s_add_i32 s28, s59, s31
	global_load_lds_dwordx4 v134, s[62:63]
	s_mov_b32 m0, s28
	s_nop 0
	global_load_lds_dwordx4 v130, s[26:27]
	s_add_i32 m0, s28, 0x2000
	s_nop 0
	global_load_lds_dwordx4 v134, s[26:27]
	s_mov_b32 m0, s40
	s_nop 0
	global_load_lds_dwordx4 v128, s[64:65]
	s_mov_b32 m0, s41
	s_nop 0
	global_load_lds_dwordx4 v132, s[64:65]
	s_waitcnt vmcnt(8)
	s_waitcnt lgkmcnt(0)
	s_barrier
	s_setprio 1
	s_waitcnt lgkmcnt(0)
	v_mfma_f32_16x16x32_bf16 v[60:63], v[152:155], v[184:187], v[60:63]
	v_mfma_f32_16x16x32_bf16 v[56:59], v[160:163], v[184:187], v[56:59]
	v_mfma_f32_16x16x32_bf16 v[52:55], v[152:155], v[192:195], v[52:55]
	v_mfma_f32_16x16x32_bf16 v[44:47], v[160:163], v[192:195], v[44:47]
	v_mfma_f32_16x16x32_bf16 v[36:39], v[152:155], v[200:203], v[36:39]
	v_mfma_f32_16x16x32_bf16 v[28:31], v[160:163], v[200:203], v[28:31]
	v_mfma_f32_16x16x32_bf16 v[20:23], v[152:155], v[208:211], v[20:23]
	v_mfma_f32_16x16x32_bf16 v[12:15], v[160:163], v[208:211], v[12:15]
	v_mfma_f32_16x16x32_bf16 v[60:63], v[156:159], v[188:191], v[60:63]
	v_mfma_f32_16x16x32_bf16 v[56:59], v[164:167], v[188:191], v[56:59]
	v_mfma_f32_16x16x32_bf16 v[52:55], v[156:159], v[196:199], v[52:55]
	v_mfma_f32_16x16x32_bf16 v[44:47], v[164:167], v[196:199], v[44:47]
	v_mfma_f32_16x16x32_bf16 v[36:39], v[156:159], v[204:207], v[36:39]
	v_mfma_f32_16x16x32_bf16 v[28:31], v[164:167], v[204:207], v[28:31]
	v_mfma_f32_16x16x32_bf16 v[20:23], v[156:159], v[212:215], v[20:23]
	v_mfma_f32_16x16x32_bf16 v[12:15], v[164:167], v[212:215], v[12:15]
	s_setprio 0
	s_setprio 1
	v_mfma_f32_16x16x32_bf16 v[48:51], v[168:171], v[184:187], v[48:51]
	v_mfma_f32_16x16x32_bf16 v[40:43], v[176:179], v[184:187], v[40:43]
	v_mfma_f32_16x16x32_bf16 v[32:35], v[168:171], v[192:195], v[32:35]
	v_mfma_f32_16x16x32_bf16 v[24:27], v[176:179], v[192:195], v[24:27]
	v_mfma_f32_16x16x32_bf16 v[16:19], v[168:171], v[200:203], v[16:19]
	v_mfma_f32_16x16x32_bf16 v[8:11], v[176:179], v[200:203], v[8:11]
	v_mfma_f32_16x16x32_bf16 v[4:7], v[168:171], v[208:211], v[4:7]
	v_mfma_f32_16x16x32_bf16 v[0:3], v[176:179], v[208:211], v[0:3]
	v_mfma_f32_16x16x32_bf16 v[48:51], v[172:175], v[188:191], v[48:51]
	v_mfma_f32_16x16x32_bf16 v[40:43], v[180:183], v[188:191], v[40:43]
	v_mfma_f32_16x16x32_bf16 v[32:35], v[172:175], v[196:199], v[32:35]
	v_mfma_f32_16x16x32_bf16 v[24:27], v[180:183], v[196:199], v[24:27]
	v_mfma_f32_16x16x32_bf16 v[16:19], v[172:175], v[204:207], v[16:19]
	v_mfma_f32_16x16x32_bf16 v[8:11], v[180:183], v[204:207], v[8:11]
	v_mfma_f32_16x16x32_bf16 v[4:7], v[172:175], v[212:215], v[4:7]
	v_mfma_f32_16x16x32_bf16 v[0:3], v[180:183], v[212:215], v[0:3]
	s_setprio 0
	s_barrier
	s_add_i32 s57, s57, 2
	s_add_u32 s24, s24, 0x100
	s_addc_u32 s25, s25, 0
	s_add_u32 s55, s55, 0x100
	s_addc_u32 s56, s56, 0
	s_cmp_gt_u32 s57, 61
.LBB6_20:
	ds_read_b128 v[152:155], v149
	ds_read_b128 v[156:159], v149 offset:1024
	ds_read_b128 v[160:163], v149 offset:2048
	ds_read_b128 v[164:167], v149 offset:3072
	ds_read_b128 v[168:171], v150
	ds_read_b128 v[172:175], v150 offset:1024
	ds_read_b128 v[176:179], v150 offset:2048
	ds_read_b128 v[180:183], v150 offset:3072
	s_add_u32 s26, s24, 0xfff00080
	s_addc_u32 s27, s25, -1
	s_cmp_eq_u32 s57, 60
	s_cselect_b32 s29, s17, s27
	s_cselect_b32 s28, s53, s26
	s_cselect_b32 s27, s15, s56
	s_cselect_b32 s26, s54, s55
	s_add_i32 m0, s23, 0xc000
	ds_read_b128 v[184:187], v151
	ds_read_b128 v[188:191], v151 offset:1024
	ds_read_b128 v[192:195], v151 offset:2048
	ds_read_b128 v[196:199], v151 offset:3072
	ds_read_b128 v[200:203], v151 offset:4096
	ds_read_b128 v[204:207], v151 offset:5120
	ds_read_b128 v[208:211], v151 offset:6144
	ds_read_b128 v[212:215], v151 offset:7168
	global_load_lds_dwordx4 v138, s[24:25]
	s_add_i32 m0, s23, 0xe000
	s_nop 0
	global_load_lds_dwordx4 v140, s[24:25]
	s_waitcnt vmcnt(8)
	s_waitcnt lgkmcnt(0)
	s_barrier
	s_setprio 1
	s_waitcnt lgkmcnt(0)
	v_mfma_f32_16x16x32_bf16 v[124:127], v[152:155], v[184:187], v[124:127]
	v_mfma_f32_16x16x32_bf16 v[120:123], v[160:163], v[184:187], v[120:123]
	v_mfma_f32_16x16x32_bf16 v[116:119], v[152:155], v[192:195], v[116:119]
	v_mfma_f32_16x16x32_bf16 v[108:111], v[160:163], v[192:195], v[108:111]
	v_mfma_f32_16x16x32_bf16 v[100:103], v[152:155], v[200:203], v[100:103]
	v_mfma_f32_16x16x32_bf16 v[92:95], v[160:163], v[200:203], v[92:95]
	v_mfma_f32_16x16x32_bf16 v[84:87], v[152:155], v[208:211], v[84:87]
	v_mfma_f32_16x16x32_bf16 v[76:79], v[160:163], v[208:211], v[76:79]
	v_mfma_f32_16x16x32_bf16 v[124:127], v[156:159], v[188:191], v[124:127]
	v_mfma_f32_16x16x32_bf16 v[120:123], v[164:167], v[188:191], v[120:123]
	v_mfma_f32_16x16x32_bf16 v[116:119], v[156:159], v[196:199], v[116:119]
	v_mfma_f32_16x16x32_bf16 v[108:111], v[164:167], v[196:199], v[108:111]
	v_mfma_f32_16x16x32_bf16 v[100:103], v[156:159], v[204:207], v[100:103]
	v_mfma_f32_16x16x32_bf16 v[92:95], v[164:167], v[204:207], v[92:95]
	v_mfma_f32_16x16x32_bf16 v[84:87], v[156:159], v[212:215], v[84:87]
	v_mfma_f32_16x16x32_bf16 v[76:79], v[164:167], v[212:215], v[76:79]
	s_setprio 0
	s_setprio 1
	v_mfma_f32_16x16x32_bf16 v[112:115], v[168:171], v[184:187], v[112:115]
	v_mfma_f32_16x16x32_bf16 v[104:107], v[176:179], v[184:187], v[104:107]
	v_mfma_f32_16x16x32_bf16 v[96:99], v[168:171], v[192:195], v[96:99]
	v_mfma_f32_16x16x32_bf16 v[88:91], v[176:179], v[192:195], v[88:91]
	v_mfma_f32_16x16x32_bf16 v[80:83], v[168:171], v[200:203], v[80:83]
	v_mfma_f32_16x16x32_bf16 v[72:75], v[176:179], v[200:203], v[72:75]
	v_mfma_f32_16x16x32_bf16 v[68:71], v[168:171], v[208:211], v[68:71]
	v_mfma_f32_16x16x32_bf16 v[64:67], v[176:179], v[208:211], v[64:67]
	v_mfma_f32_16x16x32_bf16 v[112:115], v[172:175], v[188:191], v[112:115]
	v_mfma_f32_16x16x32_bf16 v[104:107], v[180:183], v[188:191], v[104:107]
	v_mfma_f32_16x16x32_bf16 v[96:99], v[172:175], v[196:199], v[96:99]
	v_mfma_f32_16x16x32_bf16 v[88:91], v[180:183], v[196:199], v[88:91]
	v_mfma_f32_16x16x32_bf16 v[80:83], v[172:175], v[204:207], v[80:83]
	v_mfma_f32_16x16x32_bf16 v[72:75], v[180:183], v[204:207], v[72:75]
	v_mfma_f32_16x16x32_bf16 v[68:71], v[172:175], v[212:215], v[68:71]
	v_mfma_f32_16x16x32_bf16 v[64:67], v[180:183], v[212:215], v[64:67]
	s_setprio 0
	s_barrier
	s_add_i32 s58, s45, s31
	s_add_u32 s62, s26, 0x80
	s_addc_u32 s63, s27, 0
	s_mov_b32 m0, s58
	ds_read_b128 v[184:187], v151 offset:16384
	ds_read_b128 v[188:191], v151 offset:17408
	ds_read_b128 v[192:195], v151 offset:18432
	ds_read_b128 v[196:199], v151 offset:19456
	ds_read_b128 v[200:203], v151 offset:20480
	ds_read_b128 v[204:207], v151 offset:21504
	ds_read_b128 v[208:211], v151 offset:22528
	ds_read_b128 v[212:215], v151 offset:23552
	global_load_lds_dwordx4 v130, s[26:27]
	s_add_i32 m0, s58, 0x2000
	s_add_u32 s58, s26, 0x100000
	s_addc_u32 s59, s27, 0
	s_add_i32 s60, s46, s31
	global_load_lds_dwordx4 v134, s[26:27]
	s_mov_b32 m0, s60
	s_add_u32 s64, s28, 0x80
	s_addc_u32 s65, s29, 0
	global_load_lds_dwordx4 v130, s[58:59]
	s_add_i32 m0, s60, 0x2000
	s_nop 0
	global_load_lds_dwordx4 v134, s[58:59]
	s_mov_b32 m0, s23
	s_nop 0
	global_load_lds_dwordx4 v128, s[28:29]
	s_mov_b32 m0, s35
	s_nop 0
	global_load_lds_dwordx4 v132, s[28:29]
	s_waitcnt vmcnt(8)
	s_waitcnt lgkmcnt(0)
	s_barrier
	s_setprio 1
	s_waitcnt lgkmcnt(0)
	v_mfma_f32_16x16x32_bf16 v[60:63], v[152:155], v[184:187], v[60:63]
	v_mfma_f32_16x16x32_bf16 v[56:59], v[160:163], v[184:187], v[56:59]
	v_mfma_f32_16x16x32_bf16 v[52:55], v[152:155], v[192:195], v[52:55]
	v_mfma_f32_16x16x32_bf16 v[44:47], v[160:163], v[192:195], v[44:47]
	v_mfma_f32_16x16x32_bf16 v[36:39], v[152:155], v[200:203], v[36:39]
	v_mfma_f32_16x16x32_bf16 v[28:31], v[160:163], v[200:203], v[28:31]
	v_mfma_f32_16x16x32_bf16 v[20:23], v[152:155], v[208:211], v[20:23]
	v_mfma_f32_16x16x32_bf16 v[12:15], v[160:163], v[208:211], v[12:15]
	v_mfma_f32_16x16x32_bf16 v[60:63], v[156:159], v[188:191], v[60:63]
	v_mfma_f32_16x16x32_bf16 v[56:59], v[164:167], v[188:191], v[56:59]
	v_mfma_f32_16x16x32_bf16 v[52:55], v[156:159], v[196:199], v[52:55]
	v_mfma_f32_16x16x32_bf16 v[44:47], v[164:167], v[196:199], v[44:47]
	v_mfma_f32_16x16x32_bf16 v[36:39], v[156:159], v[204:207], v[36:39]
	v_mfma_f32_16x16x32_bf16 v[28:31], v[164:167], v[204:207], v[28:31]
	v_mfma_f32_16x16x32_bf16 v[20:23], v[156:159], v[212:215], v[20:23]
	v_mfma_f32_16x16x32_bf16 v[12:15], v[164:167], v[212:215], v[12:15]
	s_setprio 0
	s_setprio 1
	v_mfma_f32_16x16x32_bf16 v[48:51], v[168:171], v[184:187], v[48:51]
	v_mfma_f32_16x16x32_bf16 v[40:43], v[176:179], v[184:187], v[40:43]
	v_mfma_f32_16x16x32_bf16 v[32:35], v[168:171], v[192:195], v[32:35]
	v_mfma_f32_16x16x32_bf16 v[24:27], v[176:179], v[192:195], v[24:27]
	v_mfma_f32_16x16x32_bf16 v[16:19], v[168:171], v[200:203], v[16:19]
	v_mfma_f32_16x16x32_bf16 v[8:11], v[176:179], v[200:203], v[8:11]
	v_mfma_f32_16x16x32_bf16 v[4:7], v[168:171], v[208:211], v[4:7]
	v_mfma_f32_16x16x32_bf16 v[0:3], v[176:179], v[208:211], v[0:3]
	v_mfma_f32_16x16x32_bf16 v[48:51], v[172:175], v[188:191], v[48:51]
	v_mfma_f32_16x16x32_bf16 v[40:43], v[180:183], v[188:191], v[40:43]
	v_mfma_f32_16x16x32_bf16 v[32:35], v[172:175], v[196:199], v[32:35]
	v_mfma_f32_16x16x32_bf16 v[24:27], v[180:183], v[196:199], v[24:27]
	v_mfma_f32_16x16x32_bf16 v[16:19], v[172:175], v[204:207], v[16:19]
	v_mfma_f32_16x16x32_bf16 v[8:11], v[180:183], v[204:207], v[8:11]
	v_mfma_f32_16x16x32_bf16 v[4:7], v[172:175], v[212:215], v[4:7]
	v_mfma_f32_16x16x32_bf16 v[0:3], v[180:183], v[212:215], v[0:3]
	s_setprio 0
	s_barrier
	s_add_i32 s58, 0, 0x18000
	s_add_i32 s59, 0, 0x1c000
	v_add_u32_e32 v164, s58, v148
	v_add_u32_e32 v180, s59, v148
	ds_read_b128 v[152:155], v164
	ds_read_b128 v[156:159], v164 offset:1024
	ds_read_b128 v[160:163], v164 offset:2048
	ds_read_b128 v[164:167], v164 offset:3072
	ds_read_b128 v[168:171], v180
	ds_read_b128 v[172:175], v180 offset:1024
	ds_read_b128 v[176:179], v180 offset:2048
	ds_read_b128 v[180:183], v180 offset:3072
	s_add_u32 s28, s28, 0x100000
	s_addc_u32 s29, s29, 0
	s_mov_b32 m0, s36
	ds_read_b128 v[184:187], v151 offset:32768
	ds_read_b128 v[188:191], v151 offset:33792
	ds_read_b128 v[192:195], v151 offset:34816
	ds_read_b128 v[196:199], v151 offset:35840
	ds_read_b128 v[200:203], v151 offset:36864
	ds_read_b128 v[204:207], v151 offset:37888
	ds_read_b128 v[208:211], v151 offset:38912
	ds_read_b128 v[212:215], v151 offset:39936
	global_load_lds_dwordx4 v128, s[28:29]
	s_mov_b32 m0, s37
	s_nop 0
	global_load_lds_dwordx4 v132, s[28:29]
	s_waitcnt vmcnt(8)
	s_waitcnt lgkmcnt(0)
	s_barrier
	s_setprio 1
	s_waitcnt lgkmcnt(0)
	v_mfma_f32_16x16x32_bf16 v[124:127], v[152:155], v[184:187], v[124:127]
	v_mfma_f32_16x16x32_bf16 v[120:123], v[160:163], v[184:187], v[120:123]
	v_mfma_f32_16x16x32_bf16 v[116:119], v[152:155], v[192:195], v[116:119]
	v_mfma_f32_16x16x32_bf16 v[108:111], v[160:163], v[192:195], v[108:111]
	v_mfma_f32_16x16x32_bf16 v[100:103], v[152:155], v[200:203], v[100:103]
	v_mfma_f32_16x16x32_bf16 v[92:95], v[160:163], v[200:203], v[92:95]
	v_mfma_f32_16x16x32_bf16 v[84:87], v[152:155], v[208:211], v[84:87]
	v_mfma_f32_16x16x32_bf16 v[76:79], v[160:163], v[208:211], v[76:79]
	v_mfma_f32_16x16x32_bf16 v[124:127], v[156:159], v[188:191], v[124:127]
	v_mfma_f32_16x16x32_bf16 v[120:123], v[164:167], v[188:191], v[120:123]
	v_mfma_f32_16x16x32_bf16 v[116:119], v[156:159], v[196:199], v[116:119]
	v_mfma_f32_16x16x32_bf16 v[108:111], v[164:167], v[196:199], v[108:111]
	v_mfma_f32_16x16x32_bf16 v[100:103], v[156:159], v[204:207], v[100:103]
	v_mfma_f32_16x16x32_bf16 v[92:95], v[164:167], v[204:207], v[92:95]
	v_mfma_f32_16x16x32_bf16 v[84:87], v[156:159], v[212:215], v[84:87]
	v_mfma_f32_16x16x32_bf16 v[76:79], v[164:167], v[212:215], v[76:79]
	s_setprio 0
	s_setprio 1
	v_mfma_f32_16x16x32_bf16 v[112:115], v[168:171], v[184:187], v[112:115]
	v_mfma_f32_16x16x32_bf16 v[104:107], v[176:179], v[184:187], v[104:107]
	v_mfma_f32_16x16x32_bf16 v[96:99], v[168:171], v[192:195], v[96:99]
	v_mfma_f32_16x16x32_bf16 v[88:91], v[176:179], v[192:195], v[88:91]
	v_mfma_f32_16x16x32_bf16 v[80:83], v[168:171], v[200:203], v[80:83]
	v_mfma_f32_16x16x32_bf16 v[72:75], v[176:179], v[200:203], v[72:75]
	v_mfma_f32_16x16x32_bf16 v[68:71], v[168:171], v[208:211], v[68:71]
	v_mfma_f32_16x16x32_bf16 v[64:67], v[176:179], v[208:211], v[64:67]
	v_mfma_f32_16x16x32_bf16 v[112:115], v[172:175], v[188:191], v[112:115]
	v_mfma_f32_16x16x32_bf16 v[104:107], v[180:183], v[188:191], v[104:107]
	v_mfma_f32_16x16x32_bf16 v[96:99], v[172:175], v[196:199], v[96:99]
	v_mfma_f32_16x16x32_bf16 v[88:91], v[180:183], v[196:199], v[88:91]
	v_mfma_f32_16x16x32_bf16 v[80:83], v[172:175], v[204:207], v[80:83]
	v_mfma_f32_16x16x32_bf16 v[72:75], v[180:183], v[204:207], v[72:75]
	v_mfma_f32_16x16x32_bf16 v[68:71], v[172:175], v[212:215], v[68:71]
	v_mfma_f32_16x16x32_bf16 v[64:67], v[180:183], v[212:215], v[64:67]
	s_setprio 0
	s_barrier
	s_add_i32 s28, s58, s31
	s_mov_b32 m0, s28
	ds_read_b128 v[184:187], v151 offset:49152
	ds_read_b128 v[188:191], v151 offset:50176
	ds_read_b128 v[192:195], v151 offset:51200
	ds_read_b128 v[196:199], v151 offset:52224
	ds_read_b128 v[200:203], v151 offset:53248
	ds_read_b128 v[204:207], v151 offset:54272
	ds_read_b128 v[208:211], v151 offset:55296
	ds_read_b128 v[212:215], v151 offset:56320
	global_load_lds_dwordx4 v130, s[62:63]
	s_add_i32 m0, s28, 0x2000
	s_add_u32 s26, s26, 0x100080
	s_addc_u32 s27, s27, 0
	s_add_i32 s28, s59, s31
	global_load_lds_dwordx4 v134, s[62:63]
	s_mov_b32 m0, s28
	s_nop 0
	global_load_lds_dwordx4 v130, s[26:27]
	s_add_i32 m0, s28, 0x2000
	s_nop 0
	global_load_lds_dwordx4 v134, s[26:27]
	s_mov_b32 m0, s40
	s_nop 0
	global_load_lds_dwordx4 v128, s[64:65]
	s_mov_b32 m0, s41
	s_nop 0
	global_load_lds_dwordx4 v132, s[64:65]
	s_waitcnt vmcnt(8)
	s_waitcnt lgkmcnt(0)
	s_barrier
	s_setprio 1
	s_waitcnt lgkmcnt(0)
	v_mfma_f32_16x16x32_bf16 v[60:63], v[152:155], v[184:187], v[60:63]
	v_mfma_f32_16x16x32_bf16 v[56:59], v[160:163], v[184:187], v[56:59]
	v_mfma_f32_16x16x32_bf16 v[52:55], v[152:155], v[192:195], v[52:55]
	v_mfma_f32_16x16x32_bf16 v[44:47], v[160:163], v[192:195], v[44:47]
	v_mfma_f32_16x16x32_bf16 v[36:39], v[152:155], v[200:203], v[36:39]
	v_mfma_f32_16x16x32_bf16 v[28:31], v[160:163], v[200:203], v[28:31]
	v_mfma_f32_16x16x32_bf16 v[20:23], v[152:155], v[208:211], v[20:23]
	v_mfma_f32_16x16x32_bf16 v[12:15], v[160:163], v[208:211], v[12:15]
	v_mfma_f32_16x16x32_bf16 v[60:63], v[156:159], v[188:191], v[60:63]
	v_mfma_f32_16x16x32_bf16 v[56:59], v[164:167], v[188:191], v[56:59]
	v_mfma_f32_16x16x32_bf16 v[52:55], v[156:159], v[196:199], v[52:55]
	v_mfma_f32_16x16x32_bf16 v[44:47], v[164:167], v[196:199], v[44:47]
	v_mfma_f32_16x16x32_bf16 v[36:39], v[156:159], v[204:207], v[36:39]
	v_mfma_f32_16x16x32_bf16 v[28:31], v[164:167], v[204:207], v[28:31]
	v_mfma_f32_16x16x32_bf16 v[20:23], v[156:159], v[212:215], v[20:23]
	v_mfma_f32_16x16x32_bf16 v[12:15], v[164:167], v[212:215], v[12:15]
	s_setprio 0
	s_setprio 1
	v_mfma_f32_16x16x32_bf16 v[48:51], v[168:171], v[184:187], v[48:51]
	v_mfma_f32_16x16x32_bf16 v[40:43], v[176:179], v[184:187], v[40:43]
	v_mfma_f32_16x16x32_bf16 v[32:35], v[168:171], v[192:195], v[32:35]
	v_mfma_f32_16x16x32_bf16 v[24:27], v[176:179], v[192:195], v[24:27]
	v_mfma_f32_16x16x32_bf16 v[16:19], v[168:171], v[200:203], v[16:19]
	v_mfma_f32_16x16x32_bf16 v[8:11], v[176:179], v[200:203], v[8:11]
	v_mfma_f32_16x16x32_bf16 v[4:7], v[168:171], v[208:211], v[4:7]
	v_mfma_f32_16x16x32_bf16 v[0:3], v[176:179], v[208:211], v[0:3]
	v_mfma_f32_16x16x32_bf16 v[48:51], v[172:175], v[188:191], v[48:51]
	v_mfma_f32_16x16x32_bf16 v[40:43], v[180:183], v[188:191], v[40:43]
	v_mfma_f32_16x16x32_bf16 v[32:35], v[172:175], v[196:199], v[32:35]
	v_mfma_f32_16x16x32_bf16 v[24:27], v[180:183], v[196:199], v[24:27]
	v_mfma_f32_16x16x32_bf16 v[16:19], v[172:175], v[204:207], v[16:19]
	v_mfma_f32_16x16x32_bf16 v[8:11], v[180:183], v[204:207], v[8:11]
	v_mfma_f32_16x16x32_bf16 v[4:7], v[172:175], v[212:215], v[4:7]
	v_mfma_f32_16x16x32_bf16 v[0:3], v[180:183], v[212:215], v[0:3]
	s_setprio 0
	s_barrier
	s_add_i32 s57, s57, 2
	s_add_u32 s24, s24, 0x100
	s_addc_u32 s25, s25, 0
	s_add_u32 s55, s55, 0x100
	s_addc_u32 s56, s56, 0
	s_cmp_gt_u32 s57, 61
	s_cbranch_scc0 .LBB6_20
	s_mov_b64 vcc, s[0:1]
	s_cbranch_vccz .LBB6_23
	s_barrier

	.amdhsa_kernel _Z10fwd_kernelILi6ELi7EEv4Args
		.amdhsa_group_segment_fixed_size 0
		.amdhsa_private_segment_fixed_size 0
		.amdhsa_kernarg_size 488
		.amdhsa_user_sgpr_count 2
		.amdhsa_user_sgpr_dispatch_ptr 0
		.amdhsa_user_sgpr_queue_ptr 0
		.amdhsa_user_sgpr_kernarg_segment_ptr 1
		.amdhsa_user_sgpr_dispatch_id 0
		.amdhsa_user_sgpr_kernarg_preload_length 0
		.amdhsa_user_sgpr_kernarg_preload_offset 0
		.amdhsa_user_sgpr_private_segment_size 0
		.amdhsa_uses_dynamic_stack 0
		.amdhsa_enable_private_segment 0
		.amdhsa_system_sgpr_workgroup_id_x 1
		.amdhsa_system_sgpr_workgroup_id_y 0
		.amdhsa_system_sgpr_workgroup_id_z 0
		.amdhsa_system_sgpr_workgroup_info 0
		.amdhsa_system_vgpr_workitem_id 0
		.amdhsa_next_free_vgpr 240
		.amdhsa_next_free_sgpr 70
		.amdhsa_accum_offset 240
		.amdhsa_reserve_vcc 1
		.amdhsa_float_round_mode_32 0
		.amdhsa_float_round_mode_16_64 0
		.amdhsa_float_denorm_mode_32 3
		.amdhsa_float_denorm_mode_16_64 3
		.amdhsa_dx10_clamp 1
		.amdhsa_ieee_mode 1
		.amdhsa_fp16_overflow 0
		.amdhsa_tg_split 0
		.amdhsa_exception_fp_ieee_invalid_op 0
		.amdhsa_exception_fp_denorm_src 0
		.amdhsa_exception_fp_ieee_div_zero 0
		.amdhsa_exception_fp_ieee_overflow 0
		.amdhsa_exception_fp_ieee_underflow 0
		.amdhsa_exception_fp_ieee_inexact 0
		.amdhsa_exception_int_div_zero 0
	.end_amdhsa_kernel

.LBB8_11:
	s_ashr_i32 s19, s18, 31
	v_cmp_lt_i64_e32 vcc, s[0:1], v[144:145]
	s_lshl_b64 s[0:1], s[18:19], 19
	s_add_u32 s20, s33, s0
	s_addc_u32 s21, s36, s1
	s_and_b64 s[0:1], vcc, exec
	s_cselect_b32 s5, s21, s29
	s_cselect_b32 s19, s20, s28
	s_ashr_i32 s11, s10, 31
	s_lshl_b64 s[0:1], s[10:11], 19
	s_add_u32 s22, s37, s0
	s_addc_u32 s23, s38, s1
	s_and_b64 s[0:1], vcc, exec
	s_cselect_b32 s11, s23, s27
	s_cselect_b32 s25, s22, s26
	s_add_u32 s34, s26, 0x100
	s_addc_u32 s35, s27, 0
	s_add_u32 s26, s28, 0x40080
	s_addc_u32 s27, s29, 0
	s_mov_b32 s65, -2
	ds_read_b128 v[148:151], v153
	ds_read_b128 v[156:159], v153 offset:1024
	ds_read_b128 v[160:163], v153 offset:2048
	ds_read_b128 v[164:167], v153 offset:3072
	ds_read_b128 v[168:171], v154
	ds_read_b128 v[172:175], v154 offset:1024
	ds_read_b128 v[176:179], v154 offset:2048
	ds_read_b128 v[180:183], v154 offset:3072
	s_add_u32 s28, s26, 0xfffc0080
	s_addc_u32 s29, s27, -1
	s_cmp_eq_u32 s65, 12
	s_cselect_b32 s31, s5, s29
	s_cselect_b32 s30, s19, s28
	s_cselect_b32 s29, s11, s35
	s_cselect_b32 s28, s25, s34
	s_add_i32 m0, s40, 0xc000
	ds_read_b128 v[184:187], v155
	ds_read_b128 v[188:191], v155 offset:1024
	ds_read_b128 v[192:195], v155 offset:2048
	ds_read_b128 v[196:199], v155 offset:3072
	ds_read_b128 v[200:203], v155 offset:4096
	ds_read_b128 v[204:207], v155 offset:5120
	ds_read_b128 v[208:211], v155 offset:6144
	ds_read_b128 v[212:215], v155 offset:7168
	global_load_lds_dwordx4 v142, s[26:27]
	s_add_i32 m0, s40, 0xe000
	s_nop 0
	global_load_lds_dwordx4 v140, s[26:27]
	s_waitcnt vmcnt(8)
	s_waitcnt lgkmcnt(0)
	s_barrier
	s_setprio 1
	s_waitcnt lgkmcnt(0)
	v_mfma_f32_16x16x32_bf16 v[124:127], v[148:151], v[184:187], 0
	v_mfma_f32_16x16x32_bf16 v[120:123], v[160:163], v[184:187], 0
	v_mfma_f32_16x16x32_bf16 v[108:111], v[148:151], v[192:195], 0
	v_mfma_f32_16x16x32_bf16 v[104:107], v[160:163], v[192:195], 0
	v_mfma_f32_16x16x32_bf16 v[92:95], v[148:151], v[200:203], 0
	v_mfma_f32_16x16x32_bf16 v[88:91], v[160:163], v[200:203], 0
	v_mfma_f32_16x16x32_bf16 v[76:79], v[148:151], v[208:211], 0
	v_mfma_f32_16x16x32_bf16 v[72:75], v[160:163], v[208:211], 0
	v_mfma_f32_16x16x32_bf16 v[124:127], v[156:159], v[188:191], v[124:127]
	v_mfma_f32_16x16x32_bf16 v[120:123], v[164:167], v[188:191], v[120:123]
	v_mfma_f32_16x16x32_bf16 v[108:111], v[156:159], v[196:199], v[108:111]
	v_mfma_f32_16x16x32_bf16 v[104:107], v[164:167], v[196:199], v[104:107]
	v_mfma_f32_16x16x32_bf16 v[92:95], v[156:159], v[204:207], v[92:95]
	v_mfma_f32_16x16x32_bf16 v[88:91], v[164:167], v[204:207], v[88:91]
	v_mfma_f32_16x16x32_bf16 v[76:79], v[156:159], v[212:215], v[76:79]
	v_mfma_f32_16x16x32_bf16 v[72:75], v[164:167], v[212:215], v[72:75]
	s_setprio 0
	s_setprio 1
	v_mfma_f32_16x16x32_bf16 v[116:119], v[168:171], v[184:187], 0
	v_mfma_f32_16x16x32_bf16 v[112:115], v[176:179], v[184:187], 0
	v_mfma_f32_16x16x32_bf16 v[100:103], v[168:171], v[192:195], 0
	v_mfma_f32_16x16x32_bf16 v[96:99], v[176:179], v[192:195], 0
	v_mfma_f32_16x16x32_bf16 v[84:87], v[168:171], v[200:203], 0
	v_mfma_f32_16x16x32_bf16 v[80:83], v[176:179], v[200:203], 0
	v_mfma_f32_16x16x32_bf16 v[68:71], v[168:171], v[208:211], 0
	v_mfma_f32_16x16x32_bf16 v[64:67], v[176:179], v[208:211], 0
	v_mfma_f32_16x16x32_bf16 v[116:119], v[172:175], v[188:191], v[116:119]
	v_mfma_f32_16x16x32_bf16 v[112:115], v[180:183], v[188:191], v[112:115]
	v_mfma_f32_16x16x32_bf16 v[100:103], v[172:175], v[196:199], v[100:103]
	v_mfma_f32_16x16x32_bf16 v[96:99], v[180:183], v[196:199], v[96:99]
	v_mfma_f32_16x16x32_bf16 v[84:87], v[172:175], v[204:207], v[84:87]
	v_mfma_f32_16x16x32_bf16 v[80:83], v[180:183], v[204:207], v[80:83]
	v_mfma_f32_16x16x32_bf16 v[68:71], v[172:175], v[212:215], v[68:71]
	v_mfma_f32_16x16x32_bf16 v[64:67], v[180:183], v[212:215], v[64:67]
	s_setprio 0
	s_barrier
	s_add_i32 s66, s52, s39
	s_add_u32 s70, s28, 0x80
	s_addc_u32 s71, s29, 0
	s_mov_b32 m0, s66
	ds_read_b128 v[184:187], v155 offset:16384
	ds_read_b128 v[188:191], v155 offset:17408
	ds_read_b128 v[192:195], v155 offset:18432
	ds_read_b128 v[196:199], v155 offset:19456
	ds_read_b128 v[200:203], v155 offset:20480
	ds_read_b128 v[204:207], v155 offset:21504
	ds_read_b128 v[208:211], v155 offset:22528
	ds_read_b128 v[212:215], v155 offset:23552
	global_load_lds_dwordx4 v130, s[28:29]
	s_add_i32 m0, s66, 0x2000
	s_add_u32 s66, s28, 0x40000
	s_addc_u32 s67, s29, 0
	s_add_i32 s68, s53, s39
	global_load_lds_dwordx4 v134, s[28:29]
	s_mov_b32 m0, s68
	s_add_u32 s72, s30, 0x80
	s_addc_u32 s73, s31, 0
	global_load_lds_dwordx4 v130, s[66:67]
	s_add_i32 m0, s68, 0x2000
	s_nop 0
	global_load_lds_dwordx4 v134, s[66:67]
	s_mov_b32 m0, s40
	s_nop 0
	global_load_lds_dwordx4 v128, s[30:31]
	s_mov_b32 m0, s41
	s_nop 0
	global_load_lds_dwordx4 v132, s[30:31]
	s_waitcnt vmcnt(8)
	s_waitcnt lgkmcnt(0)
	s_barrier
	s_setprio 1
	s_waitcnt lgkmcnt(0)
	v_mfma_f32_16x16x32_bf16 v[60:63], v[148:151], v[184:187], 0
	v_mfma_f32_16x16x32_bf16 v[56:59], v[160:163], v[184:187], 0
	v_mfma_f32_16x16x32_bf16 v[44:47], v[148:151], v[192:195], 0
	v_mfma_f32_16x16x32_bf16 v[40:43], v[160:163], v[192:195], 0
	v_mfma_f32_16x16x32_bf16 v[28:31], v[148:151], v[200:203], 0
	v_mfma_f32_16x16x32_bf16 v[24:27], v[160:163], v[200:203], 0
	v_mfma_f32_16x16x32_bf16 v[12:15], v[148:151], v[208:211], 0
	v_mfma_f32_16x16x32_bf16 v[8:11], v[160:163], v[208:211], 0
	v_mfma_f32_16x16x32_bf16 v[60:63], v[156:159], v[188:191], v[60:63]
	v_mfma_f32_16x16x32_bf16 v[56:59], v[164:167], v[188:191], v[56:59]
	v_mfma_f32_16x16x32_bf16 v[44:47], v[156:159], v[196:199], v[44:47]
	v_mfma_f32_16x16x32_bf16 v[40:43], v[164:167], v[196:199], v[40:43]
	v_mfma_f32_16x16x32_bf16 v[28:31], v[156:159], v[204:207], v[28:31]
	v_mfma_f32_16x16x32_bf16 v[24:27], v[164:167], v[204:207], v[24:27]
	v_mfma_f32_16x16x32_bf16 v[12:15], v[156:159], v[212:215], v[12:15]
	v_mfma_f32_16x16x32_bf16 v[8:11], v[164:167], v[212:215], v[8:11]
	s_setprio 0
	s_setprio 1
	v_mfma_f32_16x16x32_bf16 v[52:55], v[168:171], v[184:187], 0
	v_mfma_f32_16x16x32_bf16 v[48:51], v[176:179], v[184:187], 0
	v_mfma_f32_16x16x32_bf16 v[36:39], v[168:171], v[192:195], 0
	v_mfma_f32_16x16x32_bf16 v[32:35], v[176:179], v[192:195], 0
	v_mfma_f32_16x16x32_bf16 v[20:23], v[168:171], v[200:203], 0
	v_mfma_f32_16x16x32_bf16 v[16:19], v[176:179], v[200:203], 0
	v_mfma_f32_16x16x32_bf16 v[4:7], v[168:171], v[208:211], 0
	v_mfma_f32_16x16x32_bf16 v[0:3], v[176:179], v[208:211], 0
	v_mfma_f32_16x16x32_bf16 v[52:55], v[172:175], v[188:191], v[52:55]
	v_mfma_f32_16x16x32_bf16 v[48:51], v[180:183], v[188:191], v[48:51]
	v_mfma_f32_16x16x32_bf16 v[36:39], v[172:175], v[196:199], v[36:39]
	v_mfma_f32_16x16x32_bf16 v[32:35], v[180:183], v[196:199], v[32:35]
	v_mfma_f32_16x16x32_bf16 v[20:23], v[172:175], v[204:207], v[20:23]
	v_mfma_f32_16x16x32_bf16 v[16:19], v[180:183], v[204:207], v[16:19]
	v_mfma_f32_16x16x32_bf16 v[4:7], v[172:175], v[212:215], v[4:7]
	v_mfma_f32_16x16x32_bf16 v[0:3], v[180:183], v[212:215], v[0:3]
	s_setprio 0
	s_barrier
	s_add_i32 s66, 0, 0x18000
	s_add_i32 s67, 0, 0x1c000
	v_add_u32_e32 v164, s66, v152
	v_add_u32_e32 v180, s67, v152
	ds_read_b128 v[148:151], v164
	ds_read_b128 v[156:159], v164 offset:1024
	ds_read_b128 v[160:163], v164 offset:2048
	ds_read_b128 v[164:167], v164 offset:3072
	ds_read_b128 v[168:171], v180
	ds_read_b128 v[172:175], v180 offset:1024
	ds_read_b128 v[176:179], v180 offset:2048
	ds_read_b128 v[180:183], v180 offset:3072
	s_add_u32 s30, s30, 0x40000
	s_addc_u32 s31, s31, 0
	s_mov_b32 m0, s42
	ds_read_b128 v[184:187], v155 offset:32768
	ds_read_b128 v[188:191], v155 offset:33792
	ds_read_b128 v[192:195], v155 offset:34816
	ds_read_b128 v[196:199], v155 offset:35840
	ds_read_b128 v[200:203], v155 offset:36864
	ds_read_b128 v[204:207], v155 offset:37888
	ds_read_b128 v[208:211], v155 offset:38912
	ds_read_b128 v[212:215], v155 offset:39936
	global_load_lds_dwordx4 v128, s[30:31]
	s_mov_b32 m0, s43
	s_nop 0
	global_load_lds_dwordx4 v132, s[30:31]
	s_waitcnt vmcnt(8)
	s_waitcnt lgkmcnt(0)
	s_barrier
	s_setprio 1
	s_waitcnt lgkmcnt(0)
	v_mfma_f32_16x16x32_bf16 v[124:127], v[148:151], v[184:187], v[124:127]
	v_mfma_f32_16x16x32_bf16 v[120:123], v[160:163], v[184:187], v[120:123]
	v_mfma_f32_16x16x32_bf16 v[108:111], v[148:151], v[192:195], v[108:111]
	v_mfma_f32_16x16x32_bf16 v[104:107], v[160:163], v[192:195], v[104:107]
	v_mfma_f32_16x16x32_bf16 v[92:95], v[148:151], v[200:203], v[92:95]
	v_mfma_f32_16x16x32_bf16 v[88:91], v[160:163], v[200:203], v[88:91]
	v_mfma_f32_16x16x32_bf16 v[76:79], v[148:151], v[208:211], v[76:79]
	v_mfma_f32_16x16x32_bf16 v[72:75], v[160:163], v[208:211], v[72:75]
	v_mfma_f32_16x16x32_bf16 v[124:127], v[156:159], v[188:191], v[124:127]
	v_mfma_f32_16x16x32_bf16 v[120:123], v[164:167], v[188:191], v[120:123]
	v_mfma_f32_16x16x32_bf16 v[108:111], v[156:159], v[196:199], v[108:111]
	v_mfma_f32_16x16x32_bf16 v[104:107], v[164:167], v[196:199], v[104:107]
	v_mfma_f32_16x16x32_bf16 v[92:95], v[156:159], v[204:207], v[92:95]
	v_mfma_f32_16x16x32_bf16 v[88:91], v[164:167], v[204:207], v[88:91]
	v_mfma_f32_16x16x32_bf16 v[76:79], v[156:159], v[212:215], v[76:79]
	v_mfma_f32_16x16x32_bf16 v[72:75], v[164:167], v[212:215], v[72:75]
	s_setprio 0
	s_setprio 1
	v_mfma_f32_16x16x32_bf16 v[116:119], v[168:171], v[184:187], v[116:119]
	v_mfma_f32_16x16x32_bf16 v[112:115], v[176:179], v[184:187], v[112:115]
	v_mfma_f32_16x16x32_bf16 v[100:103], v[168:171], v[192:195], v[100:103]
	v_mfma_f32_16x16x32_bf16 v[96:99], v[176:179], v[192:195], v[96:99]
	v_mfma_f32_16x16x32_bf16 v[84:87], v[168:171], v[200:203], v[84:87]
	v_mfma_f32_16x16x32_bf16 v[80:83], v[176:179], v[200:203], v[80:83]
	v_mfma_f32_16x16x32_bf16 v[68:71], v[168:171], v[208:211], v[68:71]
	v_mfma_f32_16x16x32_bf16 v[64:67], v[176:179], v[208:211], v[64:67]
	v_mfma_f32_16x16x32_bf16 v[116:119], v[172:175], v[188:191], v[116:119]
	v_mfma_f32_16x16x32_bf16 v[112:115], v[180:183], v[188:191], v[112:115]
	v_mfma_f32_16x16x32_bf16 v[100:103], v[172:175], v[196:199], v[100:103]
	v_mfma_f32_16x16x32_bf16 v[96:99], v[180:183], v[196:199], v[96:99]
	v_mfma_f32_16x16x32_bf16 v[84:87], v[172:175], v[204:207], v[84:87]
	v_mfma_f32_16x16x32_bf16 v[80:83], v[180:183], v[204:207], v[80:83]
	v_mfma_f32_16x16x32_bf16 v[68:71], v[172:175], v[212:215], v[68:71]
	v_mfma_f32_16x16x32_bf16 v[64:67], v[180:183], v[212:215], v[64:67]
	s_setprio 0
	s_barrier
	s_add_i32 s30, s66, s39
	s_mov_b32 m0, s30
	ds_read_b128 v[184:187], v155 offset:49152
	ds_read_b128 v[188:191], v155 offset:50176
	ds_read_b128 v[192:195], v155 offset:51200
	ds_read_b128 v[196:199], v155 offset:52224
	ds_read_b128 v[200:203], v155 offset:53248
	ds_read_b128 v[204:207], v155 offset:54272
	ds_read_b128 v[208:211], v155 offset:55296
	ds_read_b128 v[212:215], v155 offset:56320
	global_load_lds_dwordx4 v130, s[70:71]
	s_add_i32 m0, s30, 0x2000
	s_add_u32 s28, s28, 0x40080
	s_addc_u32 s29, s29, 0
	s_add_i32 s30, s67, s39
	global_load_lds_dwordx4 v134, s[70:71]
	s_mov_b32 m0, s30
	s_nop 0
	global_load_lds_dwordx4 v130, s[28:29]
	s_add_i32 m0, s30, 0x2000
	s_nop 0
	global_load_lds_dwordx4 v134, s[28:29]
	s_mov_b32 m0, s45
	s_nop 0
	global_load_lds_dwordx4 v128, s[72:73]
	s_mov_b32 m0, s46
	s_nop 0
	global_load_lds_dwordx4 v132, s[72:73]
	s_waitcnt vmcnt(8)
	s_waitcnt lgkmcnt(0)
	s_barrier
	s_setprio 1
	s_waitcnt lgkmcnt(0)
	v_mfma_f32_16x16x32_bf16 v[60:63], v[148:151], v[184:187], v[60:63]
	v_mfma_f32_16x16x32_bf16 v[56:59], v[160:163], v[184:187], v[56:59]
	v_mfma_f32_16x16x32_bf16 v[44:47], v[148:151], v[192:195], v[44:47]
	v_mfma_f32_16x16x32_bf16 v[40:43], v[160:163], v[192:195], v[40:43]
	v_mfma_f32_16x16x32_bf16 v[28:31], v[148:151], v[200:203], v[28:31]
	v_mfma_f32_16x16x32_bf16 v[24:27], v[160:163], v[200:203], v[24:27]
	v_mfma_f32_16x16x32_bf16 v[12:15], v[148:151], v[208:211], v[12:15]
	v_mfma_f32_16x16x32_bf16 v[8:11], v[160:163], v[208:211], v[8:11]
	v_mfma_f32_16x16x32_bf16 v[60:63], v[156:159], v[188:191], v[60:63]
	v_mfma_f32_16x16x32_bf16 v[56:59], v[164:167], v[188:191], v[56:59]
	v_mfma_f32_16x16x32_bf16 v[44:47], v[156:159], v[196:199], v[44:47]
	v_mfma_f32_16x16x32_bf16 v[40:43], v[164:167], v[196:199], v[40:43]
	v_mfma_f32_16x16x32_bf16 v[28:31], v[156:159], v[204:207], v[28:31]
	v_mfma_f32_16x16x32_bf16 v[24:27], v[164:167], v[204:207], v[24:27]
	v_mfma_f32_16x16x32_bf16 v[12:15], v[156:159], v[212:215], v[12:15]
	v_mfma_f32_16x16x32_bf16 v[8:11], v[164:167], v[212:215], v[8:11]
	s_setprio 0
	s_setprio 1
	v_mfma_f32_16x16x32_bf16 v[52:55], v[168:171], v[184:187], v[52:55]
	v_mfma_f32_16x16x32_bf16 v[48:51], v[176:179], v[184:187], v[48:51]
	v_mfma_f32_16x16x32_bf16 v[36:39], v[168:171], v[192:195], v[36:39]
	v_mfma_f32_16x16x32_bf16 v[32:35], v[176:179], v[192:195], v[32:35]
	v_mfma_f32_16x16x32_bf16 v[20:23], v[168:171], v[200:203], v[20:23]
	v_mfma_f32_16x16x32_bf16 v[16:19], v[176:179], v[200:203], v[16:19]
	v_mfma_f32_16x16x32_bf16 v[4:7], v[168:171], v[208:211], v[4:7]
	v_mfma_f32_16x16x32_bf16 v[0:3], v[176:179], v[208:211], v[0:3]
	v_mfma_f32_16x16x32_bf16 v[52:55], v[172:175], v[188:191], v[52:55]
	v_mfma_f32_16x16x32_bf16 v[48:51], v[180:183], v[188:191], v[48:51]
	v_mfma_f32_16x16x32_bf16 v[36:39], v[172:175], v[196:199], v[36:39]
	v_mfma_f32_16x16x32_bf16 v[32:35], v[180:183], v[196:199], v[32:35]
	v_mfma_f32_16x16x32_bf16 v[20:23], v[172:175], v[204:207], v[20:23]
	v_mfma_f32_16x16x32_bf16 v[16:19], v[180:183], v[204:207], v[16:19]
	v_mfma_f32_16x16x32_bf16 v[4:7], v[172:175], v[212:215], v[4:7]
	v_mfma_f32_16x16x32_bf16 v[0:3], v[180:183], v[212:215], v[0:3]
	s_setprio 0
	s_barrier
	s_add_i32 s65, s65, 2
	s_add_u32 s34, s34, 0x100
	s_addc_u32 s35, s35, 0
	s_add_u32 s26, s26, 0x100
	s_addc_u32 s27, s27, 0
	s_cmp_lt_u32 s65, 14
.LBB8_12:
	ds_read_b128 v[148:151], v153
	ds_read_b128 v[156:159], v153 offset:1024
	ds_read_b128 v[160:163], v153 offset:2048
	ds_read_b128 v[164:167], v153 offset:3072
	ds_read_b128 v[168:171], v154
	ds_read_b128 v[172:175], v154 offset:1024
	ds_read_b128 v[176:179], v154 offset:2048
	ds_read_b128 v[180:183], v154 offset:3072
	s_add_u32 s28, s26, 0xfffc0080
	s_addc_u32 s29, s27, -1
	s_cmp_eq_u32 s65, 12
	s_cselect_b32 s31, s5, s29
	s_cselect_b32 s30, s19, s28
	s_cselect_b32 s29, s11, s35
	s_cselect_b32 s28, s25, s34
	s_add_i32 m0, s40, 0xc000
	ds_read_b128 v[184:187], v155
	ds_read_b128 v[188:191], v155 offset:1024
	ds_read_b128 v[192:195], v155 offset:2048
	ds_read_b128 v[196:199], v155 offset:3072
	ds_read_b128 v[200:203], v155 offset:4096
	ds_read_b128 v[204:207], v155 offset:5120
	ds_read_b128 v[208:211], v155 offset:6144
	ds_read_b128 v[212:215], v155 offset:7168
	global_load_lds_dwordx4 v142, s[26:27]
	s_add_i32 m0, s40, 0xe000
	s_nop 0
	global_load_lds_dwordx4 v140, s[26:27]
	s_waitcnt vmcnt(8)
	s_waitcnt lgkmcnt(0)
	s_barrier
	s_setprio 1
	s_waitcnt lgkmcnt(0)
	v_mfma_f32_16x16x32_bf16 v[124:127], v[148:151], v[184:187], v[124:127]
	v_mfma_f32_16x16x32_bf16 v[120:123], v[160:163], v[184:187], v[120:123]
	v_mfma_f32_16x16x32_bf16 v[108:111], v[148:151], v[192:195], v[108:111]
	v_mfma_f32_16x16x32_bf16 v[104:107], v[160:163], v[192:195], v[104:107]
	v_mfma_f32_16x16x32_bf16 v[92:95], v[148:151], v[200:203], v[92:95]
	v_mfma_f32_16x16x32_bf16 v[88:91], v[160:163], v[200:203], v[88:91]
	v_mfma_f32_16x16x32_bf16 v[76:79], v[148:151], v[208:211], v[76:79]
	v_mfma_f32_16x16x32_bf16 v[72:75], v[160:163], v[208:211], v[72:75]
	v_mfma_f32_16x16x32_bf16 v[124:127], v[156:159], v[188:191], v[124:127]
	v_mfma_f32_16x16x32_bf16 v[120:123], v[164:167], v[188:191], v[120:123]
	v_mfma_f32_16x16x32_bf16 v[108:111], v[156:159], v[196:199], v[108:111]
	v_mfma_f32_16x16x32_bf16 v[104:107], v[164:167], v[196:199], v[104:107]
	v_mfma_f32_16x16x32_bf16 v[92:95], v[156:159], v[204:207], v[92:95]
	v_mfma_f32_16x16x32_bf16 v[88:91], v[164:167], v[204:207], v[88:91]
	v_mfma_f32_16x16x32_bf16 v[76:79], v[156:159], v[212:215], v[76:79]
	v_mfma_f32_16x16x32_bf16 v[72:75], v[164:167], v[212:215], v[72:75]
	s_setprio 0
	s_setprio 1
	v_mfma_f32_16x16x32_bf16 v[116:119], v[168:171], v[184:187], v[116:119]
	v_mfma_f32_16x16x32_bf16 v[112:115], v[176:179], v[184:187], v[112:115]
	v_mfma_f32_16x16x32_bf16 v[100:103], v[168:171], v[192:195], v[100:103]
	v_mfma_f32_16x16x32_bf16 v[96:99], v[176:179], v[192:195], v[96:99]
	v_mfma_f32_16x16x32_bf16 v[84:87], v[168:171], v[200:203], v[84:87]
	v_mfma_f32_16x16x32_bf16 v[80:83], v[176:179], v[200:203], v[80:83]
	v_mfma_f32_16x16x32_bf16 v[68:71], v[168:171], v[208:211], v[68:71]
	v_mfma_f32_16x16x32_bf16 v[64:67], v[176:179], v[208:211], v[64:67]
	v_mfma_f32_16x16x32_bf16 v[116:119], v[172:175], v[188:191], v[116:119]
	v_mfma_f32_16x16x32_bf16 v[112:115], v[180:183], v[188:191], v[112:115]
	v_mfma_f32_16x16x32_bf16 v[100:103], v[172:175], v[196:199], v[100:103]
	v_mfma_f32_16x16x32_bf16 v[96:99], v[180:183], v[196:199], v[96:99]
	v_mfma_f32_16x16x32_bf16 v[84:87], v[172:175], v[204:207], v[84:87]
	v_mfma_f32_16x16x32_bf16 v[80:83], v[180:183], v[204:207], v[80:83]
	v_mfma_f32_16x16x32_bf16 v[68:71], v[172:175], v[212:215], v[68:71]
	v_mfma_f32_16x16x32_bf16 v[64:67], v[180:183], v[212:215], v[64:67]
	s_setprio 0
	s_barrier
	s_add_i32 s66, s52, s39
	s_add_u32 s70, s28, 0x80
	s_addc_u32 s71, s29, 0
	s_mov_b32 m0, s66
	ds_read_b128 v[184:187], v155 offset:16384
	ds_read_b128 v[188:191], v155 offset:17408
	ds_read_b128 v[192:195], v155 offset:18432
	ds_read_b128 v[196:199], v155 offset:19456
	ds_read_b128 v[200:203], v155 offset:20480
	ds_read_b128 v[204:207], v155 offset:21504
	ds_read_b128 v[208:211], v155 offset:22528
	ds_read_b128 v[212:215], v155 offset:23552
	global_load_lds_dwordx4 v130, s[28:29]
	s_add_i32 m0, s66, 0x2000
	s_add_u32 s66, s28, 0x40000
	s_addc_u32 s67, s29, 0
	s_add_i32 s68, s53, s39
	global_load_lds_dwordx4 v134, s[28:29]
	s_mov_b32 m0, s68
	s_add_u32 s72, s30, 0x80
	s_addc_u32 s73, s31, 0
	global_load_lds_dwordx4 v130, s[66:67]
	s_add_i32 m0, s68, 0x2000
	s_nop 0
	global_load_lds_dwordx4 v134, s[66:67]
	s_mov_b32 m0, s40
	s_nop 0
	global_load_lds_dwordx4 v128, s[30:31]
	s_mov_b32 m0, s41
	s_nop 0
	global_load_lds_dwordx4 v132, s[30:31]
	s_waitcnt vmcnt(8)
	s_waitcnt lgkmcnt(0)
	s_barrier
	s_setprio 1
	s_waitcnt lgkmcnt(0)
	v_mfma_f32_16x16x32_bf16 v[60:63], v[148:151], v[184:187], v[60:63]
	v_mfma_f32_16x16x32_bf16 v[56:59], v[160:163], v[184:187], v[56:59]
	v_mfma_f32_16x16x32_bf16 v[44:47], v[148:151], v[192:195], v[44:47]
	v_mfma_f32_16x16x32_bf16 v[40:43], v[160:163], v[192:195], v[40:43]
	v_mfma_f32_16x16x32_bf16 v[28:31], v[148:151], v[200:203], v[28:31]
	v_mfma_f32_16x16x32_bf16 v[24:27], v[160:163], v[200:203], v[24:27]
	v_mfma_f32_16x16x32_bf16 v[12:15], v[148:151], v[208:211], v[12:15]
	v_mfma_f32_16x16x32_bf16 v[8:11], v[160:163], v[208:211], v[8:11]
	v_mfma_f32_16x16x32_bf16 v[60:63], v[156:159], v[188:191], v[60:63]
	v_mfma_f32_16x16x32_bf16 v[56:59], v[164:167], v[188:191], v[56:59]
	v_mfma_f32_16x16x32_bf16 v[44:47], v[156:159], v[196:199], v[44:47]
	v_mfma_f32_16x16x32_bf16 v[40:43], v[164:167], v[196:199], v[40:43]
	v_mfma_f32_16x16x32_bf16 v[28:31], v[156:159], v[204:207], v[28:31]
	v_mfma_f32_16x16x32_bf16 v[24:27], v[164:167], v[204:207], v[24:27]
	v_mfma_f32_16x16x32_bf16 v[12:15], v[156:159], v[212:215], v[12:15]
	v_mfma_f32_16x16x32_bf16 v[8:11], v[164:167], v[212:215], v[8:11]
	s_setprio 0
	s_setprio 1
	v_mfma_f32_16x16x32_bf16 v[52:55], v[168:171], v[184:187], v[52:55]
	v_mfma_f32_16x16x32_bf16 v[48:51], v[176:179], v[184:187], v[48:51]
	v_mfma_f32_16x16x32_bf16 v[36:39], v[168:171], v[192:195], v[36:39]
	v_mfma_f32_16x16x32_bf16 v[32:35], v[176:179], v[192:195], v[32:35]
	v_mfma_f32_16x16x32_bf16 v[20:23], v[168:171], v[200:203], v[20:23]
	v_mfma_f32_16x16x32_bf16 v[16:19], v[176:179], v[200:203], v[16:19]
	v_mfma_f32_16x16x32_bf16 v[4:7], v[168:171], v[208:211], v[4:7]
	v_mfma_f32_16x16x32_bf16 v[0:3], v[176:179], v[208:211], v[0:3]
	v_mfma_f32_16x16x32_bf16 v[52:55], v[172:175], v[188:191], v[52:55]
	v_mfma_f32_16x16x32_bf16 v[48:51], v[180:183], v[188:191], v[48:51]
	v_mfma_f32_16x16x32_bf16 v[36:39], v[172:175], v[196:199], v[36:39]
	v_mfma_f32_16x16x32_bf16 v[32:35], v[180:183], v[196:199], v[32:35]
	v_mfma_f32_16x16x32_bf16 v[20:23], v[172:175], v[204:207], v[20:23]
	v_mfma_f32_16x16x32_bf16 v[16:19], v[180:183], v[204:207], v[16:19]
	v_mfma_f32_16x16x32_bf16 v[4:7], v[172:175], v[212:215], v[4:7]
	v_mfma_f32_16x16x32_bf16 v[0:3], v[180:183], v[212:215], v[0:3]
	s_setprio 0
	s_barrier
	s_add_i32 s66, 0, 0x18000
	s_add_i32 s67, 0, 0x1c000
	v_add_u32_e32 v164, s66, v152
	v_add_u32_e32 v180, s67, v152
	ds_read_b128 v[148:151], v164
	ds_read_b128 v[156:159], v164 offset:1024
	ds_read_b128 v[160:163], v164 offset:2048
	ds_read_b128 v[164:167], v164 offset:3072
	ds_read_b128 v[168:171], v180
	ds_read_b128 v[172:175], v180 offset:1024
	ds_read_b128 v[176:179], v180 offset:2048
	ds_read_b128 v[180:183], v180 offset:3072
	s_add_u32 s30, s30, 0x40000
	s_addc_u32 s31, s31, 0
	s_mov_b32 m0, s42
	ds_read_b128 v[184:187], v155 offset:32768
	ds_read_b128 v[188:191], v155 offset:33792
	ds_read_b128 v[192:195], v155 offset:34816
	ds_read_b128 v[196:199], v155 offset:35840
	ds_read_b128 v[200:203], v155 offset:36864
	ds_read_b128 v[204:207], v155 offset:37888
	ds_read_b128 v[208:211], v155 offset:38912
	ds_read_b128 v[212:215], v155 offset:39936
	global_load_lds_dwordx4 v128, s[30:31]
	s_mov_b32 m0, s43
	s_nop 0
	global_load_lds_dwordx4 v132, s[30:31]
	s_waitcnt vmcnt(8)
	s_waitcnt lgkmcnt(0)
	s_barrier
	s_setprio 1
	s_waitcnt lgkmcnt(0)
	v_mfma_f32_16x16x32_bf16 v[124:127], v[148:151], v[184:187], v[124:127]
	v_mfma_f32_16x16x32_bf16 v[120:123], v[160:163], v[184:187], v[120:123]
	v_mfma_f32_16x16x32_bf16 v[108:111], v[148:151], v[192:195], v[108:111]
	v_mfma_f32_16x16x32_bf16 v[104:107], v[160:163], v[192:195], v[104:107]
	v_mfma_f32_16x16x32_bf16 v[92:95], v[148:151], v[200:203], v[92:95]
	v_mfma_f32_16x16x32_bf16 v[88:91], v[160:163], v[200:203], v[88:91]
	v_mfma_f32_16x16x32_bf16 v[76:79], v[148:151], v[208:211], v[76:79]
	v_mfma_f32_16x16x32_bf16 v[72:75], v[160:163], v[208:211], v[72:75]
	v_mfma_f32_16x16x32_bf16 v[124:127], v[156:159], v[188:191], v[124:127]
	v_mfma_f32_16x16x32_bf16 v[120:123], v[164:167], v[188:191], v[120:123]
	v_mfma_f32_16x16x32_bf16 v[108:111], v[156:159], v[196:199], v[108:111]
	v_mfma_f32_16x16x32_bf16 v[104:107], v[164:167], v[196:199], v[104:107]
	v_mfma_f32_16x16x32_bf16 v[92:95], v[156:159], v[204:207], v[92:95]
	v_mfma_f32_16x16x32_bf16 v[88:91], v[164:167], v[204:207], v[88:91]
	v_mfma_f32_16x16x32_bf16 v[76:79], v[156:159], v[212:215], v[76:79]
	v_mfma_f32_16x16x32_bf16 v[72:75], v[164:167], v[212:215], v[72:75]
	s_setprio 0
	s_setprio 1
	v_mfma_f32_16x16x32_bf16 v[116:119], v[168:171], v[184:187], v[116:119]
	v_mfma_f32_16x16x32_bf16 v[112:115], v[176:179], v[184:187], v[112:115]
	v_mfma_f32_16x16x32_bf16 v[100:103], v[168:171], v[192:195], v[100:103]
	v_mfma_f32_16x16x32_bf16 v[96:99], v[176:179], v[192:195], v[96:99]
	v_mfma_f32_16x16x32_bf16 v[84:87], v[168:171], v[200:203], v[84:87]
	v_mfma_f32_16x16x32_bf16 v[80:83], v[176:179], v[200:203], v[80:83]
	v_mfma_f32_16x16x32_bf16 v[68:71], v[168:171], v[208:211], v[68:71]
	v_mfma_f32_16x16x32_bf16 v[64:67], v[176:179], v[208:211], v[64:67]
	v_mfma_f32_16x16x32_bf16 v[116:119], v[172:175], v[188:191], v[116:119]
	v_mfma_f32_16x16x32_bf16 v[112:115], v[180:183], v[188:191], v[112:115]
	v_mfma_f32_16x16x32_bf16 v[100:103], v[172:175], v[196:199], v[100:103]
	v_mfma_f32_16x16x32_bf16 v[96:99], v[180:183], v[196:199], v[96:99]
	v_mfma_f32_16x16x32_bf16 v[84:87], v[172:175], v[204:207], v[84:87]
	v_mfma_f32_16x16x32_bf16 v[80:83], v[180:183], v[204:207], v[80:83]
	v_mfma_f32_16x16x32_bf16 v[68:71], v[172:175], v[212:215], v[68:71]
	v_mfma_f32_16x16x32_bf16 v[64:67], v[180:183], v[212:215], v[64:67]
	s_setprio 0
	s_barrier
	s_add_i32 s30, s66, s39
	s_mov_b32 m0, s30
	ds_read_b128 v[184:187], v155 offset:49152
	ds_read_b128 v[188:191], v155 offset:50176
	ds_read_b128 v[192:195], v155 offset:51200
	ds_read_b128 v[196:199], v155 offset:52224
	ds_read_b128 v[200:203], v155 offset:53248
	ds_read_b128 v[204:207], v155 offset:54272
	ds_read_b128 v[208:211], v155 offset:55296
	ds_read_b128 v[212:215], v155 offset:56320
	global_load_lds_dwordx4 v130, s[70:71]
	s_add_i32 m0, s30, 0x2000
	s_add_u32 s28, s28, 0x40080
	s_addc_u32 s29, s29, 0
	s_add_i32 s30, s67, s39
	global_load_lds_dwordx4 v134, s[70:71]
	s_mov_b32 m0, s30
	s_nop 0
	global_load_lds_dwordx4 v130, s[28:29]
	s_add_i32 m0, s30, 0x2000
	s_nop 0
	global_load_lds_dwordx4 v134, s[28:29]
	s_mov_b32 m0, s45
	s_nop 0
	global_load_lds_dwordx4 v128, s[72:73]
	s_mov_b32 m0, s46
	s_nop 0
	global_load_lds_dwordx4 v132, s[72:73]
	s_waitcnt vmcnt(8)
	s_waitcnt lgkmcnt(0)
	s_barrier
	s_setprio 1
	s_waitcnt lgkmcnt(0)
	v_mfma_f32_16x16x32_bf16 v[60:63], v[148:151], v[184:187], v[60:63]
	v_mfma_f32_16x16x32_bf16 v[56:59], v[160:163], v[184:187], v[56:59]
	v_mfma_f32_16x16x32_bf16 v[44:47], v[148:151], v[192:195], v[44:47]
	v_mfma_f32_16x16x32_bf16 v[40:43], v[160:163], v[192:195], v[40:43]
	v_mfma_f32_16x16x32_bf16 v[28:31], v[148:151], v[200:203], v[28:31]
	v_mfma_f32_16x16x32_bf16 v[24:27], v[160:163], v[200:203], v[24:27]
	v_mfma_f32_16x16x32_bf16 v[12:15], v[148:151], v[208:211], v[12:15]
	v_mfma_f32_16x16x32_bf16 v[8:11], v[160:163], v[208:211], v[8:11]
	v_mfma_f32_16x16x32_bf16 v[60:63], v[156:159], v[188:191], v[60:63]
	v_mfma_f32_16x16x32_bf16 v[56:59], v[164:167], v[188:191], v[56:59]
	v_mfma_f32_16x16x32_bf16 v[44:47], v[156:159], v[196:199], v[44:47]
	v_mfma_f32_16x16x32_bf16 v[40:43], v[164:167], v[196:199], v[40:43]
	v_mfma_f32_16x16x32_bf16 v[28:31], v[156:159], v[204:207], v[28:31]
	v_mfma_f32_16x16x32_bf16 v[24:27], v[164:167], v[204:207], v[24:27]
	v_mfma_f32_16x16x32_bf16 v[12:15], v[156:159], v[212:215], v[12:15]
	v_mfma_f32_16x16x32_bf16 v[8:11], v[164:167], v[212:215], v[8:11]
	s_setprio 0
	s_setprio 1
	v_mfma_f32_16x16x32_bf16 v[52:55], v[168:171], v[184:187], v[52:55]
	v_mfma_f32_16x16x32_bf16 v[48:51], v[176:179], v[184:187], v[48:51]
	v_mfma_f32_16x16x32_bf16 v[36:39], v[168:171], v[192:195], v[36:39]
	v_mfma_f32_16x16x32_bf16 v[32:35], v[176:179], v[192:195], v[32:35]
	v_mfma_f32_16x16x32_bf16 v[20:23], v[168:171], v[200:203], v[20:23]
	v_mfma_f32_16x16x32_bf16 v[16:19], v[176:179], v[200:203], v[16:19]
	v_mfma_f32_16x16x32_bf16 v[4:7], v[168:171], v[208:211], v[4:7]
	v_mfma_f32_16x16x32_bf16 v[0:3], v[176:179], v[208:211], v[0:3]
	v_mfma_f32_16x16x32_bf16 v[52:55], v[172:175], v[188:191], v[52:55]
	v_mfma_f32_16x16x32_bf16 v[48:51], v[180:183], v[188:191], v[48:51]
	v_mfma_f32_16x16x32_bf16 v[36:39], v[172:175], v[196:199], v[36:39]
	v_mfma_f32_16x16x32_bf16 v[32:35], v[180:183], v[196:199], v[32:35]
	v_mfma_f32_16x16x32_bf16 v[20:23], v[172:175], v[204:207], v[20:23]
	v_mfma_f32_16x16x32_bf16 v[16:19], v[180:183], v[204:207], v[16:19]
	v_mfma_f32_16x16x32_bf16 v[4:7], v[172:175], v[212:215], v[4:7]
	v_mfma_f32_16x16x32_bf16 v[0:3], v[180:183], v[212:215], v[0:3]
	s_setprio 0
	s_barrier
	s_add_i32 s65, s65, 2
	s_add_u32 s34, s34, 0x100
	s_addc_u32 s35, s35, 0
	s_add_u32 s26, s26, 0x100
	s_addc_u32 s27, s27, 0
	s_cmp_lt_u32 s65, 14
	s_cbranch_scc1 .LBB8_12
	s_andn2_b64 vcc, exec, s[16:17]
	s_cbranch_vccnz .LBB8_15
	s_barrier

	.amdhsa_kernel _Z10fwd_kernelILi8ELi9EEv4Args
		.amdhsa_group_segment_fixed_size 0
		.amdhsa_private_segment_fixed_size 0
		.amdhsa_kernarg_size 488
		.amdhsa_user_sgpr_count 2
		.amdhsa_user_sgpr_dispatch_ptr 0
		.amdhsa_user_sgpr_queue_ptr 0
		.amdhsa_user_sgpr_kernarg_segment_ptr 1
		.amdhsa_user_sgpr_dispatch_id 0
		.amdhsa_user_sgpr_kernarg_preload_length 0
		.amdhsa_user_sgpr_kernarg_preload_offset 0
		.amdhsa_user_sgpr_private_segment_size 0
		.amdhsa_uses_dynamic_stack 0
		.amdhsa_enable_private_segment 0
		.amdhsa_system_sgpr_workgroup_id_x 1
		.amdhsa_system_sgpr_workgroup_id_y 0
		.amdhsa_system_sgpr_workgroup_id_z 0
		.amdhsa_system_sgpr_workgroup_info 0
		.amdhsa_system_vgpr_workitem_id 0
		.amdhsa_next_free_vgpr 256
		.amdhsa_next_free_sgpr 78
		.amdhsa_accum_offset 256
		.amdhsa_reserve_vcc 1
		.amdhsa_float_round_mode_32 0
		.amdhsa_float_round_mode_16_64 0
		.amdhsa_float_denorm_mode_32 3
		.amdhsa_float_denorm_mode_16_64 3
		.amdhsa_dx10_clamp 1
		.amdhsa_ieee_mode 1
		.amdhsa_fp16_overflow 0
		.amdhsa_tg_split 0
		.amdhsa_exception_fp_ieee_invalid_op 0
		.amdhsa_exception_fp_denorm_src 0
		.amdhsa_exception_fp_ieee_div_zero 0
		.amdhsa_exception_fp_ieee_overflow 0
		.amdhsa_exception_fp_ieee_underflow 0
		.amdhsa_exception_fp_ieee_inexact 0
		.amdhsa_exception_int_div_zero 0
	.end_amdhsa_kernel

.LBB10_19:
	s_ashr_i32 s17, s16, 31
	v_cmp_lt_i64_e32 vcc, s[0:1], v[142:143]
	s_lshl_b64 s[0:1], s[16:17], 19
	s_add_u32 s18, s33, s0
	s_addc_u32 s19, s34, s1
	s_and_b64 s[0:1], vcc, exec
	s_cselect_b32 s17, s19, s27
	s_cselect_b32 s53, s18, s26
	s_ashr_i32 s15, s14, 31
	s_lshl_b64 s[0:1], s[14:15], 19
	s_add_u32 s20, s4, s0
	s_addc_u32 s21, s5, s1
	s_and_b64 s[0:1], vcc, exec
	s_cselect_b32 s15, s21, s25
	s_cselect_b32 s54, s20, s24
	s_add_u32 s55, s24, 0x100
	s_addc_u32 s56, s25, 0
	s_add_u32 s24, s26, 0x40080
	s_addc_u32 s25, s27, 0
	s_mov_b32 s57, -2
	ds_read_b128 v[152:155], v149
	ds_read_b128 v[156:159], v149 offset:1024
	ds_read_b128 v[160:163], v149 offset:2048
	ds_read_b128 v[164:167], v149 offset:3072
	ds_read_b128 v[168:171], v150
	ds_read_b128 v[172:175], v150 offset:1024
	ds_read_b128 v[176:179], v150 offset:2048
	ds_read_b128 v[180:183], v150 offset:3072
	s_add_u32 s26, s24, 0xfffc0080
	s_addc_u32 s27, s25, -1
	s_cmp_eq_u32 s57, 12
	s_cselect_b32 s29, s17, s27
	s_cselect_b32 s28, s53, s26
	s_cselect_b32 s27, s15, s56
	s_cselect_b32 s26, s54, s55
	s_add_i32 m0, s35, 0xc000
	ds_read_b128 v[184:187], v151
	ds_read_b128 v[188:191], v151 offset:1024
	ds_read_b128 v[192:195], v151 offset:2048
	ds_read_b128 v[196:199], v151 offset:3072
	ds_read_b128 v[200:203], v151 offset:4096
	ds_read_b128 v[204:207], v151 offset:5120
	ds_read_b128 v[208:211], v151 offset:6144
	ds_read_b128 v[212:215], v151 offset:7168
	global_load_lds_dwordx4 v140, s[24:25]
	s_add_i32 m0, s35, 0xe000
	s_nop 0
	global_load_lds_dwordx4 v138, s[24:25]
	s_waitcnt vmcnt(8)
	s_waitcnt lgkmcnt(0)
	s_barrier
	s_setprio 1
	s_waitcnt lgkmcnt(0)
	v_mfma_f32_16x16x32_bf16 v[124:127], v[152:155], v[184:187], 0
	v_mfma_f32_16x16x32_bf16 v[120:123], v[160:163], v[184:187], 0
	v_mfma_f32_16x16x32_bf16 v[116:119], v[152:155], v[192:195], 0
	v_mfma_f32_16x16x32_bf16 v[108:111], v[160:163], v[192:195], 0
	v_mfma_f32_16x16x32_bf16 v[100:103], v[152:155], v[200:203], 0
	v_mfma_f32_16x16x32_bf16 v[92:95], v[160:163], v[200:203], 0
	v_mfma_f32_16x16x32_bf16 v[84:87], v[152:155], v[208:211], 0
	v_mfma_f32_16x16x32_bf16 v[76:79], v[160:163], v[208:211], 0
	v_mfma_f32_16x16x32_bf16 v[124:127], v[156:159], v[188:191], v[124:127]
	v_mfma_f32_16x16x32_bf16 v[120:123], v[164:167], v[188:191], v[120:123]
	v_mfma_f32_16x16x32_bf16 v[116:119], v[156:159], v[196:199], v[116:119]
	v_mfma_f32_16x16x32_bf16 v[108:111], v[164:167], v[196:199], v[108:111]
	v_mfma_f32_16x16x32_bf16 v[100:103], v[156:159], v[204:207], v[100:103]
	v_mfma_f32_16x16x32_bf16 v[92:95], v[164:167], v[204:207], v[92:95]
	v_mfma_f32_16x16x32_bf16 v[84:87], v[156:159], v[212:215], v[84:87]
	v_mfma_f32_16x16x32_bf16 v[76:79], v[164:167], v[212:215], v[76:79]
	s_setprio 0
	s_setprio 1
	v_mfma_f32_16x16x32_bf16 v[112:115], v[168:171], v[184:187], 0
	v_mfma_f32_16x16x32_bf16 v[104:107], v[176:179], v[184:187], 0
	v_mfma_f32_16x16x32_bf16 v[96:99], v[168:171], v[192:195], 0
	v_mfma_f32_16x16x32_bf16 v[88:91], v[176:179], v[192:195], 0
	v_mfma_f32_16x16x32_bf16 v[80:83], v[168:171], v[200:203], 0
	v_mfma_f32_16x16x32_bf16 v[72:75], v[176:179], v[200:203], 0
	v_mfma_f32_16x16x32_bf16 v[68:71], v[168:171], v[208:211], 0
	v_mfma_f32_16x16x32_bf16 v[64:67], v[176:179], v[208:211], 0
	v_mfma_f32_16x16x32_bf16 v[112:115], v[172:175], v[188:191], v[112:115]
	v_mfma_f32_16x16x32_bf16 v[104:107], v[180:183], v[188:191], v[104:107]
	v_mfma_f32_16x16x32_bf16 v[96:99], v[172:175], v[196:199], v[96:99]
	v_mfma_f32_16x16x32_bf16 v[88:91], v[180:183], v[196:199], v[88:91]
	v_mfma_f32_16x16x32_bf16 v[80:83], v[172:175], v[204:207], v[80:83]
	v_mfma_f32_16x16x32_bf16 v[72:75], v[180:183], v[204:207], v[72:75]
	v_mfma_f32_16x16x32_bf16 v[68:71], v[172:175], v[212:215], v[68:71]
	v_mfma_f32_16x16x32_bf16 v[64:67], v[180:183], v[212:215], v[64:67]
	s_setprio 0
	s_barrier
	s_add_i32 s58, s46, s31
	s_add_u32 s62, s26, 0x80
	s_addc_u32 s63, s27, 0
	s_mov_b32 m0, s58
	ds_read_b128 v[184:187], v151 offset:16384
	ds_read_b128 v[188:191], v151 offset:17408
	ds_read_b128 v[192:195], v151 offset:18432
	ds_read_b128 v[196:199], v151 offset:19456
	ds_read_b128 v[200:203], v151 offset:20480
	ds_read_b128 v[204:207], v151 offset:21504
	ds_read_b128 v[208:211], v151 offset:22528
	ds_read_b128 v[212:215], v151 offset:23552
	global_load_lds_dwordx4 v130, s[26:27]
	s_add_i32 m0, s58, 0x2000
	s_add_u32 s58, s26, 0x40000
	s_addc_u32 s59, s27, 0
	s_add_i32 s60, s47, s31
	global_load_lds_dwordx4 v134, s[26:27]
	s_mov_b32 m0, s60
	s_add_u32 s64, s28, 0x80
	s_addc_u32 s65, s29, 0
	global_load_lds_dwordx4 v130, s[58:59]
	s_add_i32 m0, s60, 0x2000
	s_nop 0
	global_load_lds_dwordx4 v134, s[58:59]
	s_mov_b32 m0, s35
	s_nop 0
	global_load_lds_dwordx4 v128, s[28:29]
	s_mov_b32 m0, s36
	s_nop 0
	global_load_lds_dwordx4 v132, s[28:29]
	s_waitcnt vmcnt(8)
	s_waitcnt lgkmcnt(0)
	s_barrier
	s_setprio 1
	s_waitcnt lgkmcnt(0)
	v_mfma_f32_16x16x32_bf16 v[60:63], v[152:155], v[184:187], 0
	v_mfma_f32_16x16x32_bf16 v[56:59], v[160:163], v[184:187], 0
	v_mfma_f32_16x16x32_bf16 v[52:55], v[152:155], v[192:195], 0
	v_mfma_f32_16x16x32_bf16 v[44:47], v[160:163], v[192:195], 0
	v_mfma_f32_16x16x32_bf16 v[36:39], v[152:155], v[200:203], 0
	v_mfma_f32_16x16x32_bf16 v[28:31], v[160:163], v[200:203], 0
	v_mfma_f32_16x16x32_bf16 v[20:23], v[152:155], v[208:211], 0
	v_mfma_f32_16x16x32_bf16 v[12:15], v[160:163], v[208:211], 0
	v_mfma_f32_16x16x32_bf16 v[60:63], v[156:159], v[188:191], v[60:63]
	v_mfma_f32_16x16x32_bf16 v[56:59], v[164:167], v[188:191], v[56:59]
	v_mfma_f32_16x16x32_bf16 v[52:55], v[156:159], v[196:199], v[52:55]
	v_mfma_f32_16x16x32_bf16 v[44:47], v[164:167], v[196:199], v[44:47]
	v_mfma_f32_16x16x32_bf16 v[36:39], v[156:159], v[204:207], v[36:39]
	v_mfma_f32_16x16x32_bf16 v[28:31], v[164:167], v[204:207], v[28:31]
	v_mfma_f32_16x16x32_bf16 v[20:23], v[156:159], v[212:215], v[20:23]
	v_mfma_f32_16x16x32_bf16 v[12:15], v[164:167], v[212:215], v[12:15]
	s_setprio 0
	s_setprio 1
	v_mfma_f32_16x16x32_bf16 v[48:51], v[168:171], v[184:187], 0
	v_mfma_f32_16x16x32_bf16 v[40:43], v[176:179], v[184:187], 0
	v_mfma_f32_16x16x32_bf16 v[32:35], v[168:171], v[192:195], 0
	v_mfma_f32_16x16x32_bf16 v[24:27], v[176:179], v[192:195], 0
	v_mfma_f32_16x16x32_bf16 v[16:19], v[168:171], v[200:203], 0
	v_mfma_f32_16x16x32_bf16 v[8:11], v[176:179], v[200:203], 0
	v_mfma_f32_16x16x32_bf16 v[4:7], v[168:171], v[208:211], 0
	v_mfma_f32_16x16x32_bf16 v[0:3], v[176:179], v[208:211], 0
	v_mfma_f32_16x16x32_bf16 v[48:51], v[172:175], v[188:191], v[48:51]
	v_mfma_f32_16x16x32_bf16 v[40:43], v[180:183], v[188:191], v[40:43]
	v_mfma_f32_16x16x32_bf16 v[32:35], v[172:175], v[196:199], v[32:35]
	v_mfma_f32_16x16x32_bf16 v[24:27], v[180:183], v[196:199], v[24:27]
	v_mfma_f32_16x16x32_bf16 v[16:19], v[172:175], v[204:207], v[16:19]
	v_mfma_f32_16x16x32_bf16 v[8:11], v[180:183], v[204:207], v[8:11]
	v_mfma_f32_16x16x32_bf16 v[4:7], v[172:175], v[212:215], v[4:7]
	v_mfma_f32_16x16x32_bf16 v[0:3], v[180:183], v[212:215], v[0:3]
	s_setprio 0
	s_barrier
	s_add_i32 s58, 0, 0x18000
	s_add_i32 s59, 0, 0x1c000
	v_add_u32_e32 v164, s58, v148
	v_add_u32_e32 v180, s59, v148
	ds_read_b128 v[152:155], v164
	ds_read_b128 v[156:159], v164 offset:1024
	ds_read_b128 v[160:163], v164 offset:2048
	ds_read_b128 v[164:167], v164 offset:3072
	ds_read_b128 v[168:171], v180
	ds_read_b128 v[172:175], v180 offset:1024
	ds_read_b128 v[176:179], v180 offset:2048
	ds_read_b128 v[180:183], v180 offset:3072
	s_add_u32 s28, s28, 0x40000
	s_addc_u32 s29, s29, 0
	s_mov_b32 m0, s37
	ds_read_b128 v[184:187], v151 offset:32768
	ds_read_b128 v[188:191], v151 offset:33792
	ds_read_b128 v[192:195], v151 offset:34816
	ds_read_b128 v[196:199], v151 offset:35840
	ds_read_b128 v[200:203], v151 offset:36864
	ds_read_b128 v[204:207], v151 offset:37888
	ds_read_b128 v[208:211], v151 offset:38912
	ds_read_b128 v[212:215], v151 offset:39936
	global_load_lds_dwordx4 v128, s[28:29]
	s_mov_b32 m0, s38
	s_nop 0
	global_load_lds_dwordx4 v132, s[28:29]
	s_waitcnt vmcnt(8)
	s_waitcnt lgkmcnt(0)
	s_barrier
	s_setprio 1
	s_waitcnt lgkmcnt(0)
	v_mfma_f32_16x16x32_bf16 v[124:127], v[152:155], v[184:187], v[124:127]
	v_mfma_f32_16x16x32_bf16 v[120:123], v[160:163], v[184:187], v[120:123]
	v_mfma_f32_16x16x32_bf16 v[116:119], v[152:155], v[192:195], v[116:119]
	v_mfma_f32_16x16x32_bf16 v[108:111], v[160:163], v[192:195], v[108:111]
	v_mfma_f32_16x16x32_bf16 v[100:103], v[152:155], v[200:203], v[100:103]
	v_mfma_f32_16x16x32_bf16 v[92:95], v[160:163], v[200:203], v[92:95]
	v_mfma_f32_16x16x32_bf16 v[84:87], v[152:155], v[208:211], v[84:87]
	v_mfma_f32_16x16x32_bf16 v[76:79], v[160:163], v[208:211], v[76:79]
	v_mfma_f32_16x16x32_bf16 v[124:127], v[156:159], v[188:191], v[124:127]
	v_mfma_f32_16x16x32_bf16 v[120:123], v[164:167], v[188:191], v[120:123]
	v_mfma_f32_16x16x32_bf16 v[116:119], v[156:159], v[196:199], v[116:119]
	v_mfma_f32_16x16x32_bf16 v[108:111], v[164:167], v[196:199], v[108:111]
	v_mfma_f32_16x16x32_bf16 v[100:103], v[156:159], v[204:207], v[100:103]
	v_mfma_f32_16x16x32_bf16 v[92:95], v[164:167], v[204:207], v[92:95]
	v_mfma_f32_16x16x32_bf16 v[84:87], v[156:159], v[212:215], v[84:87]
	v_mfma_f32_16x16x32_bf16 v[76:79], v[164:167], v[212:215], v[76:79]
	s_setprio 0
	s_setprio 1
	v_mfma_f32_16x16x32_bf16 v[112:115], v[168:171], v[184:187], v[112:115]
	v_mfma_f32_16x16x32_bf16 v[104:107], v[176:179], v[184:187], v[104:107]
	v_mfma_f32_16x16x32_bf16 v[96:99], v[168:171], v[192:195], v[96:99]
	v_mfma_f32_16x16x32_bf16 v[88:91], v[176:179], v[192:195], v[88:91]
	v_mfma_f32_16x16x32_bf16 v[80:83], v[168:171], v[200:203], v[80:83]
	v_mfma_f32_16x16x32_bf16 v[72:75], v[176:179], v[200:203], v[72:75]
	v_mfma_f32_16x16x32_bf16 v[68:71], v[168:171], v[208:211], v[68:71]
	v_mfma_f32_16x16x32_bf16 v[64:67], v[176:179], v[208:211], v[64:67]
	v_mfma_f32_16x16x32_bf16 v[112:115], v[172:175], v[188:191], v[112:115]
	v_mfma_f32_16x16x32_bf16 v[104:107], v[180:183], v[188:191], v[104:107]
	v_mfma_f32_16x16x32_bf16 v[96:99], v[172:175], v[196:199], v[96:99]
	v_mfma_f32_16x16x32_bf16 v[88:91], v[180:183], v[196:199], v[88:91]
	v_mfma_f32_16x16x32_bf16 v[80:83], v[172:175], v[204:207], v[80:83]
	v_mfma_f32_16x16x32_bf16 v[72:75], v[180:183], v[204:207], v[72:75]
	v_mfma_f32_16x16x32_bf16 v[68:71], v[172:175], v[212:215], v[68:71]
	v_mfma_f32_16x16x32_bf16 v[64:67], v[180:183], v[212:215], v[64:67]
	s_setprio 0
	s_barrier
	s_add_i32 s28, s58, s31
	s_mov_b32 m0, s28
	ds_read_b128 v[184:187], v151 offset:49152
	ds_read_b128 v[188:191], v151 offset:50176
	ds_read_b128 v[192:195], v151 offset:51200
	ds_read_b128 v[196:199], v151 offset:52224
	ds_read_b128 v[200:203], v151 offset:53248
	ds_read_b128 v[204:207], v151 offset:54272
	ds_read_b128 v[208:211], v151 offset:55296
	ds_read_b128 v[212:215], v151 offset:56320
	global_load_lds_dwordx4 v130, s[62:63]
	s_add_i32 m0, s28, 0x2000
	s_add_u32 s26, s26, 0x40080
	s_addc_u32 s27, s27, 0
	s_add_i32 s28, s59, s31
	global_load_lds_dwordx4 v134, s[62:63]
	s_mov_b32 m0, s28
	s_nop 0
	global_load_lds_dwordx4 v130, s[26:27]
	s_add_i32 m0, s28, 0x2000
	s_nop 0
	global_load_lds_dwordx4 v134, s[26:27]
	s_mov_b32 m0, s41
	s_nop 0
	global_load_lds_dwordx4 v128, s[64:65]
	s_mov_b32 m0, s42
	s_nop 0
	global_load_lds_dwordx4 v132, s[64:65]
	s_waitcnt vmcnt(8)
	s_waitcnt lgkmcnt(0)
	s_barrier
	s_setprio 1
	s_waitcnt lgkmcnt(0)
	v_mfma_f32_16x16x32_bf16 v[60:63], v[152:155], v[184:187], v[60:63]
	v_mfma_f32_16x16x32_bf16 v[56:59], v[160:163], v[184:187], v[56:59]
	v_mfma_f32_16x16x32_bf16 v[52:55], v[152:155], v[192:195], v[52:55]
	v_mfma_f32_16x16x32_bf16 v[44:47], v[160:163], v[192:195], v[44:47]
	v_mfma_f32_16x16x32_bf16 v[36:39], v[152:155], v[200:203], v[36:39]
	v_mfma_f32_16x16x32_bf16 v[28:31], v[160:163], v[200:203], v[28:31]
	v_mfma_f32_16x16x32_bf16 v[20:23], v[152:155], v[208:211], v[20:23]
	v_mfma_f32_16x16x32_bf16 v[12:15], v[160:163], v[208:211], v[12:15]
	v_mfma_f32_16x16x32_bf16 v[60:63], v[156:159], v[188:191], v[60:63]
	v_mfma_f32_16x16x32_bf16 v[56:59], v[164:167], v[188:191], v[56:59]
	v_mfma_f32_16x16x32_bf16 v[52:55], v[156:159], v[196:199], v[52:55]
	v_mfma_f32_16x16x32_bf16 v[44:47], v[164:167], v[196:199], v[44:47]
	v_mfma_f32_16x16x32_bf16 v[36:39], v[156:159], v[204:207], v[36:39]
	v_mfma_f32_16x16x32_bf16 v[28:31], v[164:167], v[204:207], v[28:31]
	v_mfma_f32_16x16x32_bf16 v[20:23], v[156:159], v[212:215], v[20:23]
	v_mfma_f32_16x16x32_bf16 v[12:15], v[164:167], v[212:215], v[12:15]
	s_setprio 0
	s_setprio 1
	v_mfma_f32_16x16x32_bf16 v[48:51], v[168:171], v[184:187], v[48:51]
	v_mfma_f32_16x16x32_bf16 v[40:43], v[176:179], v[184:187], v[40:43]
	v_mfma_f32_16x16x32_bf16 v[32:35], v[168:171], v[192:195], v[32:35]
	v_mfma_f32_16x16x32_bf16 v[24:27], v[176:179], v[192:195], v[24:27]
	v_mfma_f32_16x16x32_bf16 v[16:19], v[168:171], v[200:203], v[16:19]
	v_mfma_f32_16x16x32_bf16 v[8:11], v[176:179], v[200:203], v[8:11]
	v_mfma_f32_16x16x32_bf16 v[4:7], v[168:171], v[208:211], v[4:7]
	v_mfma_f32_16x16x32_bf16 v[0:3], v[176:179], v[208:211], v[0:3]
	v_mfma_f32_16x16x32_bf16 v[48:51], v[172:175], v[188:191], v[48:51]
	v_mfma_f32_16x16x32_bf16 v[40:43], v[180:183], v[188:191], v[40:43]
	v_mfma_f32_16x16x32_bf16 v[32:35], v[172:175], v[196:199], v[32:35]
	v_mfma_f32_16x16x32_bf16 v[24:27], v[180:183], v[196:199], v[24:27]
	v_mfma_f32_16x16x32_bf16 v[16:19], v[172:175], v[204:207], v[16:19]
	v_mfma_f32_16x16x32_bf16 v[8:11], v[180:183], v[204:207], v[8:11]
	v_mfma_f32_16x16x32_bf16 v[4:7], v[172:175], v[212:215], v[4:7]
	v_mfma_f32_16x16x32_bf16 v[0:3], v[180:183], v[212:215], v[0:3]
	s_setprio 0
	s_barrier
	s_add_i32 s57, s57, 2
	s_add_u32 s55, s55, 0x100
	s_addc_u32 s56, s56, 0
	s_add_u32 s24, s24, 0x100
	s_addc_u32 s25, s25, 0
	s_cmp_lt_u32 s57, 14
.LBB10_20:
	ds_read_b128 v[152:155], v149
	ds_read_b128 v[156:159], v149 offset:1024
	ds_read_b128 v[160:163], v149 offset:2048
	ds_read_b128 v[164:167], v149 offset:3072
	ds_read_b128 v[168:171], v150
	ds_read_b128 v[172:175], v150 offset:1024
	ds_read_b128 v[176:179], v150 offset:2048
	ds_read_b128 v[180:183], v150 offset:3072
	s_add_u32 s26, s24, 0xfffc0080
	s_addc_u32 s27, s25, -1
	s_cmp_eq_u32 s57, 12
	s_cselect_b32 s29, s17, s27
	s_cselect_b32 s28, s53, s26
	s_cselect_b32 s27, s15, s56
	s_cselect_b32 s26, s54, s55
	s_add_i32 m0, s35, 0xc000
	ds_read_b128 v[184:187], v151
	ds_read_b128 v[188:191], v151 offset:1024
	ds_read_b128 v[192:195], v151 offset:2048
	ds_read_b128 v[196:199], v151 offset:3072
	ds_read_b128 v[200:203], v151 offset:4096
	ds_read_b128 v[204:207], v151 offset:5120
	ds_read_b128 v[208:211], v151 offset:6144
	ds_read_b128 v[212:215], v151 offset:7168
	global_load_lds_dwordx4 v140, s[24:25]
	s_add_i32 m0, s35, 0xe000
	s_nop 0
	global_load_lds_dwordx4 v138, s[24:25]
	s_waitcnt vmcnt(8)
	s_waitcnt lgkmcnt(0)
	s_barrier
	s_setprio 1
	s_waitcnt lgkmcnt(0)
	v_mfma_f32_16x16x32_bf16 v[124:127], v[152:155], v[184:187], v[124:127]
	v_mfma_f32_16x16x32_bf16 v[120:123], v[160:163], v[184:187], v[120:123]
	v_mfma_f32_16x16x32_bf16 v[116:119], v[152:155], v[192:195], v[116:119]
	v_mfma_f32_16x16x32_bf16 v[108:111], v[160:163], v[192:195], v[108:111]
	v_mfma_f32_16x16x32_bf16 v[100:103], v[152:155], v[200:203], v[100:103]
	v_mfma_f32_16x16x32_bf16 v[92:95], v[160:163], v[200:203], v[92:95]
	v_mfma_f32_16x16x32_bf16 v[84:87], v[152:155], v[208:211], v[84:87]
	v_mfma_f32_16x16x32_bf16 v[76:79], v[160:163], v[208:211], v[76:79]
	v_mfma_f32_16x16x32_bf16 v[124:127], v[156:159], v[188:191], v[124:127]
	v_mfma_f32_16x16x32_bf16 v[120:123], v[164:167], v[188:191], v[120:123]
	v_mfma_f32_16x16x32_bf16 v[116:119], v[156:159], v[196:199], v[116:119]
	v_mfma_f32_16x16x32_bf16 v[108:111], v[164:167], v[196:199], v[108:111]
	v_mfma_f32_16x16x32_bf16 v[100:103], v[156:159], v[204:207], v[100:103]
	v_mfma_f32_16x16x32_bf16 v[92:95], v[164:167], v[204:207], v[92:95]
	v_mfma_f32_16x16x32_bf16 v[84:87], v[156:159], v[212:215], v[84:87]
	v_mfma_f32_16x16x32_bf16 v[76:79], v[164:167], v[212:215], v[76:79]
	s_setprio 0
	s_setprio 1
	v_mfma_f32_16x16x32_bf16 v[112:115], v[168:171], v[184:187], v[112:115]
	v_mfma_f32_16x16x32_bf16 v[104:107], v[176:179], v[184:187], v[104:107]
	v_mfma_f32_16x16x32_bf16 v[96:99], v[168:171], v[192:195], v[96:99]
	v_mfma_f32_16x16x32_bf16 v[88:91], v[176:179], v[192:195], v[88:91]
	v_mfma_f32_16x16x32_bf16 v[80:83], v[168:171], v[200:203], v[80:83]
	v_mfma_f32_16x16x32_bf16 v[72:75], v[176:179], v[200:203], v[72:75]
	v_mfma_f32_16x16x32_bf16 v[68:71], v[168:171], v[208:211], v[68:71]
	v_mfma_f32_16x16x32_bf16 v[64:67], v[176:179], v[208:211], v[64:67]
	v_mfma_f32_16x16x32_bf16 v[112:115], v[172:175], v[188:191], v[112:115]
	v_mfma_f32_16x16x32_bf16 v[104:107], v[180:183], v[188:191], v[104:107]
	v_mfma_f32_16x16x32_bf16 v[96:99], v[172:175], v[196:199], v[96:99]
	v_mfma_f32_16x16x32_bf16 v[88:91], v[180:183], v[196:199], v[88:91]
	v_mfma_f32_16x16x32_bf16 v[80:83], v[172:175], v[204:207], v[80:83]
	v_mfma_f32_16x16x32_bf16 v[72:75], v[180:183], v[204:207], v[72:75]
	v_mfma_f32_16x16x32_bf16 v[68:71], v[172:175], v[212:215], v[68:71]
	v_mfma_f32_16x16x32_bf16 v[64:67], v[180:183], v[212:215], v[64:67]
	s_setprio 0
	s_barrier
	s_add_i32 s58, s46, s31
	s_add_u32 s62, s26, 0x80
	s_addc_u32 s63, s27, 0
	s_mov_b32 m0, s58
	ds_read_b128 v[184:187], v151 offset:16384
	ds_read_b128 v[188:191], v151 offset:17408
	ds_read_b128 v[192:195], v151 offset:18432
	ds_read_b128 v[196:199], v151 offset:19456
	ds_read_b128 v[200:203], v151 offset:20480
	ds_read_b128 v[204:207], v151 offset:21504
	ds_read_b128 v[208:211], v151 offset:22528
	ds_read_b128 v[212:215], v151 offset:23552
	global_load_lds_dwordx4 v130, s[26:27]
	s_add_i32 m0, s58, 0x2000
	s_add_u32 s58, s26, 0x40000
	s_addc_u32 s59, s27, 0
	s_add_i32 s60, s47, s31
	global_load_lds_dwordx4 v134, s[26:27]
	s_mov_b32 m0, s60
	s_add_u32 s64, s28, 0x80
	s_addc_u32 s65, s29, 0
	global_load_lds_dwordx4 v130, s[58:59]
	s_add_i32 m0, s60, 0x2000
	s_nop 0
	global_load_lds_dwordx4 v134, s[58:59]
	s_mov_b32 m0, s35
	s_nop 0
	global_load_lds_dwordx4 v128, s[28:29]
	s_mov_b32 m0, s36
	s_nop 0
	global_load_lds_dwordx4 v132, s[28:29]
	s_waitcnt vmcnt(8)
	s_waitcnt lgkmcnt(0)
	s_barrier
	s_setprio 1
	s_waitcnt lgkmcnt(0)
	v_mfma_f32_16x16x32_bf16 v[60:63], v[152:155], v[184:187], v[60:63]
	v_mfma_f32_16x16x32_bf16 v[56:59], v[160:163], v[184:187], v[56:59]
	v_mfma_f32_16x16x32_bf16 v[52:55], v[152:155], v[192:195], v[52:55]
	v_mfma_f32_16x16x32_bf16 v[44:47], v[160:163], v[192:195], v[44:47]
	v_mfma_f32_16x16x32_bf16 v[36:39], v[152:155], v[200:203], v[36:39]
	v_mfma_f32_16x16x32_bf16 v[28:31], v[160:163], v[200:203], v[28:31]
	v_mfma_f32_16x16x32_bf16 v[20:23], v[152:155], v[208:211], v[20:23]
	v_mfma_f32_16x16x32_bf16 v[12:15], v[160:163], v[208:211], v[12:15]
	v_mfma_f32_16x16x32_bf16 v[60:63], v[156:159], v[188:191], v[60:63]
	v_mfma_f32_16x16x32_bf16 v[56:59], v[164:167], v[188:191], v[56:59]
	v_mfma_f32_16x16x32_bf16 v[52:55], v[156:159], v[196:199], v[52:55]
	v_mfma_f32_16x16x32_bf16 v[44:47], v[164:167], v[196:199], v[44:47]
	v_mfma_f32_16x16x32_bf16 v[36:39], v[156:159], v[204:207], v[36:39]
	v_mfma_f32_16x16x32_bf16 v[28:31], v[164:167], v[204:207], v[28:31]
	v_mfma_f32_16x16x32_bf16 v[20:23], v[156:159], v[212:215], v[20:23]
	v_mfma_f32_16x16x32_bf16 v[12:15], v[164:167], v[212:215], v[12:15]
	s_setprio 0
	s_setprio 1
	v_mfma_f32_16x16x32_bf16 v[48:51], v[168:171], v[184:187], v[48:51]
	v_mfma_f32_16x16x32_bf16 v[40:43], v[176:179], v[184:187], v[40:43]
	v_mfma_f32_16x16x32_bf16 v[32:35], v[168:171], v[192:195], v[32:35]
	v_mfma_f32_16x16x32_bf16 v[24:27], v[176:179], v[192:195], v[24:27]
	v_mfma_f32_16x16x32_bf16 v[16:19], v[168:171], v[200:203], v[16:19]
	v_mfma_f32_16x16x32_bf16 v[8:11], v[176:179], v[200:203], v[8:11]
	v_mfma_f32_16x16x32_bf16 v[4:7], v[168:171], v[208:211], v[4:7]
	v_mfma_f32_16x16x32_bf16 v[0:3], v[176:179], v[208:211], v[0:3]
	v_mfma_f32_16x16x32_bf16 v[48:51], v[172:175], v[188:191], v[48:51]
	v_mfma_f32_16x16x32_bf16 v[40:43], v[180:183], v[188:191], v[40:43]
	v_mfma_f32_16x16x32_bf16 v[32:35], v[172:175], v[196:199], v[32:35]
	v_mfma_f32_16x16x32_bf16 v[24:27], v[180:183], v[196:199], v[24:27]
	v_mfma_f32_16x16x32_bf16 v[16:19], v[172:175], v[204:207], v[16:19]
	v_mfma_f32_16x16x32_bf16 v[8:11], v[180:183], v[204:207], v[8:11]
	v_mfma_f32_16x16x32_bf16 v[4:7], v[172:175], v[212:215], v[4:7]
	v_mfma_f32_16x16x32_bf16 v[0:3], v[180:183], v[212:215], v[0:3]
	s_setprio 0
	s_barrier
	s_add_i32 s58, 0, 0x18000
	s_add_i32 s59, 0, 0x1c000
	v_add_u32_e32 v164, s58, v148
	v_add_u32_e32 v180, s59, v148
	ds_read_b128 v[152:155], v164
	ds_read_b128 v[156:159], v164 offset:1024
	ds_read_b128 v[160:163], v164 offset:2048
	ds_read_b128 v[164:167], v164 offset:3072
	ds_read_b128 v[168:171], v180
	ds_read_b128 v[172:175], v180 offset:1024
	ds_read_b128 v[176:179], v180 offset:2048
	ds_read_b128 v[180:183], v180 offset:3072
	s_add_u32 s28, s28, 0x40000
	s_addc_u32 s29, s29, 0
	s_mov_b32 m0, s37
	ds_read_b128 v[184:187], v151 offset:32768
	ds_read_b128 v[188:191], v151 offset:33792
	ds_read_b128 v[192:195], v151 offset:34816
	ds_read_b128 v[196:199], v151 offset:35840
	ds_read_b128 v[200:203], v151 offset:36864
	ds_read_b128 v[204:207], v151 offset:37888
	ds_read_b128 v[208:211], v151 offset:38912
	ds_read_b128 v[212:215], v151 offset:39936
	global_load_lds_dwordx4 v128, s[28:29]
	s_mov_b32 m0, s38
	s_nop 0
	global_load_lds_dwordx4 v132, s[28:29]
	s_waitcnt vmcnt(8)
	s_waitcnt lgkmcnt(0)
	s_barrier
	s_setprio 1
	s_waitcnt lgkmcnt(0)
	v_mfma_f32_16x16x32_bf16 v[124:127], v[152:155], v[184:187], v[124:127]
	v_mfma_f32_16x16x32_bf16 v[120:123], v[160:163], v[184:187], v[120:123]
	v_mfma_f32_16x16x32_bf16 v[116:119], v[152:155], v[192:195], v[116:119]
	v_mfma_f32_16x16x32_bf16 v[108:111], v[160:163], v[192:195], v[108:111]
	v_mfma_f32_16x16x32_bf16 v[100:103], v[152:155], v[200:203], v[100:103]
	v_mfma_f32_16x16x32_bf16 v[92:95], v[160:163], v[200:203], v[92:95]
	v_mfma_f32_16x16x32_bf16 v[84:87], v[152:155], v[208:211], v[84:87]
	v_mfma_f32_16x16x32_bf16 v[76:79], v[160:163], v[208:211], v[76:79]
	v_mfma_f32_16x16x32_bf16 v[124:127], v[156:159], v[188:191], v[124:127]
	v_mfma_f32_16x16x32_bf16 v[120:123], v[164:167], v[188:191], v[120:123]
	v_mfma_f32_16x16x32_bf16 v[116:119], v[156:159], v[196:199], v[116:119]
	v_mfma_f32_16x16x32_bf16 v[108:111], v[164:167], v[196:199], v[108:111]
	v_mfma_f32_16x16x32_bf16 v[100:103], v[156:159], v[204:207], v[100:103]
	v_mfma_f32_16x16x32_bf16 v[92:95], v[164:167], v[204:207], v[92:95]
	v_mfma_f32_16x16x32_bf16 v[84:87], v[156:159], v[212:215], v[84:87]
	v_mfma_f32_16x16x32_bf16 v[76:79], v[164:167], v[212:215], v[76:79]
	s_setprio 0
	s_setprio 1
	v_mfma_f32_16x16x32_bf16 v[112:115], v[168:171], v[184:187], v[112:115]
	v_mfma_f32_16x16x32_bf16 v[104:107], v[176:179], v[184:187], v[104:107]
	v_mfma_f32_16x16x32_bf16 v[96:99], v[168:171], v[192:195], v[96:99]
	v_mfma_f32_16x16x32_bf16 v[88:91], v[176:179], v[192:195], v[88:91]
	v_mfma_f32_16x16x32_bf16 v[80:83], v[168:171], v[200:203], v[80:83]
	v_mfma_f32_16x16x32_bf16 v[72:75], v[176:179], v[200:203], v[72:75]
	v_mfma_f32_16x16x32_bf16 v[68:71], v[168:171], v[208:211], v[68:71]
	v_mfma_f32_16x16x32_bf16 v[64:67], v[176:179], v[208:211], v[64:67]
	v_mfma_f32_16x16x32_bf16 v[112:115], v[172:175], v[188:191], v[112:115]
	v_mfma_f32_16x16x32_bf16 v[104:107], v[180:183], v[188:191], v[104:107]
	v_mfma_f32_16x16x32_bf16 v[96:99], v[172:175], v[196:199], v[96:99]
	v_mfma_f32_16x16x32_bf16 v[88:91], v[180:183], v[196:199], v[88:91]
	v_mfma_f32_16x16x32_bf16 v[80:83], v[172:175], v[204:207], v[80:83]
	v_mfma_f32_16x16x32_bf16 v[72:75], v[180:183], v[204:207], v[72:75]
	v_mfma_f32_16x16x32_bf16 v[68:71], v[172:175], v[212:215], v[68:71]
	v_mfma_f32_16x16x32_bf16 v[64:67], v[180:183], v[212:215], v[64:67]
	s_setprio 0
	s_barrier
	s_add_i32 s28, s58, s31
	s_mov_b32 m0, s28
	ds_read_b128 v[184:187], v151 offset:49152
	ds_read_b128 v[188:191], v151 offset:50176
	ds_read_b128 v[192:195], v151 offset:51200
	ds_read_b128 v[196:199], v151 offset:52224
	ds_read_b128 v[200:203], v151 offset:53248
	ds_read_b128 v[204:207], v151 offset:54272
	ds_read_b128 v[208:211], v151 offset:55296
	ds_read_b128 v[212:215], v151 offset:56320
	global_load_lds_dwordx4 v130, s[62:63]
	s_add_i32 m0, s28, 0x2000
	s_add_u32 s26, s26, 0x40080
	s_addc_u32 s27, s27, 0
	s_add_i32 s28, s59, s31
	global_load_lds_dwordx4 v134, s[62:63]
	s_mov_b32 m0, s28
	s_nop 0
	global_load_lds_dwordx4 v130, s[26:27]
	s_add_i32 m0, s28, 0x2000
	s_nop 0
	global_load_lds_dwordx4 v134, s[26:27]
	s_mov_b32 m0, s41
	s_nop 0
	global_load_lds_dwordx4 v128, s[64:65]
	s_mov_b32 m0, s42
	s_nop 0
	global_load_lds_dwordx4 v132, s[64:65]
	s_waitcnt vmcnt(8)
	s_waitcnt lgkmcnt(0)
	s_barrier
	s_setprio 1
	s_waitcnt lgkmcnt(0)
	v_mfma_f32_16x16x32_bf16 v[60:63], v[152:155], v[184:187], v[60:63]
	v_mfma_f32_16x16x32_bf16 v[56:59], v[160:163], v[184:187], v[56:59]
	v_mfma_f32_16x16x32_bf16 v[52:55], v[152:155], v[192:195], v[52:55]
	v_mfma_f32_16x16x32_bf16 v[44:47], v[160:163], v[192:195], v[44:47]
	v_mfma_f32_16x16x32_bf16 v[36:39], v[152:155], v[200:203], v[36:39]
	v_mfma_f32_16x16x32_bf16 v[28:31], v[160:163], v[200:203], v[28:31]
	v_mfma_f32_16x16x32_bf16 v[20:23], v[152:155], v[208:211], v[20:23]
	v_mfma_f32_16x16x32_bf16 v[12:15], v[160:163], v[208:211], v[12:15]
	v_mfma_f32_16x16x32_bf16 v[60:63], v[156:159], v[188:191], v[60:63]
	v_mfma_f32_16x16x32_bf16 v[56:59], v[164:167], v[188:191], v[56:59]
	v_mfma_f32_16x16x32_bf16 v[52:55], v[156:159], v[196:199], v[52:55]
	v_mfma_f32_16x16x32_bf16 v[44:47], v[164:167], v[196:199], v[44:47]
	v_mfma_f32_16x16x32_bf16 v[36:39], v[156:159], v[204:207], v[36:39]
	v_mfma_f32_16x16x32_bf16 v[28:31], v[164:167], v[204:207], v[28:31]
	v_mfma_f32_16x16x32_bf16 v[20:23], v[156:159], v[212:215], v[20:23]
	v_mfma_f32_16x16x32_bf16 v[12:15], v[164:167], v[212:215], v[12:15]
	s_setprio 0
	s_setprio 1
	v_mfma_f32_16x16x32_bf16 v[48:51], v[168:171], v[184:187], v[48:51]
	v_mfma_f32_16x16x32_bf16 v[40:43], v[176:179], v[184:187], v[40:43]
	v_mfma_f32_16x16x32_bf16 v[32:35], v[168:171], v[192:195], v[32:35]
	v_mfma_f32_16x16x32_bf16 v[24:27], v[176:179], v[192:195], v[24:27]
	v_mfma_f32_16x16x32_bf16 v[16:19], v[168:171], v[200:203], v[16:19]
	v_mfma_f32_16x16x32_bf16 v[8:11], v[176:179], v[200:203], v[8:11]
	v_mfma_f32_16x16x32_bf16 v[4:7], v[168:171], v[208:211], v[4:7]
	v_mfma_f32_16x16x32_bf16 v[0:3], v[176:179], v[208:211], v[0:3]
	v_mfma_f32_16x16x32_bf16 v[48:51], v[172:175], v[188:191], v[48:51]
	v_mfma_f32_16x16x32_bf16 v[40:43], v[180:183], v[188:191], v[40:43]
	v_mfma_f32_16x16x32_bf16 v[32:35], v[172:175], v[196:199], v[32:35]
	v_mfma_f32_16x16x32_bf16 v[24:27], v[180:183], v[196:199], v[24:27]
	v_mfma_f32_16x16x32_bf16 v[16:19], v[172:175], v[204:207], v[16:19]
	v_mfma_f32_16x16x32_bf16 v[8:11], v[180:183], v[204:207], v[8:11]
	v_mfma_f32_16x16x32_bf16 v[4:7], v[172:175], v[212:215], v[4:7]
	v_mfma_f32_16x16x32_bf16 v[0:3], v[180:183], v[212:215], v[0:3]
	s_setprio 0
	s_barrier
	s_add_i32 s57, s57, 2
	s_add_u32 s55, s55, 0x100
	s_addc_u32 s56, s56, 0
	s_add_u32 s24, s24, 0x100
	s_addc_u32 s25, s25, 0
	s_cmp_lt_u32 s57, 14
	s_cbranch_scc1 .LBB10_20
	s_andn2_b64 vcc, exec, s[12:13]
	s_cbranch_vccnz .LBB10_23
	s_barrier

	.amdhsa_kernel _Z10fwd_kernelILi10ELi11EEv4Args
		.amdhsa_group_segment_fixed_size 0
		.amdhsa_private_segment_fixed_size 0
		.amdhsa_kernarg_size 488
		.amdhsa_user_sgpr_count 2
		.amdhsa_user_sgpr_dispatch_ptr 0
		.amdhsa_user_sgpr_queue_ptr 0
		.amdhsa_user_sgpr_kernarg_segment_ptr 1
		.amdhsa_user_sgpr_dispatch_id 0
		.amdhsa_user_sgpr_kernarg_preload_length 0
		.amdhsa_user_sgpr_kernarg_preload_offset 0
		.amdhsa_user_sgpr_private_segment_size 0
		.amdhsa_uses_dynamic_stack 0
		.amdhsa_enable_private_segment 0
		.amdhsa_system_sgpr_workgroup_id_x 1
		.amdhsa_system_sgpr_workgroup_id_y 0
		.amdhsa_system_sgpr_workgroup_id_z 0
		.amdhsa_system_sgpr_workgroup_info 0
		.amdhsa_system_vgpr_workitem_id 0
		.amdhsa_next_free_vgpr 240
		.amdhsa_next_free_sgpr 70
		.amdhsa_accum_offset 240
		.amdhsa_reserve_vcc 1
		.amdhsa_float_round_mode_32 0
		.amdhsa_float_round_mode_16_64 0
		.amdhsa_float_denorm_mode_32 3
		.amdhsa_float_denorm_mode_16_64 3
		.amdhsa_dx10_clamp 1
		.amdhsa_ieee_mode 1
		.amdhsa_fp16_overflow 0
		.amdhsa_tg_split 0
		.amdhsa_exception_fp_ieee_invalid_op 0
		.amdhsa_exception_fp_denorm_src 0
		.amdhsa_exception_fp_ieee_div_zero 0
		.amdhsa_exception_fp_ieee_overflow 0
		.amdhsa_exception_fp_ieee_underflow 0
		.amdhsa_exception_fp_ieee_inexact 0
		.amdhsa_exception_int_div_zero 0
	.end_amdhsa_kernel

.LBB12_8:
	s_ashr_i32 s15, s14, 31
	v_cmp_lt_i64_e32 vcc, s[0:1], v[142:143]
	s_lshl_b64 s[0:1], s[14:15], 19
	s_add_u32 s16, s28, s0
	s_addc_u32 s17, s29, s1
	s_and_b64 s[0:1], vcc, exec
	s_cselect_b32 s15, s17, s25
	s_cselect_b32 s54, s16, s24
	s_ashr_i32 s13, s12, 31
	s_lshl_b64 s[0:1], s[12:13], 19
	s_add_u32 s18, s30, s0
	s_addc_u32 s19, s31, s1
	s_and_b64 s[0:1], vcc, exec
	s_cselect_b32 s13, s19, s23
	s_cselect_b32 s55, s18, s22
	s_add_u32 s56, s22, 0x100
	s_addc_u32 s57, s23, 0
	s_add_u32 s22, s24, 0x40080
	s_addc_u32 s23, s25, 0
	s_mov_b32 s58, -2
	ds_read_b128 v[152:155], v149
	ds_read_b128 v[156:159], v149 offset:1024
	ds_read_b128 v[160:163], v149 offset:2048
	ds_read_b128 v[164:167], v149 offset:3072
	ds_read_b128 v[168:171], v150
	ds_read_b128 v[172:175], v150 offset:1024
	ds_read_b128 v[176:179], v150 offset:2048
	ds_read_b128 v[180:183], v150 offset:3072
	s_add_u32 s24, s22, 0xfffc0080
	s_addc_u32 s25, s23, -1
	s_cmp_eq_u32 s58, 12
	s_cselect_b32 s27, s15, s25
	s_cselect_b32 s26, s54, s24
	s_cselect_b32 s25, s13, s57
	s_cselect_b32 s24, s55, s56
	s_add_i32 m0, s36, 0xc000
	ds_read_b128 v[184:187], v151
	ds_read_b128 v[188:191], v151 offset:1024
	ds_read_b128 v[192:195], v151 offset:2048
	ds_read_b128 v[196:199], v151 offset:3072
	ds_read_b128 v[200:203], v151 offset:4096
	ds_read_b128 v[204:207], v151 offset:5120
	ds_read_b128 v[208:211], v151 offset:6144
	ds_read_b128 v[212:215], v151 offset:7168
	global_load_lds_dwordx4 v140, s[22:23]
	s_add_i32 m0, s36, 0xe000
	s_nop 0
	global_load_lds_dwordx4 v138, s[22:23]
	s_waitcnt vmcnt(8)
	s_waitcnt lgkmcnt(0)
	s_barrier
	s_setprio 1
	s_waitcnt lgkmcnt(0)
	v_mfma_f32_16x16x32_bf16 v[124:127], v[152:155], v[184:187], 0
	v_mfma_f32_16x16x32_bf16 v[120:123], v[160:163], v[184:187], 0
	v_mfma_f32_16x16x32_bf16 v[108:111], v[152:155], v[192:195], 0
	v_mfma_f32_16x16x32_bf16 v[104:107], v[160:163], v[192:195], 0
	v_mfma_f32_16x16x32_bf16 v[92:95], v[152:155], v[200:203], 0
	v_mfma_f32_16x16x32_bf16 v[88:91], v[160:163], v[200:203], 0
	v_mfma_f32_16x16x32_bf16 v[76:79], v[152:155], v[208:211], 0
	v_mfma_f32_16x16x32_bf16 v[72:75], v[160:163], v[208:211], 0
	v_mfma_f32_16x16x32_bf16 v[124:127], v[156:159], v[188:191], v[124:127]
	v_mfma_f32_16x16x32_bf16 v[120:123], v[164:167], v[188:191], v[120:123]
	v_mfma_f32_16x16x32_bf16 v[108:111], v[156:159], v[196:199], v[108:111]
	v_mfma_f32_16x16x32_bf16 v[104:107], v[164:167], v[196:199], v[104:107]
	v_mfma_f32_16x16x32_bf16 v[92:95], v[156:159], v[204:207], v[92:95]
	v_mfma_f32_16x16x32_bf16 v[88:91], v[164:167], v[204:207], v[88:91]
	v_mfma_f32_16x16x32_bf16 v[76:79], v[156:159], v[212:215], v[76:79]
	v_mfma_f32_16x16x32_bf16 v[72:75], v[164:167], v[212:215], v[72:75]
	s_setprio 0
	s_setprio 1
	v_mfma_f32_16x16x32_bf16 v[116:119], v[168:171], v[184:187], 0
	v_mfma_f32_16x16x32_bf16 v[112:115], v[176:179], v[184:187], 0
	v_mfma_f32_16x16x32_bf16 v[100:103], v[168:171], v[192:195], 0
	v_mfma_f32_16x16x32_bf16 v[96:99], v[176:179], v[192:195], 0
	v_mfma_f32_16x16x32_bf16 v[84:87], v[168:171], v[200:203], 0
	v_mfma_f32_16x16x32_bf16 v[80:83], v[176:179], v[200:203], 0
	v_mfma_f32_16x16x32_bf16 v[68:71], v[168:171], v[208:211], 0
	v_mfma_f32_16x16x32_bf16 v[64:67], v[176:179], v[208:211], 0
	v_mfma_f32_16x16x32_bf16 v[116:119], v[172:175], v[188:191], v[116:119]
	v_mfma_f32_16x16x32_bf16 v[112:115], v[180:183], v[188:191], v[112:115]
	v_mfma_f32_16x16x32_bf16 v[100:103], v[172:175], v[196:199], v[100:103]
	v_mfma_f32_16x16x32_bf16 v[96:99], v[180:183], v[196:199], v[96:99]
	v_mfma_f32_16x16x32_bf16 v[84:87], v[172:175], v[204:207], v[84:87]
	v_mfma_f32_16x16x32_bf16 v[80:83], v[180:183], v[204:207], v[80:83]
	v_mfma_f32_16x16x32_bf16 v[68:71], v[172:175], v[212:215], v[68:71]
	v_mfma_f32_16x16x32_bf16 v[64:67], v[180:183], v[212:215], v[64:67]
	s_setprio 0
	s_barrier
	s_add_i32 s59, s44, s33
	s_add_u32 s62, s24, 0x80
	s_addc_u32 s63, s25, 0
	s_mov_b32 m0, s59
	ds_read_b128 v[184:187], v151 offset:16384
	ds_read_b128 v[188:191], v151 offset:17408
	ds_read_b128 v[192:195], v151 offset:18432
	ds_read_b128 v[196:199], v151 offset:19456
	ds_read_b128 v[200:203], v151 offset:20480
	ds_read_b128 v[204:207], v151 offset:21504
	ds_read_b128 v[208:211], v151 offset:22528
	ds_read_b128 v[212:215], v151 offset:23552
	global_load_lds_dwordx4 v132, s[24:25]
	s_add_i32 m0, s59, 0x2000
	s_add_u32 s60, s24, 0x40000
	s_addc_u32 s61, s25, 0
	s_add_i32 s59, s45, s33
	global_load_lds_dwordx4 v128, s[24:25]
	s_mov_b32 m0, s59
	s_add_u32 s64, s26, 0x80
	s_addc_u32 s65, s27, 0
	global_load_lds_dwordx4 v132, s[60:61]
	s_add_i32 m0, s59, 0x2000
	s_nop 0
	global_load_lds_dwordx4 v128, s[60:61]
	s_mov_b32 m0, s36
	s_nop 0
	global_load_lds_dwordx4 v134, s[26:27]
	s_mov_b32 m0, s37
	s_nop 0
	global_load_lds_dwordx4 v130, s[26:27]
	s_waitcnt vmcnt(8)
	s_waitcnt lgkmcnt(0)
	s_barrier
	s_setprio 1
	s_waitcnt lgkmcnt(0)
	v_mfma_f32_16x16x32_bf16 v[60:63], v[152:155], v[184:187], 0
	v_mfma_f32_16x16x32_bf16 v[56:59], v[160:163], v[184:187], 0
	v_mfma_f32_16x16x32_bf16 v[44:47], v[152:155], v[192:195], 0
	v_mfma_f32_16x16x32_bf16 v[40:43], v[160:163], v[192:195], 0
	v_mfma_f32_16x16x32_bf16 v[28:31], v[152:155], v[200:203], 0
	v_mfma_f32_16x16x32_bf16 v[24:27], v[160:163], v[200:203], 0
	v_mfma_f32_16x16x32_bf16 v[12:15], v[152:155], v[208:211], 0
	v_mfma_f32_16x16x32_bf16 v[8:11], v[160:163], v[208:211], 0
	v_mfma_f32_16x16x32_bf16 v[60:63], v[156:159], v[188:191], v[60:63]
	v_mfma_f32_16x16x32_bf16 v[56:59], v[164:167], v[188:191], v[56:59]
	v_mfma_f32_16x16x32_bf16 v[44:47], v[156:159], v[196:199], v[44:47]
	v_mfma_f32_16x16x32_bf16 v[40:43], v[164:167], v[196:199], v[40:43]
	v_mfma_f32_16x16x32_bf16 v[28:31], v[156:159], v[204:207], v[28:31]
	v_mfma_f32_16x16x32_bf16 v[24:27], v[164:167], v[204:207], v[24:27]
	v_mfma_f32_16x16x32_bf16 v[12:15], v[156:159], v[212:215], v[12:15]
	v_mfma_f32_16x16x32_bf16 v[8:11], v[164:167], v[212:215], v[8:11]
	s_setprio 0
	s_setprio 1
	v_mfma_f32_16x16x32_bf16 v[52:55], v[168:171], v[184:187], 0
	v_mfma_f32_16x16x32_bf16 v[48:51], v[176:179], v[184:187], 0
	v_mfma_f32_16x16x32_bf16 v[36:39], v[168:171], v[192:195], 0
	v_mfma_f32_16x16x32_bf16 v[32:35], v[176:179], v[192:195], 0
	v_mfma_f32_16x16x32_bf16 v[20:23], v[168:171], v[200:203], 0
	v_mfma_f32_16x16x32_bf16 v[16:19], v[176:179], v[200:203], 0
	v_mfma_f32_16x16x32_bf16 v[4:7], v[168:171], v[208:211], 0
	v_mfma_f32_16x16x32_bf16 v[0:3], v[176:179], v[208:211], 0
	v_mfma_f32_16x16x32_bf16 v[52:55], v[172:175], v[188:191], v[52:55]
	v_mfma_f32_16x16x32_bf16 v[48:51], v[180:183], v[188:191], v[48:51]
	v_mfma_f32_16x16x32_bf16 v[36:39], v[172:175], v[196:199], v[36:39]
	v_mfma_f32_16x16x32_bf16 v[32:35], v[180:183], v[196:199], v[32:35]
	v_mfma_f32_16x16x32_bf16 v[20:23], v[172:175], v[204:207], v[20:23]
	v_mfma_f32_16x16x32_bf16 v[16:19], v[180:183], v[204:207], v[16:19]
	v_mfma_f32_16x16x32_bf16 v[4:7], v[172:175], v[212:215], v[4:7]
	v_mfma_f32_16x16x32_bf16 v[0:3], v[180:183], v[212:215], v[0:3]
	s_setprio 0
	s_barrier
	s_add_i32 s59, 0, 0x18000
	s_add_i32 s60, 0, 0x1c000
	v_add_u32_e32 v164, s59, v148
	v_add_u32_e32 v180, s60, v148
	ds_read_b128 v[152:155], v164
	ds_read_b128 v[156:159], v164 offset:1024
	ds_read_b128 v[160:163], v164 offset:2048
	ds_read_b128 v[164:167], v164 offset:3072
	ds_read_b128 v[168:171], v180
	ds_read_b128 v[172:175], v180 offset:1024
	ds_read_b128 v[176:179], v180 offset:2048
	ds_read_b128 v[180:183], v180 offset:3072
	s_add_u32 s26, s26, 0x40000
	s_addc_u32 s27, s27, 0
	s_mov_b32 m0, s38
	ds_read_b128 v[184:187], v151 offset:32768
	ds_read_b128 v[188:191], v151 offset:33792
	ds_read_b128 v[192:195], v151 offset:34816
	ds_read_b128 v[196:199], v151 offset:35840
	ds_read_b128 v[200:203], v151 offset:36864
	ds_read_b128 v[204:207], v151 offset:37888
	ds_read_b128 v[208:211], v151 offset:38912
	ds_read_b128 v[212:215], v151 offset:39936
	global_load_lds_dwordx4 v134, s[26:27]
	s_mov_b32 m0, s39
	s_nop 0
	global_load_lds_dwordx4 v130, s[26:27]
	s_waitcnt vmcnt(8)
	s_waitcnt lgkmcnt(0)
	s_barrier
	s_setprio 1
	s_waitcnt lgkmcnt(0)
	v_mfma_f32_16x16x32_bf16 v[124:127], v[152:155], v[184:187], v[124:127]
	v_mfma_f32_16x16x32_bf16 v[120:123], v[160:163], v[184:187], v[120:123]
	v_mfma_f32_16x16x32_bf16 v[108:111], v[152:155], v[192:195], v[108:111]
	v_mfma_f32_16x16x32_bf16 v[104:107], v[160:163], v[192:195], v[104:107]
	v_mfma_f32_16x16x32_bf16 v[92:95], v[152:155], v[200:203], v[92:95]
	v_mfma_f32_16x16x32_bf16 v[88:91], v[160:163], v[200:203], v[88:91]
	v_mfma_f32_16x16x32_bf16 v[76:79], v[152:155], v[208:211], v[76:79]
	v_mfma_f32_16x16x32_bf16 v[72:75], v[160:163], v[208:211], v[72:75]
	v_mfma_f32_16x16x32_bf16 v[124:127], v[156:159], v[188:191], v[124:127]
	v_mfma_f32_16x16x32_bf16 v[120:123], v[164:167], v[188:191], v[120:123]
	v_mfma_f32_16x16x32_bf16 v[108:111], v[156:159], v[196:199], v[108:111]
	v_mfma_f32_16x16x32_bf16 v[104:107], v[164:167], v[196:199], v[104:107]
	v_mfma_f32_16x16x32_bf16 v[92:95], v[156:159], v[204:207], v[92:95]
	v_mfma_f32_16x16x32_bf16 v[88:91], v[164:167], v[204:207], v[88:91]
	v_mfma_f32_16x16x32_bf16 v[76:79], v[156:159], v[212:215], v[76:79]
	v_mfma_f32_16x16x32_bf16 v[72:75], v[164:167], v[212:215], v[72:75]
	s_setprio 0
	s_setprio 1
	v_mfma_f32_16x16x32_bf16 v[116:119], v[168:171], v[184:187], v[116:119]
	v_mfma_f32_16x16x32_bf16 v[112:115], v[176:179], v[184:187], v[112:115]
	v_mfma_f32_16x16x32_bf16 v[100:103], v[168:171], v[192:195], v[100:103]
	v_mfma_f32_16x16x32_bf16 v[96:99], v[176:179], v[192:195], v[96:99]
	v_mfma_f32_16x16x32_bf16 v[84:87], v[168:171], v[200:203], v[84:87]
	v_mfma_f32_16x16x32_bf16 v[80:83], v[176:179], v[200:203], v[80:83]
	v_mfma_f32_16x16x32_bf16 v[68:71], v[168:171], v[208:211], v[68:71]
	v_mfma_f32_16x16x32_bf16 v[64:67], v[176:179], v[208:211], v[64:67]
	v_mfma_f32_16x16x32_bf16 v[116:119], v[172:175], v[188:191], v[116:119]
	v_mfma_f32_16x16x32_bf16 v[112:115], v[180:183], v[188:191], v[112:115]
	v_mfma_f32_16x16x32_bf16 v[100:103], v[172:175], v[196:199], v[100:103]
	v_mfma_f32_16x16x32_bf16 v[96:99], v[180:183], v[196:199], v[96:99]
	v_mfma_f32_16x16x32_bf16 v[84:87], v[172:175], v[204:207], v[84:87]
	v_mfma_f32_16x16x32_bf16 v[80:83], v[180:183], v[204:207], v[80:83]
	v_mfma_f32_16x16x32_bf16 v[68:71], v[172:175], v[212:215], v[68:71]
	v_mfma_f32_16x16x32_bf16 v[64:67], v[180:183], v[212:215], v[64:67]
	s_setprio 0
	s_barrier
	s_add_i32 s26, s59, s33
	s_mov_b32 m0, s26
	ds_read_b128 v[184:187], v151 offset:49152
	ds_read_b128 v[188:191], v151 offset:50176
	ds_read_b128 v[192:195], v151 offset:51200
	ds_read_b128 v[196:199], v151 offset:52224
	ds_read_b128 v[200:203], v151 offset:53248
	ds_read_b128 v[204:207], v151 offset:54272
	ds_read_b128 v[208:211], v151 offset:55296
	ds_read_b128 v[212:215], v151 offset:56320
	global_load_lds_dwordx4 v132, s[62:63]
	s_add_i32 m0, s26, 0x2000
	s_add_u32 s24, s24, 0x40080
	s_addc_u32 s25, s25, 0
	s_add_i32 s26, s60, s33
	global_load_lds_dwordx4 v128, s[62:63]
	s_mov_b32 m0, s26
	s_nop 0
	global_load_lds_dwordx4 v132, s[24:25]
	s_add_i32 m0, s26, 0x2000
	s_nop 0
	global_load_lds_dwordx4 v128, s[24:25]
	s_mov_b32 m0, s41
	s_nop 0
	global_load_lds_dwordx4 v134, s[64:65]
	s_mov_b32 m0, s42
	s_nop 0
	global_load_lds_dwordx4 v130, s[64:65]
	s_waitcnt vmcnt(8)
	s_waitcnt lgkmcnt(0)
	s_barrier
	s_setprio 1
	s_waitcnt lgkmcnt(0)
	v_mfma_f32_16x16x32_bf16 v[60:63], v[152:155], v[184:187], v[60:63]
	v_mfma_f32_16x16x32_bf16 v[56:59], v[160:163], v[184:187], v[56:59]
	v_mfma_f32_16x16x32_bf16 v[44:47], v[152:155], v[192:195], v[44:47]
	v_mfma_f32_16x16x32_bf16 v[40:43], v[160:163], v[192:195], v[40:43]
	v_mfma_f32_16x16x32_bf16 v[28:31], v[152:155], v[200:203], v[28:31]
	v_mfma_f32_16x16x32_bf16 v[24:27], v[160:163], v[200:203], v[24:27]
	v_mfma_f32_16x16x32_bf16 v[12:15], v[152:155], v[208:211], v[12:15]
	v_mfma_f32_16x16x32_bf16 v[8:11], v[160:163], v[208:211], v[8:11]
	v_mfma_f32_16x16x32_bf16 v[60:63], v[156:159], v[188:191], v[60:63]
	v_mfma_f32_16x16x32_bf16 v[56:59], v[164:167], v[188:191], v[56:59]
	v_mfma_f32_16x16x32_bf16 v[44:47], v[156:159], v[196:199], v[44:47]
	v_mfma_f32_16x16x32_bf16 v[40:43], v[164:167], v[196:199], v[40:43]
	v_mfma_f32_16x16x32_bf16 v[28:31], v[156:159], v[204:207], v[28:31]
	v_mfma_f32_16x16x32_bf16 v[24:27], v[164:167], v[204:207], v[24:27]
	v_mfma_f32_16x16x32_bf16 v[12:15], v[156:159], v[212:215], v[12:15]
	v_mfma_f32_16x16x32_bf16 v[8:11], v[164:167], v[212:215], v[8:11]
	s_setprio 0
	s_setprio 1
	v_mfma_f32_16x16x32_bf16 v[52:55], v[168:171], v[184:187], v[52:55]
	v_mfma_f32_16x16x32_bf16 v[48:51], v[176:179], v[184:187], v[48:51]
	v_mfma_f32_16x16x32_bf16 v[36:39], v[168:171], v[192:195], v[36:39]
	v_mfma_f32_16x16x32_bf16 v[32:35], v[176:179], v[192:195], v[32:35]
	v_mfma_f32_16x16x32_bf16 v[20:23], v[168:171], v[200:203], v[20:23]
	v_mfma_f32_16x16x32_bf16 v[16:19], v[176:179], v[200:203], v[16:19]
	v_mfma_f32_16x16x32_bf16 v[4:7], v[168:171], v[208:211], v[4:7]
	v_mfma_f32_16x16x32_bf16 v[0:3], v[176:179], v[208:211], v[0:3]
	v_mfma_f32_16x16x32_bf16 v[52:55], v[172:175], v[188:191], v[52:55]
	v_mfma_f32_16x16x32_bf16 v[48:51], v[180:183], v[188:191], v[48:51]
	v_mfma_f32_16x16x32_bf16 v[36:39], v[172:175], v[196:199], v[36:39]
	v_mfma_f32_16x16x32_bf16 v[32:35], v[180:183], v[196:199], v[32:35]
	v_mfma_f32_16x16x32_bf16 v[20:23], v[172:175], v[204:207], v[20:23]
	v_mfma_f32_16x16x32_bf16 v[16:19], v[180:183], v[204:207], v[16:19]
	v_mfma_f32_16x16x32_bf16 v[4:7], v[172:175], v[212:215], v[4:7]
	v_mfma_f32_16x16x32_bf16 v[0:3], v[180:183], v[212:215], v[0:3]
	s_setprio 0
	s_barrier
	s_add_i32 s58, s58, 2
	s_add_u32 s56, s56, 0x100
	s_addc_u32 s57, s57, 0
	s_add_u32 s22, s22, 0x100
	s_addc_u32 s23, s23, 0
	s_cmp_lt_u32 s58, 14
.LBB12_9:
	ds_read_b128 v[152:155], v149
	ds_read_b128 v[156:159], v149 offset:1024
	ds_read_b128 v[160:163], v149 offset:2048
	ds_read_b128 v[164:167], v149 offset:3072
	ds_read_b128 v[168:171], v150
	ds_read_b128 v[172:175], v150 offset:1024
	ds_read_b128 v[176:179], v150 offset:2048
	ds_read_b128 v[180:183], v150 offset:3072
	s_add_u32 s24, s22, 0xfffc0080
	s_addc_u32 s25, s23, -1
	s_cmp_eq_u32 s58, 12
	s_cselect_b32 s27, s15, s25
	s_cselect_b32 s26, s54, s24
	s_cselect_b32 s25, s13, s57
	s_cselect_b32 s24, s55, s56
	s_add_i32 m0, s36, 0xc000
	ds_read_b128 v[184:187], v151
	ds_read_b128 v[188:191], v151 offset:1024
	ds_read_b128 v[192:195], v151 offset:2048
	ds_read_b128 v[196:199], v151 offset:3072
	ds_read_b128 v[200:203], v151 offset:4096
	ds_read_b128 v[204:207], v151 offset:5120
	ds_read_b128 v[208:211], v151 offset:6144
	ds_read_b128 v[212:215], v151 offset:7168
	global_load_lds_dwordx4 v140, s[22:23]
	s_add_i32 m0, s36, 0xe000
	s_nop 0
	global_load_lds_dwordx4 v138, s[22:23]
	s_waitcnt vmcnt(8)
	s_waitcnt lgkmcnt(0)
	s_barrier
	s_setprio 1
	s_waitcnt lgkmcnt(0)
	v_mfma_f32_16x16x32_bf16 v[124:127], v[152:155], v[184:187], v[124:127]
	v_mfma_f32_16x16x32_bf16 v[120:123], v[160:163], v[184:187], v[120:123]
	v_mfma_f32_16x16x32_bf16 v[108:111], v[152:155], v[192:195], v[108:111]
	v_mfma_f32_16x16x32_bf16 v[104:107], v[160:163], v[192:195], v[104:107]
	v_mfma_f32_16x16x32_bf16 v[92:95], v[152:155], v[200:203], v[92:95]
	v_mfma_f32_16x16x32_bf16 v[88:91], v[160:163], v[200:203], v[88:91]
	v_mfma_f32_16x16x32_bf16 v[76:79], v[152:155], v[208:211], v[76:79]
	v_mfma_f32_16x16x32_bf16 v[72:75], v[160:163], v[208:211], v[72:75]
	v_mfma_f32_16x16x32_bf16 v[124:127], v[156:159], v[188:191], v[124:127]
	v_mfma_f32_16x16x32_bf16 v[120:123], v[164:167], v[188:191], v[120:123]
	v_mfma_f32_16x16x32_bf16 v[108:111], v[156:159], v[196:199], v[108:111]
	v_mfma_f32_16x16x32_bf16 v[104:107], v[164:167], v[196:199], v[104:107]
	v_mfma_f32_16x16x32_bf16 v[92:95], v[156:159], v[204:207], v[92:95]
	v_mfma_f32_16x16x32_bf16 v[88:91], v[164:167], v[204:207], v[88:91]
	v_mfma_f32_16x16x32_bf16 v[76:79], v[156:159], v[212:215], v[76:79]
	v_mfma_f32_16x16x32_bf16 v[72:75], v[164:167], v[212:215], v[72:75]
	s_setprio 0
	s_setprio 1
	v_mfma_f32_16x16x32_bf16 v[116:119], v[168:171], v[184:187], v[116:119]
	v_mfma_f32_16x16x32_bf16 v[112:115], v[176:179], v[184:187], v[112:115]
	v_mfma_f32_16x16x32_bf16 v[100:103], v[168:171], v[192:195], v[100:103]
	v_mfma_f32_16x16x32_bf16 v[96:99], v[176:179], v[192:195], v[96:99]
	v_mfma_f32_16x16x32_bf16 v[84:87], v[168:171], v[200:203], v[84:87]
	v_mfma_f32_16x16x32_bf16 v[80:83], v[176:179], v[200:203], v[80:83]
	v_mfma_f32_16x16x32_bf16 v[68:71], v[168:171], v[208:211], v[68:71]
	v_mfma_f32_16x16x32_bf16 v[64:67], v[176:179], v[208:211], v[64:67]
	v_mfma_f32_16x16x32_bf16 v[116:119], v[172:175], v[188:191], v[116:119]
	v_mfma_f32_16x16x32_bf16 v[112:115], v[180:183], v[188:191], v[112:115]
	v_mfma_f32_16x16x32_bf16 v[100:103], v[172:175], v[196:199], v[100:103]
	v_mfma_f32_16x16x32_bf16 v[96:99], v[180:183], v[196:199], v[96:99]
	v_mfma_f32_16x16x32_bf16 v[84:87], v[172:175], v[204:207], v[84:87]
	v_mfma_f32_16x16x32_bf16 v[80:83], v[180:183], v[204:207], v[80:83]
	v_mfma_f32_16x16x32_bf16 v[68:71], v[172:175], v[212:215], v[68:71]
	v_mfma_f32_16x16x32_bf16 v[64:67], v[180:183], v[212:215], v[64:67]
	s_setprio 0
	s_barrier
	s_add_i32 s59, s44, s33
	s_add_u32 s62, s24, 0x80
	s_addc_u32 s63, s25, 0
	s_mov_b32 m0, s59
	ds_read_b128 v[184:187], v151 offset:16384
	ds_read_b128 v[188:191], v151 offset:17408
	ds_read_b128 v[192:195], v151 offset:18432
	ds_read_b128 v[196:199], v151 offset:19456
	ds_read_b128 v[200:203], v151 offset:20480
	ds_read_b128 v[204:207], v151 offset:21504
	ds_read_b128 v[208:211], v151 offset:22528
	ds_read_b128 v[212:215], v151 offset:23552
	global_load_lds_dwordx4 v132, s[24:25]
	s_add_i32 m0, s59, 0x2000
	s_add_u32 s60, s24, 0x40000
	s_addc_u32 s61, s25, 0
	s_add_i32 s59, s45, s33
	global_load_lds_dwordx4 v128, s[24:25]
	s_mov_b32 m0, s59
	s_add_u32 s64, s26, 0x80
	s_addc_u32 s65, s27, 0
	global_load_lds_dwordx4 v132, s[60:61]
	s_add_i32 m0, s59, 0x2000
	s_nop 0
	global_load_lds_dwordx4 v128, s[60:61]
	s_mov_b32 m0, s36
	s_nop 0
	global_load_lds_dwordx4 v134, s[26:27]
	s_mov_b32 m0, s37
	s_nop 0
	global_load_lds_dwordx4 v130, s[26:27]
	s_waitcnt vmcnt(8)
	s_waitcnt lgkmcnt(0)
	s_barrier
	s_setprio 1
	s_waitcnt lgkmcnt(0)
	v_mfma_f32_16x16x32_bf16 v[60:63], v[152:155], v[184:187], v[60:63]
	v_mfma_f32_16x16x32_bf16 v[56:59], v[160:163], v[184:187], v[56:59]
	v_mfma_f32_16x16x32_bf16 v[44:47], v[152:155], v[192:195], v[44:47]
	v_mfma_f32_16x16x32_bf16 v[40:43], v[160:163], v[192:195], v[40:43]
	v_mfma_f32_16x16x32_bf16 v[28:31], v[152:155], v[200:203], v[28:31]
	v_mfma_f32_16x16x32_bf16 v[24:27], v[160:163], v[200:203], v[24:27]
	v_mfma_f32_16x16x32_bf16 v[12:15], v[152:155], v[208:211], v[12:15]
	v_mfma_f32_16x16x32_bf16 v[8:11], v[160:163], v[208:211], v[8:11]
	v_mfma_f32_16x16x32_bf16 v[60:63], v[156:159], v[188:191], v[60:63]
	v_mfma_f32_16x16x32_bf16 v[56:59], v[164:167], v[188:191], v[56:59]
	v_mfma_f32_16x16x32_bf16 v[44:47], v[156:159], v[196:199], v[44:47]
	v_mfma_f32_16x16x32_bf16 v[40:43], v[164:167], v[196:199], v[40:43]
	v_mfma_f32_16x16x32_bf16 v[28:31], v[156:159], v[204:207], v[28:31]
	v_mfma_f32_16x16x32_bf16 v[24:27], v[164:167], v[204:207], v[24:27]
	v_mfma_f32_16x16x32_bf16 v[12:15], v[156:159], v[212:215], v[12:15]
	v_mfma_f32_16x16x32_bf16 v[8:11], v[164:167], v[212:215], v[8:11]
	s_setprio 0
	s_setprio 1
	v_mfma_f32_16x16x32_bf16 v[52:55], v[168:171], v[184:187], v[52:55]
	v_mfma_f32_16x16x32_bf16 v[48:51], v[176:179], v[184:187], v[48:51]
	v_mfma_f32_16x16x32_bf16 v[36:39], v[168:171], v[192:195], v[36:39]
	v_mfma_f32_16x16x32_bf16 v[32:35], v[176:179], v[192:195], v[32:35]
	v_mfma_f32_16x16x32_bf16 v[20:23], v[168:171], v[200:203], v[20:23]
	v_mfma_f32_16x16x32_bf16 v[16:19], v[176:179], v[200:203], v[16:19]
	v_mfma_f32_16x16x32_bf16 v[4:7], v[168:171], v[208:211], v[4:7]
	v_mfma_f32_16x16x32_bf16 v[0:3], v[176:179], v[208:211], v[0:3]
	v_mfma_f32_16x16x32_bf16 v[52:55], v[172:175], v[188:191], v[52:55]
	v_mfma_f32_16x16x32_bf16 v[48:51], v[180:183], v[188:191], v[48:51]
	v_mfma_f32_16x16x32_bf16 v[36:39], v[172:175], v[196:199], v[36:39]
	v_mfma_f32_16x16x32_bf16 v[32:35], v[180:183], v[196:199], v[32:35]
	v_mfma_f32_16x16x32_bf16 v[20:23], v[172:175], v[204:207], v[20:23]
	v_mfma_f32_16x16x32_bf16 v[16:19], v[180:183], v[204:207], v[16:19]
	v_mfma_f32_16x16x32_bf16 v[4:7], v[172:175], v[212:215], v[4:7]
	v_mfma_f32_16x16x32_bf16 v[0:3], v[180:183], v[212:215], v[0:3]
	s_setprio 0
	s_barrier
	s_add_i32 s59, 0, 0x18000
	s_add_i32 s60, 0, 0x1c000
	v_add_u32_e32 v164, s59, v148
	v_add_u32_e32 v180, s60, v148
	ds_read_b128 v[152:155], v164
	ds_read_b128 v[156:159], v164 offset:1024
	ds_read_b128 v[160:163], v164 offset:2048
	ds_read_b128 v[164:167], v164 offset:3072
	ds_read_b128 v[168:171], v180
	ds_read_b128 v[172:175], v180 offset:1024
	ds_read_b128 v[176:179], v180 offset:2048
	ds_read_b128 v[180:183], v180 offset:3072
	s_add_u32 s26, s26, 0x40000
	s_addc_u32 s27, s27, 0
	s_mov_b32 m0, s38
	ds_read_b128 v[184:187], v151 offset:32768
	ds_read_b128 v[188:191], v151 offset:33792
	ds_read_b128 v[192:195], v151 offset:34816
	ds_read_b128 v[196:199], v151 offset:35840
	ds_read_b128 v[200:203], v151 offset:36864
	ds_read_b128 v[204:207], v151 offset:37888
	ds_read_b128 v[208:211], v151 offset:38912
	ds_read_b128 v[212:215], v151 offset:39936
	global_load_lds_dwordx4 v134, s[26:27]
	s_mov_b32 m0, s39
	s_nop 0
	global_load_lds_dwordx4 v130, s[26:27]
	s_waitcnt vmcnt(8)
	s_waitcnt lgkmcnt(0)
	s_barrier
	s_setprio 1
	s_waitcnt lgkmcnt(0)
	v_mfma_f32_16x16x32_bf16 v[124:127], v[152:155], v[184:187], v[124:127]
	v_mfma_f32_16x16x32_bf16 v[120:123], v[160:163], v[184:187], v[120:123]
	v_mfma_f32_16x16x32_bf16 v[108:111], v[152:155], v[192:195], v[108:111]
	v_mfma_f32_16x16x32_bf16 v[104:107], v[160:163], v[192:195], v[104:107]
	v_mfma_f32_16x16x32_bf16 v[92:95], v[152:155], v[200:203], v[92:95]
	v_mfma_f32_16x16x32_bf16 v[88:91], v[160:163], v[200:203], v[88:91]
	v_mfma_f32_16x16x32_bf16 v[76:79], v[152:155], v[208:211], v[76:79]
	v_mfma_f32_16x16x32_bf16 v[72:75], v[160:163], v[208:211], v[72:75]
	v_mfma_f32_16x16x32_bf16 v[124:127], v[156:159], v[188:191], v[124:127]
	v_mfma_f32_16x16x32_bf16 v[120:123], v[164:167], v[188:191], v[120:123]
	v_mfma_f32_16x16x32_bf16 v[108:111], v[156:159], v[196:199], v[108:111]
	v_mfma_f32_16x16x32_bf16 v[104:107], v[164:167], v[196:199], v[104:107]
	v_mfma_f32_16x16x32_bf16 v[92:95], v[156:159], v[204:207], v[92:95]
	v_mfma_f32_16x16x32_bf16 v[88:91], v[164:167], v[204:207], v[88:91]
	v_mfma_f32_16x16x32_bf16 v[76:79], v[156:159], v[212:215], v[76:79]
	v_mfma_f32_16x16x32_bf16 v[72:75], v[164:167], v[212:215], v[72:75]
	s_setprio 0
	s_setprio 1
	v_mfma_f32_16x16x32_bf16 v[116:119], v[168:171], v[184:187], v[116:119]
	v_mfma_f32_16x16x32_bf16 v[112:115], v[176:179], v[184:187], v[112:115]
	v_mfma_f32_16x16x32_bf16 v[100:103], v[168:171], v[192:195], v[100:103]
	v_mfma_f32_16x16x32_bf16 v[96:99], v[176:179], v[192:195], v[96:99]
	v_mfma_f32_16x16x32_bf16 v[84:87], v[168:171], v[200:203], v[84:87]
	v_mfma_f32_16x16x32_bf16 v[80:83], v[176:179], v[200:203], v[80:83]
	v_mfma_f32_16x16x32_bf16 v[68:71], v[168:171], v[208:211], v[68:71]
	v_mfma_f32_16x16x32_bf16 v[64:67], v[176:179], v[208:211], v[64:67]
	v_mfma_f32_16x16x32_bf16 v[116:119], v[172:175], v[188:191], v[116:119]
	v_mfma_f32_16x16x32_bf16 v[112:115], v[180:183], v[188:191], v[112:115]
	v_mfma_f32_16x16x32_bf16 v[100:103], v[172:175], v[196:199], v[100:103]
	v_mfma_f32_16x16x32_bf16 v[96:99], v[180:183], v[196:199], v[96:99]
	v_mfma_f32_16x16x32_bf16 v[84:87], v[172:175], v[204:207], v[84:87]
	v_mfma_f32_16x16x32_bf16 v[80:83], v[180:183], v[204:207], v[80:83]
	v_mfma_f32_16x16x32_bf16 v[68:71], v[172:175], v[212:215], v[68:71]
	v_mfma_f32_16x16x32_bf16 v[64:67], v[180:183], v[212:215], v[64:67]
	s_setprio 0
	s_barrier
	s_add_i32 s26, s59, s33
	s_mov_b32 m0, s26
	ds_read_b128 v[184:187], v151 offset:49152
	ds_read_b128 v[188:191], v151 offset:50176
	ds_read_b128 v[192:195], v151 offset:51200
	ds_read_b128 v[196:199], v151 offset:52224
	ds_read_b128 v[200:203], v151 offset:53248
	ds_read_b128 v[204:207], v151 offset:54272
	ds_read_b128 v[208:211], v151 offset:55296
	ds_read_b128 v[212:215], v151 offset:56320
	global_load_lds_dwordx4 v132, s[62:63]
	s_add_i32 m0, s26, 0x2000
	s_add_u32 s24, s24, 0x40080
	s_addc_u32 s25, s25, 0
	s_add_i32 s26, s60, s33
	global_load_lds_dwordx4 v128, s[62:63]
	s_mov_b32 m0, s26
	s_nop 0
	global_load_lds_dwordx4 v132, s[24:25]
	s_add_i32 m0, s26, 0x2000
	s_nop 0
	global_load_lds_dwordx4 v128, s[24:25]
	s_mov_b32 m0, s41
	s_nop 0
	global_load_lds_dwordx4 v134, s[64:65]
	s_mov_b32 m0, s42
	s_nop 0
	global_load_lds_dwordx4 v130, s[64:65]
	s_waitcnt vmcnt(8)
	s_waitcnt lgkmcnt(0)
	s_barrier
	s_setprio 1
	s_waitcnt lgkmcnt(0)
	v_mfma_f32_16x16x32_bf16 v[60:63], v[152:155], v[184:187], v[60:63]
	v_mfma_f32_16x16x32_bf16 v[56:59], v[160:163], v[184:187], v[56:59]
	v_mfma_f32_16x16x32_bf16 v[44:47], v[152:155], v[192:195], v[44:47]
	v_mfma_f32_16x16x32_bf16 v[40:43], v[160:163], v[192:195], v[40:43]
	v_mfma_f32_16x16x32_bf16 v[28:31], v[152:155], v[200:203], v[28:31]
	v_mfma_f32_16x16x32_bf16 v[24:27], v[160:163], v[200:203], v[24:27]
	v_mfma_f32_16x16x32_bf16 v[12:15], v[152:155], v[208:211], v[12:15]
	v_mfma_f32_16x16x32_bf16 v[8:11], v[160:163], v[208:211], v[8:11]
	v_mfma_f32_16x16x32_bf16 v[60:63], v[156:159], v[188:191], v[60:63]
	v_mfma_f32_16x16x32_bf16 v[56:59], v[164:167], v[188:191], v[56:59]
	v_mfma_f32_16x16x32_bf16 v[44:47], v[156:159], v[196:199], v[44:47]
	v_mfma_f32_16x16x32_bf16 v[40:43], v[164:167], v[196:199], v[40:43]
	v_mfma_f32_16x16x32_bf16 v[28:31], v[156:159], v[204:207], v[28:31]
	v_mfma_f32_16x16x32_bf16 v[24:27], v[164:167], v[204:207], v[24:27]
	v_mfma_f32_16x16x32_bf16 v[12:15], v[156:159], v[212:215], v[12:15]
	v_mfma_f32_16x16x32_bf16 v[8:11], v[164:167], v[212:215], v[8:11]
	s_setprio 0
	s_setprio 1
	v_mfma_f32_16x16x32_bf16 v[52:55], v[168:171], v[184:187], v[52:55]
	v_mfma_f32_16x16x32_bf16 v[48:51], v[176:179], v[184:187], v[48:51]
	v_mfma_f32_16x16x32_bf16 v[36:39], v[168:171], v[192:195], v[36:39]
	v_mfma_f32_16x16x32_bf16 v[32:35], v[176:179], v[192:195], v[32:35]
	v_mfma_f32_16x16x32_bf16 v[20:23], v[168:171], v[200:203], v[20:23]
	v_mfma_f32_16x16x32_bf16 v[16:19], v[176:179], v[200:203], v[16:19]
	v_mfma_f32_16x16x32_bf16 v[4:7], v[168:171], v[208:211], v[4:7]
	v_mfma_f32_16x16x32_bf16 v[0:3], v[176:179], v[208:211], v[0:3]
	v_mfma_f32_16x16x32_bf16 v[52:55], v[172:175], v[188:191], v[52:55]
	v_mfma_f32_16x16x32_bf16 v[48:51], v[180:183], v[188:191], v[48:51]
	v_mfma_f32_16x16x32_bf16 v[36:39], v[172:175], v[196:199], v[36:39]
	v_mfma_f32_16x16x32_bf16 v[32:35], v[180:183], v[196:199], v[32:35]
	v_mfma_f32_16x16x32_bf16 v[20:23], v[172:175], v[204:207], v[20:23]
	v_mfma_f32_16x16x32_bf16 v[16:19], v[180:183], v[204:207], v[16:19]
	v_mfma_f32_16x16x32_bf16 v[4:7], v[172:175], v[212:215], v[4:7]
	v_mfma_f32_16x16x32_bf16 v[0:3], v[180:183], v[212:215], v[0:3]
	s_setprio 0
	s_barrier
	s_add_i32 s58, s58, 2
	s_add_u32 s56, s56, 0x100
	s_addc_u32 s57, s57, 0
	s_add_u32 s22, s22, 0x100
	s_addc_u32 s23, s23, 0
	s_cmp_lt_u32 s58, 14
	s_cbranch_scc1 .LBB12_9
	s_andn2_b64 vcc, exec, s[10:11]
	s_cbranch_vccnz .LBB12_12
	s_barrier

	.amdhsa_kernel _Z10fwd_kernelILi12ELi13EEv4Args
		.amdhsa_group_segment_fixed_size 0
		.amdhsa_private_segment_fixed_size 0
		.amdhsa_kernarg_size 488
		.amdhsa_user_sgpr_count 2
		.amdhsa_user_sgpr_dispatch_ptr 0
		.amdhsa_user_sgpr_queue_ptr 0
		.amdhsa_user_sgpr_kernarg_segment_ptr 1
		.amdhsa_user_sgpr_dispatch_id 0
		.amdhsa_user_sgpr_kernarg_preload_length 0
		.amdhsa_user_sgpr_kernarg_preload_offset 0
		.amdhsa_user_sgpr_private_segment_size 0
		.amdhsa_uses_dynamic_stack 0
		.amdhsa_enable_private_segment 0
		.amdhsa_system_sgpr_workgroup_id_x 1
		.amdhsa_system_sgpr_workgroup_id_y 0
		.amdhsa_system_sgpr_workgroup_id_z 0
		.amdhsa_system_sgpr_workgroup_info 0
		.amdhsa_system_vgpr_workitem_id 0
		.amdhsa_next_free_vgpr 256
		.amdhsa_next_free_sgpr 70
		.amdhsa_accum_offset 256
		.amdhsa_reserve_vcc 1
		.amdhsa_float_round_mode_32 0
		.amdhsa_float_round_mode_16_64 0
		.amdhsa_float_denorm_mode_32 3
		.amdhsa_float_denorm_mode_16_64 3
		.amdhsa_dx10_clamp 1
		.amdhsa_ieee_mode 1
		.amdhsa_fp16_overflow 0
		.amdhsa_tg_split 0
		.amdhsa_exception_fp_ieee_invalid_op 0
		.amdhsa_exception_fp_denorm_src 0
		.amdhsa_exception_fp_ieee_div_zero 0
		.amdhsa_exception_fp_ieee_overflow 0
		.amdhsa_exception_fp_ieee_underflow 0
		.amdhsa_exception_fp_ieee_inexact 0
		.amdhsa_exception_int_div_zero 0
	.end_amdhsa_kernel

.LBB13_19:
	s_ashr_i32 s17, s16, 31
	v_cmp_lt_i64_e32 vcc, s[0:1], v[142:143]
	s_lshl_b64 s[0:1], s[16:17], 21
	s_add_u32 s18, s33, s0
	s_addc_u32 s19, s34, s1
	s_and_b64 s[0:1], vcc, exec
	s_cselect_b32 s17, s19, s27
	s_cselect_b32 s53, s18, s26
	s_ashr_i32 s15, s14, 31
	s_lshl_b64 s[0:1], s[14:15], 21
	s_add_u32 s20, s4, s0
	s_addc_u32 s21, s5, s1
	s_and_b64 s[0:1], vcc, exec
	s_cselect_b32 s15, s21, s25
	s_cselect_b32 s54, s20, s24
	s_add_u32 s55, s24, 0x100
	s_addc_u32 s56, s25, 0
	s_add_u32 s24, s26, 0x100080
	s_addc_u32 s25, s27, 0
	s_mov_b32 s57, -2
	ds_read_b128 v[152:155], v149
	ds_read_b128 v[156:159], v149 offset:1024
	ds_read_b128 v[160:163], v149 offset:2048
	ds_read_b128 v[164:167], v149 offset:3072
	ds_read_b128 v[168:171], v150
	ds_read_b128 v[172:175], v150 offset:1024
	ds_read_b128 v[176:179], v150 offset:2048
	ds_read_b128 v[180:183], v150 offset:3072
	s_add_u32 s26, s24, 0xfff00080
	s_addc_u32 s27, s25, -1
	s_cmp_eq_u32 s57, 60
	s_cselect_b32 s29, s17, s27
	s_cselect_b32 s28, s53, s26
	s_cselect_b32 s27, s15, s56
	s_cselect_b32 s26, s54, s55
	s_add_i32 m0, s35, 0xc000
	ds_read_b128 v[184:187], v151
	ds_read_b128 v[188:191], v151 offset:1024
	ds_read_b128 v[192:195], v151 offset:2048
	ds_read_b128 v[196:199], v151 offset:3072
	ds_read_b128 v[200:203], v151 offset:4096
	ds_read_b128 v[204:207], v151 offset:5120
	ds_read_b128 v[208:211], v151 offset:6144
	ds_read_b128 v[212:215], v151 offset:7168
	global_load_lds_dwordx4 v140, s[24:25]
	s_add_i32 m0, s35, 0xe000
	s_nop 0
	global_load_lds_dwordx4 v138, s[24:25]
	s_waitcnt vmcnt(8)
	s_waitcnt lgkmcnt(0)
	s_barrier
	s_setprio 1
	s_waitcnt lgkmcnt(0)
	v_mfma_f32_16x16x32_bf16 v[124:127], v[152:155], v[184:187], 0
	v_mfma_f32_16x16x32_bf16 v[120:123], v[160:163], v[184:187], 0
	v_mfma_f32_16x16x32_bf16 v[116:119], v[152:155], v[192:195], 0
	v_mfma_f32_16x16x32_bf16 v[108:111], v[160:163], v[192:195], 0
	v_mfma_f32_16x16x32_bf16 v[100:103], v[152:155], v[200:203], 0
	v_mfma_f32_16x16x32_bf16 v[92:95], v[160:163], v[200:203], 0
	v_mfma_f32_16x16x32_bf16 v[84:87], v[152:155], v[208:211], 0
	v_mfma_f32_16x16x32_bf16 v[76:79], v[160:163], v[208:211], 0
	v_mfma_f32_16x16x32_bf16 v[124:127], v[156:159], v[188:191], v[124:127]
	v_mfma_f32_16x16x32_bf16 v[120:123], v[164:167], v[188:191], v[120:123]
	v_mfma_f32_16x16x32_bf16 v[116:119], v[156:159], v[196:199], v[116:119]
	v_mfma_f32_16x16x32_bf16 v[108:111], v[164:167], v[196:199], v[108:111]
	v_mfma_f32_16x16x32_bf16 v[100:103], v[156:159], v[204:207], v[100:103]
	v_mfma_f32_16x16x32_bf16 v[92:95], v[164:167], v[204:207], v[92:95]
	v_mfma_f32_16x16x32_bf16 v[84:87], v[156:159], v[212:215], v[84:87]
	v_mfma_f32_16x16x32_bf16 v[76:79], v[164:167], v[212:215], v[76:79]
	s_setprio 0
	s_setprio 1
	v_mfma_f32_16x16x32_bf16 v[112:115], v[168:171], v[184:187], 0
	v_mfma_f32_16x16x32_bf16 v[104:107], v[176:179], v[184:187], 0
	v_mfma_f32_16x16x32_bf16 v[96:99], v[168:171], v[192:195], 0
	v_mfma_f32_16x16x32_bf16 v[88:91], v[176:179], v[192:195], 0
	v_mfma_f32_16x16x32_bf16 v[80:83], v[168:171], v[200:203], 0
	v_mfma_f32_16x16x32_bf16 v[72:75], v[176:179], v[200:203], 0
	v_mfma_f32_16x16x32_bf16 v[68:71], v[168:171], v[208:211], 0
	v_mfma_f32_16x16x32_bf16 v[64:67], v[176:179], v[208:211], 0
	v_mfma_f32_16x16x32_bf16 v[112:115], v[172:175], v[188:191], v[112:115]
	v_mfma_f32_16x16x32_bf16 v[104:107], v[180:183], v[188:191], v[104:107]
	v_mfma_f32_16x16x32_bf16 v[96:99], v[172:175], v[196:199], v[96:99]
	v_mfma_f32_16x16x32_bf16 v[88:91], v[180:183], v[196:199], v[88:91]
	v_mfma_f32_16x16x32_bf16 v[80:83], v[172:175], v[204:207], v[80:83]
	v_mfma_f32_16x16x32_bf16 v[72:75], v[180:183], v[204:207], v[72:75]
	v_mfma_f32_16x16x32_bf16 v[68:71], v[172:175], v[212:215], v[68:71]
	v_mfma_f32_16x16x32_bf16 v[64:67], v[180:183], v[212:215], v[64:67]
	s_setprio 0
	s_barrier
	s_add_i32 s58, s46, s31
	s_add_u32 s62, s26, 0x80
	s_addc_u32 s63, s27, 0
	s_mov_b32 m0, s58
	ds_read_b128 v[184:187], v151 offset:16384
	ds_read_b128 v[188:191], v151 offset:17408
	ds_read_b128 v[192:195], v151 offset:18432
	ds_read_b128 v[196:199], v151 offset:19456
	ds_read_b128 v[200:203], v151 offset:20480
	ds_read_b128 v[204:207], v151 offset:21504
	ds_read_b128 v[208:211], v151 offset:22528
	ds_read_b128 v[212:215], v151 offset:23552
	global_load_lds_dwordx4 v130, s[26:27]
	s_add_i32 m0, s58, 0x2000
	s_add_u32 s58, s26, 0x100000
	s_addc_u32 s59, s27, 0
	s_add_i32 s60, s47, s31
	global_load_lds_dwordx4 v134, s[26:27]
	s_mov_b32 m0, s60
	s_add_u32 s64, s28, 0x80
	s_addc_u32 s65, s29, 0
	global_load_lds_dwordx4 v130, s[58:59]
	s_add_i32 m0, s60, 0x2000
	s_nop 0
	global_load_lds_dwordx4 v134, s[58:59]
	s_mov_b32 m0, s35
	s_nop 0
	global_load_lds_dwordx4 v128, s[28:29]
	s_mov_b32 m0, s36
	s_nop 0
	global_load_lds_dwordx4 v132, s[28:29]
	s_waitcnt vmcnt(8)
	s_waitcnt lgkmcnt(0)
	s_barrier
	s_setprio 1
	s_waitcnt lgkmcnt(0)
	v_mfma_f32_16x16x32_bf16 v[60:63], v[152:155], v[184:187], 0
	v_mfma_f32_16x16x32_bf16 v[56:59], v[160:163], v[184:187], 0
	v_mfma_f32_16x16x32_bf16 v[52:55], v[152:155], v[192:195], 0
	v_mfma_f32_16x16x32_bf16 v[44:47], v[160:163], v[192:195], 0
	v_mfma_f32_16x16x32_bf16 v[36:39], v[152:155], v[200:203], 0
	v_mfma_f32_16x16x32_bf16 v[28:31], v[160:163], v[200:203], 0
	v_mfma_f32_16x16x32_bf16 v[20:23], v[152:155], v[208:211], 0
	v_mfma_f32_16x16x32_bf16 v[12:15], v[160:163], v[208:211], 0
	v_mfma_f32_16x16x32_bf16 v[60:63], v[156:159], v[188:191], v[60:63]
	v_mfma_f32_16x16x32_bf16 v[56:59], v[164:167], v[188:191], v[56:59]
	v_mfma_f32_16x16x32_bf16 v[52:55], v[156:159], v[196:199], v[52:55]
	v_mfma_f32_16x16x32_bf16 v[44:47], v[164:167], v[196:199], v[44:47]
	v_mfma_f32_16x16x32_bf16 v[36:39], v[156:159], v[204:207], v[36:39]
	v_mfma_f32_16x16x32_bf16 v[28:31], v[164:167], v[204:207], v[28:31]
	v_mfma_f32_16x16x32_bf16 v[20:23], v[156:159], v[212:215], v[20:23]
	v_mfma_f32_16x16x32_bf16 v[12:15], v[164:167], v[212:215], v[12:15]
	s_setprio 0
	s_setprio 1
	v_mfma_f32_16x16x32_bf16 v[48:51], v[168:171], v[184:187], 0
	v_mfma_f32_16x16x32_bf16 v[40:43], v[176:179], v[184:187], 0
	v_mfma_f32_16x16x32_bf16 v[32:35], v[168:171], v[192:195], 0
	v_mfma_f32_16x16x32_bf16 v[24:27], v[176:179], v[192:195], 0
	v_mfma_f32_16x16x32_bf16 v[16:19], v[168:171], v[200:203], 0
	v_mfma_f32_16x16x32_bf16 v[8:11], v[176:179], v[200:203], 0
	v_mfma_f32_16x16x32_bf16 v[4:7], v[168:171], v[208:211], 0
	v_mfma_f32_16x16x32_bf16 v[0:3], v[176:179], v[208:211], 0
	v_mfma_f32_16x16x32_bf16 v[48:51], v[172:175], v[188:191], v[48:51]
	v_mfma_f32_16x16x32_bf16 v[40:43], v[180:183], v[188:191], v[40:43]
	v_mfma_f32_16x16x32_bf16 v[32:35], v[172:175], v[196:199], v[32:35]
	v_mfma_f32_16x16x32_bf16 v[24:27], v[180:183], v[196:199], v[24:27]
	v_mfma_f32_16x16x32_bf16 v[16:19], v[172:175], v[204:207], v[16:19]
	v_mfma_f32_16x16x32_bf16 v[8:11], v[180:183], v[204:207], v[8:11]
	v_mfma_f32_16x16x32_bf16 v[4:7], v[172:175], v[212:215], v[4:7]
	v_mfma_f32_16x16x32_bf16 v[0:3], v[180:183], v[212:215], v[0:3]
	s_setprio 0
	s_barrier
	s_add_i32 s58, 0, 0x18000
	s_add_i32 s59, 0, 0x1c000
	v_add_u32_e32 v164, s58, v148
	v_add_u32_e32 v180, s59, v148
	ds_read_b128 v[152:155], v164
	ds_read_b128 v[156:159], v164 offset:1024
	ds_read_b128 v[160:163], v164 offset:2048
	ds_read_b128 v[164:167], v164 offset:3072
	ds_read_b128 v[168:171], v180
	ds_read_b128 v[172:175], v180 offset:1024
	ds_read_b128 v[176:179], v180 offset:2048
	ds_read_b128 v[180:183], v180 offset:3072
	s_add_u32 s28, s28, 0x100000
	s_addc_u32 s29, s29, 0
	s_mov_b32 m0, s37
	ds_read_b128 v[184:187], v151 offset:32768
	ds_read_b128 v[188:191], v151 offset:33792
	ds_read_b128 v[192:195], v151 offset:34816
	ds_read_b128 v[196:199], v151 offset:35840
	ds_read_b128 v[200:203], v151 offset:36864
	ds_read_b128 v[204:207], v151 offset:37888
	ds_read_b128 v[208:211], v151 offset:38912
	ds_read_b128 v[212:215], v151 offset:39936
	global_load_lds_dwordx4 v128, s[28:29]
	s_mov_b32 m0, s38
	s_nop 0
	global_load_lds_dwordx4 v132, s[28:29]
	s_waitcnt vmcnt(8)
	s_waitcnt lgkmcnt(0)
	s_barrier
	s_setprio 1
	s_waitcnt lgkmcnt(0)
	v_mfma_f32_16x16x32_bf16 v[124:127], v[152:155], v[184:187], v[124:127]
	v_mfma_f32_16x16x32_bf16 v[120:123], v[160:163], v[184:187], v[120:123]
	v_mfma_f32_16x16x32_bf16 v[116:119], v[152:155], v[192:195], v[116:119]
	v_mfma_f32_16x16x32_bf16 v[108:111], v[160:163], v[192:195], v[108:111]
	v_mfma_f32_16x16x32_bf16 v[100:103], v[152:155], v[200:203], v[100:103]
	v_mfma_f32_16x16x32_bf16 v[92:95], v[160:163], v[200:203], v[92:95]
	v_mfma_f32_16x16x32_bf16 v[84:87], v[152:155], v[208:211], v[84:87]
	v_mfma_f32_16x16x32_bf16 v[76:79], v[160:163], v[208:211], v[76:79]
	v_mfma_f32_16x16x32_bf16 v[124:127], v[156:159], v[188:191], v[124:127]
	v_mfma_f32_16x16x32_bf16 v[120:123], v[164:167], v[188:191], v[120:123]
	v_mfma_f32_16x16x32_bf16 v[116:119], v[156:159], v[196:199], v[116:119]
	v_mfma_f32_16x16x32_bf16 v[108:111], v[164:167], v[196:199], v[108:111]
	v_mfma_f32_16x16x32_bf16 v[100:103], v[156:159], v[204:207], v[100:103]
	v_mfma_f32_16x16x32_bf16 v[92:95], v[164:167], v[204:207], v[92:95]
	v_mfma_f32_16x16x32_bf16 v[84:87], v[156:159], v[212:215], v[84:87]
	v_mfma_f32_16x16x32_bf16 v[76:79], v[164:167], v[212:215], v[76:79]
	s_setprio 0
	s_setprio 1
	v_mfma_f32_16x16x32_bf16 v[112:115], v[168:171], v[184:187], v[112:115]
	v_mfma_f32_16x16x32_bf16 v[104:107], v[176:179], v[184:187], v[104:107]
	v_mfma_f32_16x16x32_bf16 v[96:99], v[168:171], v[192:195], v[96:99]
	v_mfma_f32_16x16x32_bf16 v[88:91], v[176:179], v[192:195], v[88:91]
	v_mfma_f32_16x16x32_bf16 v[80:83], v[168:171], v[200:203], v[80:83]
	v_mfma_f32_16x16x32_bf16 v[72:75], v[176:179], v[200:203], v[72:75]
	v_mfma_f32_16x16x32_bf16 v[68:71], v[168:171], v[208:211], v[68:71]
	v_mfma_f32_16x16x32_bf16 v[64:67], v[176:179], v[208:211], v[64:67]
	v_mfma_f32_16x16x32_bf16 v[112:115], v[172:175], v[188:191], v[112:115]
	v_mfma_f32_16x16x32_bf16 v[104:107], v[180:183], v[188:191], v[104:107]
	v_mfma_f32_16x16x32_bf16 v[96:99], v[172:175], v[196:199], v[96:99]
	v_mfma_f32_16x16x32_bf16 v[88:91], v[180:183], v[196:199], v[88:91]
	v_mfma_f32_16x16x32_bf16 v[80:83], v[172:175], v[204:207], v[80:83]
	v_mfma_f32_16x16x32_bf16 v[72:75], v[180:183], v[204:207], v[72:75]
	v_mfma_f32_16x16x32_bf16 v[68:71], v[172:175], v[212:215], v[68:71]
	v_mfma_f32_16x16x32_bf16 v[64:67], v[180:183], v[212:215], v[64:67]
	s_setprio 0
	s_barrier
	s_add_i32 s28, s58, s31
	s_mov_b32 m0, s28
	ds_read_b128 v[184:187], v151 offset:49152
	ds_read_b128 v[188:191], v151 offset:50176
	ds_read_b128 v[192:195], v151 offset:51200
	ds_read_b128 v[196:199], v151 offset:52224
	ds_read_b128 v[200:203], v151 offset:53248
	ds_read_b128 v[204:207], v151 offset:54272
	ds_read_b128 v[208:211], v151 offset:55296
	ds_read_b128 v[212:215], v151 offset:56320
	global_load_lds_dwordx4 v130, s[62:63]
	s_add_i32 m0, s28, 0x2000
	s_add_u32 s26, s26, 0x100080
	s_addc_u32 s27, s27, 0
	s_add_i32 s28, s59, s31
	global_load_lds_dwordx4 v134, s[62:63]
	s_mov_b32 m0, s28
	s_nop 0
	global_load_lds_dwordx4 v130, s[26:27]
	s_add_i32 m0, s28, 0x2000
	s_nop 0
	global_load_lds_dwordx4 v134, s[26:27]
	s_mov_b32 m0, s41
	s_nop 0
	global_load_lds_dwordx4 v128, s[64:65]
	s_mov_b32 m0, s42
	s_nop 0
	global_load_lds_dwordx4 v132, s[64:65]
	s_waitcnt vmcnt(8)
	s_waitcnt lgkmcnt(0)
	s_barrier
	s_setprio 1
	s_waitcnt lgkmcnt(0)
	v_mfma_f32_16x16x32_bf16 v[60:63], v[152:155], v[184:187], v[60:63]
	v_mfma_f32_16x16x32_bf16 v[56:59], v[160:163], v[184:187], v[56:59]
	v_mfma_f32_16x16x32_bf16 v[52:55], v[152:155], v[192:195], v[52:55]
	v_mfma_f32_16x16x32_bf16 v[44:47], v[160:163], v[192:195], v[44:47]
	v_mfma_f32_16x16x32_bf16 v[36:39], v[152:155], v[200:203], v[36:39]
	v_mfma_f32_16x16x32_bf16 v[28:31], v[160:163], v[200:203], v[28:31]
	v_mfma_f32_16x16x32_bf16 v[20:23], v[152:155], v[208:211], v[20:23]
	v_mfma_f32_16x16x32_bf16 v[12:15], v[160:163], v[208:211], v[12:15]
	v_mfma_f32_16x16x32_bf16 v[60:63], v[156:159], v[188:191], v[60:63]
	v_mfma_f32_16x16x32_bf16 v[56:59], v[164:167], v[188:191], v[56:59]
	v_mfma_f32_16x16x32_bf16 v[52:55], v[156:159], v[196:199], v[52:55]
	v_mfma_f32_16x16x32_bf16 v[44:47], v[164:167], v[196:199], v[44:47]
	v_mfma_f32_16x16x32_bf16 v[36:39], v[156:159], v[204:207], v[36:39]
	v_mfma_f32_16x16x32_bf16 v[28:31], v[164:167], v[204:207], v[28:31]
	v_mfma_f32_16x16x32_bf16 v[20:23], v[156:159], v[212:215], v[20:23]
	v_mfma_f32_16x16x32_bf16 v[12:15], v[164:167], v[212:215], v[12:15]
	s_setprio 0
	s_setprio 1
	v_mfma_f32_16x16x32_bf16 v[48:51], v[168:171], v[184:187], v[48:51]
	v_mfma_f32_16x16x32_bf16 v[40:43], v[176:179], v[184:187], v[40:43]
	v_mfma_f32_16x16x32_bf16 v[32:35], v[168:171], v[192:195], v[32:35]
	v_mfma_f32_16x16x32_bf16 v[24:27], v[176:179], v[192:195], v[24:27]
	v_mfma_f32_16x16x32_bf16 v[16:19], v[168:171], v[200:203], v[16:19]
	v_mfma_f32_16x16x32_bf16 v[8:11], v[176:179], v[200:203], v[8:11]
	v_mfma_f32_16x16x32_bf16 v[4:7], v[168:171], v[208:211], v[4:7]
	v_mfma_f32_16x16x32_bf16 v[0:3], v[176:179], v[208:211], v[0:3]
	v_mfma_f32_16x16x32_bf16 v[48:51], v[172:175], v[188:191], v[48:51]
	v_mfma_f32_16x16x32_bf16 v[40:43], v[180:183], v[188:191], v[40:43]
	v_mfma_f32_16x16x32_bf16 v[32:35], v[172:175], v[196:199], v[32:35]
	v_mfma_f32_16x16x32_bf16 v[24:27], v[180:183], v[196:199], v[24:27]
	v_mfma_f32_16x16x32_bf16 v[16:19], v[172:175], v[204:207], v[16:19]
	v_mfma_f32_16x16x32_bf16 v[8:11], v[180:183], v[204:207], v[8:11]
	v_mfma_f32_16x16x32_bf16 v[4:7], v[172:175], v[212:215], v[4:7]
	v_mfma_f32_16x16x32_bf16 v[0:3], v[180:183], v[212:215], v[0:3]
	s_setprio 0
	s_barrier
	s_add_i32 s57, s57, 2
	s_add_u32 s55, s55, 0x100
	s_addc_u32 s56, s56, 0
	s_add_u32 s24, s24, 0x100
	s_addc_u32 s25, s25, 0
	s_cmp_lt_u32 s57, 62
.LBB13_20:
	ds_read_b128 v[152:155], v149
	ds_read_b128 v[156:159], v149 offset:1024
	ds_read_b128 v[160:163], v149 offset:2048
	ds_read_b128 v[164:167], v149 offset:3072
	ds_read_b128 v[168:171], v150
	ds_read_b128 v[172:175], v150 offset:1024
	ds_read_b128 v[176:179], v150 offset:2048
	ds_read_b128 v[180:183], v150 offset:3072
	s_add_u32 s26, s24, 0xfff00080
	s_addc_u32 s27, s25, -1
	s_cmp_eq_u32 s57, 60
	s_cselect_b32 s29, s17, s27
	s_cselect_b32 s28, s53, s26
	s_cselect_b32 s27, s15, s56
	s_cselect_b32 s26, s54, s55
	s_add_i32 m0, s35, 0xc000
	ds_read_b128 v[184:187], v151
	ds_read_b128 v[188:191], v151 offset:1024
	ds_read_b128 v[192:195], v151 offset:2048
	ds_read_b128 v[196:199], v151 offset:3072
	ds_read_b128 v[200:203], v151 offset:4096
	ds_read_b128 v[204:207], v151 offset:5120
	ds_read_b128 v[208:211], v151 offset:6144
	ds_read_b128 v[212:215], v151 offset:7168
	global_load_lds_dwordx4 v140, s[24:25]
	s_add_i32 m0, s35, 0xe000
	s_nop 0
	global_load_lds_dwordx4 v138, s[24:25]
	s_waitcnt vmcnt(8)
	s_waitcnt lgkmcnt(0)
	s_barrier
	s_setprio 1
	s_waitcnt lgkmcnt(0)
	v_mfma_f32_16x16x32_bf16 v[124:127], v[152:155], v[184:187], v[124:127]
	v_mfma_f32_16x16x32_bf16 v[120:123], v[160:163], v[184:187], v[120:123]
	v_mfma_f32_16x16x32_bf16 v[116:119], v[152:155], v[192:195], v[116:119]
	v_mfma_f32_16x16x32_bf16 v[108:111], v[160:163], v[192:195], v[108:111]
	v_mfma_f32_16x16x32_bf16 v[100:103], v[152:155], v[200:203], v[100:103]
	v_mfma_f32_16x16x32_bf16 v[92:95], v[160:163], v[200:203], v[92:95]
	v_mfma_f32_16x16x32_bf16 v[84:87], v[152:155], v[208:211], v[84:87]
	v_mfma_f32_16x16x32_bf16 v[76:79], v[160:163], v[208:211], v[76:79]
	v_mfma_f32_16x16x32_bf16 v[124:127], v[156:159], v[188:191], v[124:127]
	v_mfma_f32_16x16x32_bf16 v[120:123], v[164:167], v[188:191], v[120:123]
	v_mfma_f32_16x16x32_bf16 v[116:119], v[156:159], v[196:199], v[116:119]
	v_mfma_f32_16x16x32_bf16 v[108:111], v[164:167], v[196:199], v[108:111]
	v_mfma_f32_16x16x32_bf16 v[100:103], v[156:159], v[204:207], v[100:103]
	v_mfma_f32_16x16x32_bf16 v[92:95], v[164:167], v[204:207], v[92:95]
	v_mfma_f32_16x16x32_bf16 v[84:87], v[156:159], v[212:215], v[84:87]
	v_mfma_f32_16x16x32_bf16 v[76:79], v[164:167], v[212:215], v[76:79]
	s_setprio 0
	s_setprio 1
	v_mfma_f32_16x16x32_bf16 v[112:115], v[168:171], v[184:187], v[112:115]
	v_mfma_f32_16x16x32_bf16 v[104:107], v[176:179], v[184:187], v[104:107]
	v_mfma_f32_16x16x32_bf16 v[96:99], v[168:171], v[192:195], v[96:99]
	v_mfma_f32_16x16x32_bf16 v[88:91], v[176:179], v[192:195], v[88:91]
	v_mfma_f32_16x16x32_bf16 v[80:83], v[168:171], v[200:203], v[80:83]
	v_mfma_f32_16x16x32_bf16 v[72:75], v[176:179], v[200:203], v[72:75]
	v_mfma_f32_16x16x32_bf16 v[68:71], v[168:171], v[208:211], v[68:71]
	v_mfma_f32_16x16x32_bf16 v[64:67], v[176:179], v[208:211], v[64:67]
	v_mfma_f32_16x16x32_bf16 v[112:115], v[172:175], v[188:191], v[112:115]
	v_mfma_f32_16x16x32_bf16 v[104:107], v[180:183], v[188:191], v[104:107]
	v_mfma_f32_16x16x32_bf16 v[96:99], v[172:175], v[196:199], v[96:99]
	v_mfma_f32_16x16x32_bf16 v[88:91], v[180:183], v[196:199], v[88:91]
	v_mfma_f32_16x16x32_bf16 v[80:83], v[172:175], v[204:207], v[80:83]
	v_mfma_f32_16x16x32_bf16 v[72:75], v[180:183], v[204:207], v[72:75]
	v_mfma_f32_16x16x32_bf16 v[68:71], v[172:175], v[212:215], v[68:71]
	v_mfma_f32_16x16x32_bf16 v[64:67], v[180:183], v[212:215], v[64:67]
	s_setprio 0
	s_barrier
	s_add_i32 s58, s46, s31
	s_add_u32 s62, s26, 0x80
	s_addc_u32 s63, s27, 0
	s_mov_b32 m0, s58
	ds_read_b128 v[184:187], v151 offset:16384
	ds_read_b128 v[188:191], v151 offset:17408
	ds_read_b128 v[192:195], v151 offset:18432
	ds_read_b128 v[196:199], v151 offset:19456
	ds_read_b128 v[200:203], v151 offset:20480
	ds_read_b128 v[204:207], v151 offset:21504
	ds_read_b128 v[208:211], v151 offset:22528
	ds_read_b128 v[212:215], v151 offset:23552
	global_load_lds_dwordx4 v130, s[26:27]
	s_add_i32 m0, s58, 0x2000
	s_add_u32 s58, s26, 0x100000
	s_addc_u32 s59, s27, 0
	s_add_i32 s60, s47, s31
	global_load_lds_dwordx4 v134, s[26:27]
	s_mov_b32 m0, s60
	s_add_u32 s64, s28, 0x80
	s_addc_u32 s65, s29, 0
	global_load_lds_dwordx4 v130, s[58:59]
	s_add_i32 m0, s60, 0x2000
	s_nop 0
	global_load_lds_dwordx4 v134, s[58:59]
	s_mov_b32 m0, s35
	s_nop 0
	global_load_lds_dwordx4 v128, s[28:29]
	s_mov_b32 m0, s36
	s_nop 0
	global_load_lds_dwordx4 v132, s[28:29]
	s_waitcnt vmcnt(8)
	s_waitcnt lgkmcnt(0)
	s_barrier
	s_setprio 1
	s_waitcnt lgkmcnt(0)
	v_mfma_f32_16x16x32_bf16 v[60:63], v[152:155], v[184:187], v[60:63]
	v_mfma_f32_16x16x32_bf16 v[56:59], v[160:163], v[184:187], v[56:59]
	v_mfma_f32_16x16x32_bf16 v[52:55], v[152:155], v[192:195], v[52:55]
	v_mfma_f32_16x16x32_bf16 v[44:47], v[160:163], v[192:195], v[44:47]
	v_mfma_f32_16x16x32_bf16 v[36:39], v[152:155], v[200:203], v[36:39]
	v_mfma_f32_16x16x32_bf16 v[28:31], v[160:163], v[200:203], v[28:31]
	v_mfma_f32_16x16x32_bf16 v[20:23], v[152:155], v[208:211], v[20:23]
	v_mfma_f32_16x16x32_bf16 v[12:15], v[160:163], v[208:211], v[12:15]
	v_mfma_f32_16x16x32_bf16 v[60:63], v[156:159], v[188:191], v[60:63]
	v_mfma_f32_16x16x32_bf16 v[56:59], v[164:167], v[188:191], v[56:59]
	v_mfma_f32_16x16x32_bf16 v[52:55], v[156:159], v[196:199], v[52:55]
	v_mfma_f32_16x16x32_bf16 v[44:47], v[164:167], v[196:199], v[44:47]
	v_mfma_f32_16x16x32_bf16 v[36:39], v[156:159], v[204:207], v[36:39]
	v_mfma_f32_16x16x32_bf16 v[28:31], v[164:167], v[204:207], v[28:31]
	v_mfma_f32_16x16x32_bf16 v[20:23], v[156:159], v[212:215], v[20:23]
	v_mfma_f32_16x16x32_bf16 v[12:15], v[164:167], v[212:215], v[12:15]
	s_setprio 0
	s_setprio 1
	v_mfma_f32_16x16x32_bf16 v[48:51], v[168:171], v[184:187], v[48:51]
	v_mfma_f32_16x16x32_bf16 v[40:43], v[176:179], v[184:187], v[40:43]
	v_mfma_f32_16x16x32_bf16 v[32:35], v[168:171], v[192:195], v[32:35]
	v_mfma_f32_16x16x32_bf16 v[24:27], v[176:179], v[192:195], v[24:27]
	v_mfma_f32_16x16x32_bf16 v[16:19], v[168:171], v[200:203], v[16:19]
	v_mfma_f32_16x16x32_bf16 v[8:11], v[176:179], v[200:203], v[8:11]
	v_mfma_f32_16x16x32_bf16 v[4:7], v[168:171], v[208:211], v[4:7]
	v_mfma_f32_16x16x32_bf16 v[0:3], v[176:179], v[208:211], v[0:3]
	v_mfma_f32_16x16x32_bf16 v[48:51], v[172:175], v[188:191], v[48:51]
	v_mfma_f32_16x16x32_bf16 v[40:43], v[180:183], v[188:191], v[40:43]
	v_mfma_f32_16x16x32_bf16 v[32:35], v[172:175], v[196:199], v[32:35]
	v_mfma_f32_16x16x32_bf16 v[24:27], v[180:183], v[196:199], v[24:27]
	v_mfma_f32_16x16x32_bf16 v[16:19], v[172:175], v[204:207], v[16:19]
	v_mfma_f32_16x16x32_bf16 v[8:11], v[180:183], v[204:207], v[8:11]
	v_mfma_f32_16x16x32_bf16 v[4:7], v[172:175], v[212:215], v[4:7]
	v_mfma_f32_16x16x32_bf16 v[0:3], v[180:183], v[212:215], v[0:3]
	s_setprio 0
	s_barrier
	s_add_i32 s58, 0, 0x18000
	s_add_i32 s59, 0, 0x1c000
	v_add_u32_e32 v164, s58, v148
	v_add_u32_e32 v180, s59, v148
	ds_read_b128 v[152:155], v164
	ds_read_b128 v[156:159], v164 offset:1024
	ds_read_b128 v[160:163], v164 offset:2048
	ds_read_b128 v[164:167], v164 offset:3072
	ds_read_b128 v[168:171], v180
	ds_read_b128 v[172:175], v180 offset:1024
	ds_read_b128 v[176:179], v180 offset:2048
	ds_read_b128 v[180:183], v180 offset:3072
	s_add_u32 s28, s28, 0x100000
	s_addc_u32 s29, s29, 0
	s_mov_b32 m0, s37
	ds_read_b128 v[184:187], v151 offset:32768
	ds_read_b128 v[188:191], v151 offset:33792
	ds_read_b128 v[192:195], v151 offset:34816
	ds_read_b128 v[196:199], v151 offset:35840
	ds_read_b128 v[200:203], v151 offset:36864
	ds_read_b128 v[204:207], v151 offset:37888
	ds_read_b128 v[208:211], v151 offset:38912
	ds_read_b128 v[212:215], v151 offset:39936
	global_load_lds_dwordx4 v128, s[28:29]
	s_mov_b32 m0, s38
	s_nop 0
	global_load_lds_dwordx4 v132, s[28:29]
	s_waitcnt vmcnt(8)
	s_waitcnt lgkmcnt(0)
	s_barrier
	s_setprio 1
	s_waitcnt lgkmcnt(0)
	v_mfma_f32_16x16x32_bf16 v[124:127], v[152:155], v[184:187], v[124:127]
	v_mfma_f32_16x16x32_bf16 v[120:123], v[160:163], v[184:187], v[120:123]
	v_mfma_f32_16x16x32_bf16 v[116:119], v[152:155], v[192:195], v[116:119]
	v_mfma_f32_16x16x32_bf16 v[108:111], v[160:163], v[192:195], v[108:111]
	v_mfma_f32_16x16x32_bf16 v[100:103], v[152:155], v[200:203], v[100:103]
	v_mfma_f32_16x16x32_bf16 v[92:95], v[160:163], v[200:203], v[92:95]
	v_mfma_f32_16x16x32_bf16 v[84:87], v[152:155], v[208:211], v[84:87]
	v_mfma_f32_16x16x32_bf16 v[76:79], v[160:163], v[208:211], v[76:79]
	v_mfma_f32_16x16x32_bf16 v[124:127], v[156:159], v[188:191], v[124:127]
	v_mfma_f32_16x16x32_bf16 v[120:123], v[164:167], v[188:191], v[120:123]
	v_mfma_f32_16x16x32_bf16 v[116:119], v[156:159], v[196:199], v[116:119]
	v_mfma_f32_16x16x32_bf16 v[108:111], v[164:167], v[196:199], v[108:111]
	v_mfma_f32_16x16x32_bf16 v[100:103], v[156:159], v[204:207], v[100:103]
	v_mfma_f32_16x16x32_bf16 v[92:95], v[164:167], v[204:207], v[92:95]
	v_mfma_f32_16x16x32_bf16 v[84:87], v[156:159], v[212:215], v[84:87]
	v_mfma_f32_16x16x32_bf16 v[76:79], v[164:167], v[212:215], v[76:79]
	s_setprio 0
	s_setprio 1
	v_mfma_f32_16x16x32_bf16 v[112:115], v[168:171], v[184:187], v[112:115]
	v_mfma_f32_16x16x32_bf16 v[104:107], v[176:179], v[184:187], v[104:107]
	v_mfma_f32_16x16x32_bf16 v[96:99], v[168:171], v[192:195], v[96:99]
	v_mfma_f32_16x16x32_bf16 v[88:91], v[176:179], v[192:195], v[88:91]
	v_mfma_f32_16x16x32_bf16 v[80:83], v[168:171], v[200:203], v[80:83]
	v_mfma_f32_16x16x32_bf16 v[72:75], v[176:179], v[200:203], v[72:75]
	v_mfma_f32_16x16x32_bf16 v[68:71], v[168:171], v[208:211], v[68:71]
	v_mfma_f32_16x16x32_bf16 v[64:67], v[176:179], v[208:211], v[64:67]
	v_mfma_f32_16x16x32_bf16 v[112:115], v[172:175], v[188:191], v[112:115]
	v_mfma_f32_16x16x32_bf16 v[104:107], v[180:183], v[188:191], v[104:107]
	v_mfma_f32_16x16x32_bf16 v[96:99], v[172:175], v[196:199], v[96:99]
	v_mfma_f32_16x16x32_bf16 v[88:91], v[180:183], v[196:199], v[88:91]
	v_mfma_f32_16x16x32_bf16 v[80:83], v[172:175], v[204:207], v[80:83]
	v_mfma_f32_16x16x32_bf16 v[72:75], v[180:183], v[204:207], v[72:75]
	v_mfma_f32_16x16x32_bf16 v[68:71], v[172:175], v[212:215], v[68:71]
	v_mfma_f32_16x16x32_bf16 v[64:67], v[180:183], v[212:215], v[64:67]
	s_setprio 0
	s_barrier
	s_add_i32 s28, s58, s31
	s_mov_b32 m0, s28
	ds_read_b128 v[184:187], v151 offset:49152
	ds_read_b128 v[188:191], v151 offset:50176
	ds_read_b128 v[192:195], v151 offset:51200
	ds_read_b128 v[196:199], v151 offset:52224
	ds_read_b128 v[200:203], v151 offset:53248
	ds_read_b128 v[204:207], v151 offset:54272
	ds_read_b128 v[208:211], v151 offset:55296
	ds_read_b128 v[212:215], v151 offset:56320
	global_load_lds_dwordx4 v130, s[62:63]
	s_add_i32 m0, s28, 0x2000
	s_add_u32 s26, s26, 0x100080
	s_addc_u32 s27, s27, 0
	s_add_i32 s28, s59, s31
	global_load_lds_dwordx4 v134, s[62:63]
	s_mov_b32 m0, s28
	s_nop 0
	global_load_lds_dwordx4 v130, s[26:27]
	s_add_i32 m0, s28, 0x2000
	s_nop 0
	global_load_lds_dwordx4 v134, s[26:27]
	s_mov_b32 m0, s41
	s_nop 0
	global_load_lds_dwordx4 v128, s[64:65]
	s_mov_b32 m0, s42
	s_nop 0
	global_load_lds_dwordx4 v132, s[64:65]
	s_waitcnt vmcnt(8)
	s_waitcnt lgkmcnt(0)
	s_barrier
	s_setprio 1
	s_waitcnt lgkmcnt(0)
	v_mfma_f32_16x16x32_bf16 v[60:63], v[152:155], v[184:187], v[60:63]
	v_mfma_f32_16x16x32_bf16 v[56:59], v[160:163], v[184:187], v[56:59]
	v_mfma_f32_16x16x32_bf16 v[52:55], v[152:155], v[192:195], v[52:55]
	v_mfma_f32_16x16x32_bf16 v[44:47], v[160:163], v[192:195], v[44:47]
	v_mfma_f32_16x16x32_bf16 v[36:39], v[152:155], v[200:203], v[36:39]
	v_mfma_f32_16x16x32_bf16 v[28:31], v[160:163], v[200:203], v[28:31]
	v_mfma_f32_16x16x32_bf16 v[20:23], v[152:155], v[208:211], v[20:23]
	v_mfma_f32_16x16x32_bf16 v[12:15], v[160:163], v[208:211], v[12:15]
	v_mfma_f32_16x16x32_bf16 v[60:63], v[156:159], v[188:191], v[60:63]
	v_mfma_f32_16x16x32_bf16 v[56:59], v[164:167], v[188:191], v[56:59]
	v_mfma_f32_16x16x32_bf16 v[52:55], v[156:159], v[196:199], v[52:55]
	v_mfma_f32_16x16x32_bf16 v[44:47], v[164:167], v[196:199], v[44:47]
	v_mfma_f32_16x16x32_bf16 v[36:39], v[156:159], v[204:207], v[36:39]
	v_mfma_f32_16x16x32_bf16 v[28:31], v[164:167], v[204:207], v[28:31]
	v_mfma_f32_16x16x32_bf16 v[20:23], v[156:159], v[212:215], v[20:23]
	v_mfma_f32_16x16x32_bf16 v[12:15], v[164:167], v[212:215], v[12:15]
	s_setprio 0
	s_setprio 1
	v_mfma_f32_16x16x32_bf16 v[48:51], v[168:171], v[184:187], v[48:51]
	v_mfma_f32_16x16x32_bf16 v[40:43], v[176:179], v[184:187], v[40:43]
	v_mfma_f32_16x16x32_bf16 v[32:35], v[168:171], v[192:195], v[32:35]
	v_mfma_f32_16x16x32_bf16 v[24:27], v[176:179], v[192:195], v[24:27]
	v_mfma_f32_16x16x32_bf16 v[16:19], v[168:171], v[200:203], v[16:19]
	v_mfma_f32_16x16x32_bf16 v[8:11], v[176:179], v[200:203], v[8:11]
	v_mfma_f32_16x16x32_bf16 v[4:7], v[168:171], v[208:211], v[4:7]
	v_mfma_f32_16x16x32_bf16 v[0:3], v[176:179], v[208:211], v[0:3]
	v_mfma_f32_16x16x32_bf16 v[48:51], v[172:175], v[188:191], v[48:51]
	v_mfma_f32_16x16x32_bf16 v[40:43], v[180:183], v[188:191], v[40:43]
	v_mfma_f32_16x16x32_bf16 v[32:35], v[172:175], v[196:199], v[32:35]
	v_mfma_f32_16x16x32_bf16 v[24:27], v[180:183], v[196:199], v[24:27]
	v_mfma_f32_16x16x32_bf16 v[16:19], v[172:175], v[204:207], v[16:19]
	v_mfma_f32_16x16x32_bf16 v[8:11], v[180:183], v[204:207], v[8:11]
	v_mfma_f32_16x16x32_bf16 v[4:7], v[172:175], v[212:215], v[4:7]
	v_mfma_f32_16x16x32_bf16 v[0:3], v[180:183], v[212:215], v[0:3]
	s_setprio 0
	s_barrier
	s_add_i32 s57, s57, 2
	s_add_u32 s55, s55, 0x100
	s_addc_u32 s56, s56, 0
	s_add_u32 s24, s24, 0x100
	s_addc_u32 s25, s25, 0
	s_cmp_lt_u32 s57, 62
	s_cbranch_scc1 .LBB13_20
	s_andn2_b64 vcc, exec, s[12:13]
	s_cbranch_vccnz .LBB13_23
	s_barrier

	.amdhsa_kernel _Z10fwd_kernelILi13ELi14EEv4Args
		.amdhsa_group_segment_fixed_size 0
		.amdhsa_private_segment_fixed_size 0
		.amdhsa_kernarg_size 488
		.amdhsa_user_sgpr_count 2
		.amdhsa_user_sgpr_dispatch_ptr 0
		.amdhsa_user_sgpr_queue_ptr 0
		.amdhsa_user_sgpr_kernarg_segment_ptr 1
		.amdhsa_user_sgpr_dispatch_id 0
		.amdhsa_user_sgpr_kernarg_preload_length 0
		.amdhsa_user_sgpr_kernarg_preload_offset 0
		.amdhsa_user_sgpr_private_segment_size 0
		.amdhsa_uses_dynamic_stack 0
		.amdhsa_enable_private_segment 0
		.amdhsa_system_sgpr_workgroup_id_x 1
		.amdhsa_system_sgpr_workgroup_id_y 0
		.amdhsa_system_sgpr_workgroup_id_z 0
		.amdhsa_system_sgpr_workgroup_info 0
		.amdhsa_system_vgpr_workitem_id 0
		.amdhsa_next_free_vgpr 240
		.amdhsa_next_free_sgpr 70
		.amdhsa_accum_offset 240
		.amdhsa_reserve_vcc 1
		.amdhsa_float_round_mode_32 0
		.amdhsa_float_round_mode_16_64 0
		.amdhsa_float_denorm_mode_32 3
		.amdhsa_float_denorm_mode_16_64 3
		.amdhsa_dx10_clamp 1
		.amdhsa_ieee_mode 1
		.amdhsa_fp16_overflow 0
		.amdhsa_tg_split 0
		.amdhsa_exception_fp_ieee_invalid_op 0
		.amdhsa_exception_fp_denorm_src 0
		.amdhsa_exception_fp_ieee_div_zero 0
		.amdhsa_exception_fp_ieee_overflow 0
		.amdhsa_exception_fp_ieee_underflow 0
		.amdhsa_exception_fp_ieee_inexact 0
		.amdhsa_exception_int_div_zero 0
	.end_amdhsa_kernel

amdhsa.kernels:
  - .agpr_count:     0
    .args:
      - .offset:         0
        .size:           232
        .value_kind:     by_value
      - .offset:         232
        .size:           4
        .value_kind:     hidden_block_count_x
      - .offset:         236
        .size:           4
        .value_kind:     hidden_block_count_y
      - .offset:         240
        .size:           4
        .value_kind:     hidden_block_count_z
      - .offset:         244
        .size:           2
        .value_kind:     hidden_group_size_x
      - .offset:         246
        .size:           2
        .value_kind:     hidden_group_size_y
      - .offset:         248
        .size:           2
        .value_kind:     hidden_group_size_z
      - .offset:         250
        .size:           2
        .value_kind:     hidden_remainder_x
      - .offset:         252
        .size:           2
        .value_kind:     hidden_remainder_y
      - .offset:         254
        .size:           2
        .value_kind:     hidden_remainder_z
      - .offset:         272
        .size:           8
        .value_kind:     hidden_global_offset_x
      - .offset:         280
        .size:           8
        .value_kind:     hidden_global_offset_y
      - .offset:         288
        .size:           8
        .value_kind:     hidden_global_offset_z
      - .offset:         296
        .size:           2
        .value_kind:     hidden_grid_dims
      - .offset:         352
        .size:           4
        .value_kind:     hidden_dynamic_lds_size
    .group_segment_fixed_size: 0
    .kernarg_segment_align: 8
    .kernarg_segment_size: 488
    .language:       OpenCL C
    .language_version:
      - 2
      - 0
    .max_flat_workgroup_size: 512
    .name:           _Z10fwd_kernelILi0ELi1EEv4Args
    .private_segment_fixed_size: 0
    .sgpr_count:     106
    .sgpr_spill_count: 0
    .symbol:         _Z10fwd_kernelILi0ELi1EEv4Args.kd
    .uniform_work_group_size: 1
    .uses_dynamic_stack: false
    .vgpr_count:     224
    .vgpr_spill_count: 0
    .wavefront_size: 64
  - .agpr_count:     0
    .args:
      - .offset:         0
        .size:           232
        .value_kind:     by_value
      - .offset:         232
        .size:           4
        .value_kind:     hidden_block_count_x
      - .offset:         236
        .size:           4
        .value_kind:     hidden_block_count_y
      - .offset:         240
        .size:           4
        .value_kind:     hidden_block_count_z
      - .offset:         244
        .size:           2
        .value_kind:     hidden_group_size_x
      - .offset:         246
        .size:           2
        .value_kind:     hidden_group_size_y
      - .offset:         248
        .size:           2
        .value_kind:     hidden_group_size_z
      - .offset:         250
        .size:           2
        .value_kind:     hidden_remainder_x
      - .offset:         252
        .size:           2
        .value_kind:     hidden_remainder_y
      - .offset:         254
        .size:           2
        .value_kind:     hidden_remainder_z
      - .offset:         272
        .size:           8
        .value_kind:     hidden_global_offset_x
      - .offset:         280
        .size:           8
        .value_kind:     hidden_global_offset_y
      - .offset:         288
        .size:           8
        .value_kind:     hidden_global_offset_z
      - .offset:         296
        .size:           2
        .value_kind:     hidden_grid_dims
      - .offset:         352
        .size:           4
        .value_kind:     hidden_dynamic_lds_size
    .group_segment_fixed_size: 0
    .kernarg_segment_align: 8
    .kernarg_segment_size: 488
    .language:       OpenCL C
    .language_version:
      - 2
      - 0
    .max_flat_workgroup_size: 512
    .name:           _Z10fwd_kernelILi1ELi2EEv4Args
    .private_segment_fixed_size: 0
    .sgpr_count:     72
    .sgpr_spill_count: 0
    .symbol:         _Z10fwd_kernelILi1ELi2EEv4Args.kd
    .uniform_work_group_size: 1
    .uses_dynamic_stack: false
    .vgpr_count:     256
    .vgpr_spill_count: 0
    .wavefront_size: 64
  - .agpr_count:     0
    .args:
      - .offset:         0
        .size:           232
        .value_kind:     by_value
      - .offset:         232
        .size:           4
        .value_kind:     hidden_block_count_x
      - .offset:         236
        .size:           4
        .value_kind:     hidden_block_count_y
      - .offset:         240
        .size:           4
        .value_kind:     hidden_block_count_z
      - .offset:         244
        .size:           2
        .value_kind:     hidden_group_size_x
      - .offset:         246
        .size:           2
        .value_kind:     hidden_group_size_y
      - .offset:         248
        .size:           2
        .value_kind:     hidden_group_size_z
      - .offset:         250
        .size:           2
        .value_kind:     hidden_remainder_x
      - .offset:         252
        .size:           2
        .value_kind:     hidden_remainder_y
      - .offset:         254
        .size:           2
        .value_kind:     hidden_remainder_z
      - .offset:         272
        .size:           8
        .value_kind:     hidden_global_offset_x
      - .offset:         280
        .size:           8
        .value_kind:     hidden_global_offset_y
      - .offset:         288
        .size:           8
        .value_kind:     hidden_global_offset_z
      - .offset:         296
        .size:           2
        .value_kind:     hidden_grid_dims
      - .offset:         352
        .size:           4
        .value_kind:     hidden_dynamic_lds_size
    .group_segment_fixed_size: 0
    .kernarg_segment_align: 8
    .kernarg_segment_size: 488
    .language:       OpenCL C
    .language_version:
      - 2
      - 0
    .max_flat_workgroup_size: 512
    .name:           _Z10fwd_kernelILi2ELi3EEv4Args
    .private_segment_fixed_size: 0
    .sgpr_count:     106
    .sgpr_spill_count: 11
    .symbol:         _Z10fwd_kernelILi2ELi3EEv4Args.kd
    .uniform_work_group_size: 1
    .uses_dynamic_stack: false
    .vgpr_count:     252
    .vgpr_spill_count: 0
    .wavefront_size: 64
  - .agpr_count:     0
    .args:
      - .offset:         0
        .size:           232
        .value_kind:     by_value
      - .offset:         232
        .size:           4
        .value_kind:     hidden_block_count_x
      - .offset:         236
        .size:           4
        .value_kind:     hidden_block_count_y
      - .offset:         240
        .size:           4
        .value_kind:     hidden_block_count_z
      - .offset:         244
        .size:           2
        .value_kind:     hidden_group_size_x
      - .offset:         246
        .size:           2
        .value_kind:     hidden_group_size_y
      - .offset:         248
        .size:           2
        .value_kind:     hidden_group_size_z
      - .offset:         250
        .size:           2
        .value_kind:     hidden_remainder_x
      - .offset:         252
        .size:           2
        .value_kind:     hidden_remainder_y
      - .offset:         254
        .size:           2
        .value_kind:     hidden_remainder_z
      - .offset:         272
        .size:           8
        .value_kind:     hidden_global_offset_x
      - .offset:         280
        .size:           8
        .value_kind:     hidden_global_offset_y
      - .offset:         288
        .size:           8
        .value_kind:     hidden_global_offset_z
      - .offset:         296
        .size:           2
        .value_kind:     hidden_grid_dims
      - .offset:         352
        .size:           4
        .value_kind:     hidden_dynamic_lds_size
    .group_segment_fixed_size: 0
    .kernarg_segment_align: 8
    .kernarg_segment_size: 488
    .language:       OpenCL C
    .language_version:
      - 2
      - 0
    .max_flat_workgroup_size: 512
    .name:           _Z10fwd_kernelILi3ELi4EEv4Args
    .private_segment_fixed_size: 0
    .sgpr_count:     76
    .sgpr_spill_count: 0
    .symbol:         _Z10fwd_kernelILi3ELi4EEv4Args.kd
    .uniform_work_group_size: 1
    .uses_dynamic_stack: false
    .vgpr_count:     240
    .vgpr_spill_count: 0
    .wavefront_size: 64
  - .agpr_count:     0
    .args:
      - .offset:         0
        .size:           232
        .value_kind:     by_value
      - .offset:         232
        .size:           4
        .value_kind:     hidden_block_count_x
      - .offset:         236
        .size:           4
        .value_kind:     hidden_block_count_y
      - .offset:         240
        .size:           4
        .value_kind:     hidden_block_count_z
      - .offset:         244
        .size:           2
        .value_kind:     hidden_group_size_x
      - .offset:         246
        .size:           2
        .value_kind:     hidden_group_size_y
      - .offset:         248
        .size:           2
        .value_kind:     hidden_group_size_z
      - .offset:         250
        .size:           2
        .value_kind:     hidden_remainder_x
      - .offset:         252
        .size:           2
        .value_kind:     hidden_remainder_y
      - .offset:         254
        .size:           2
        .value_kind:     hidden_remainder_z
      - .offset:         272
        .size:           8
        .value_kind:     hidden_global_offset_x
      - .offset:         280
        .size:           8
        .value_kind:     hidden_global_offset_y
      - .offset:         288
        .size:           8
        .value_kind:     hidden_global_offset_z
      - .offset:         296
        .size:           2
        .value_kind:     hidden_grid_dims
    .group_segment_fixed_size: 0
    .kernarg_segment_align: 8
    .kernarg_segment_size: 488
    .language:       OpenCL C
    .language_version:
      - 2
      - 0
    .max_flat_workgroup_size: 512
    .name:           _Z10fwd_kernelILi4ELi5EEv4Args
    .private_segment_fixed_size: 0
    .sgpr_count:     66
    .sgpr_spill_count: 0
    .symbol:         _Z10fwd_kernelILi4ELi5EEv4Args.kd
    .uniform_work_group_size: 1
    .uses_dynamic_stack: false
    .vgpr_count:     256
    .vgpr_spill_count: 0
    .wavefront_size: 64
  - .agpr_count:     0
    .args:
      - .offset:         0
        .size:           232
        .value_kind:     by_value
      - .offset:         232
        .size:           4
        .value_kind:     hidden_block_count_x
      - .offset:         236
        .size:           4
        .value_kind:     hidden_block_count_y
      - .offset:         240
        .size:           4
        .value_kind:     hidden_block_count_z
      - .offset:         244
        .size:           2
        .value_kind:     hidden_group_size_x
      - .offset:         246
        .size:           2
        .value_kind:     hidden_group_size_y
      - .offset:         248
        .size:           2
        .value_kind:     hidden_group_size_z
      - .offset:         250
        .size:           2
        .value_kind:     hidden_remainder_x
      - .offset:         252
        .size:           2
        .value_kind:     hidden_remainder_y
      - .offset:         254
        .size:           2
        .value_kind:     hidden_remainder_z
      - .offset:         272
        .size:           8
        .value_kind:     hidden_global_offset_x
      - .offset:         280
        .size:           8
        .value_kind:     hidden_global_offset_y
      - .offset:         288
        .size:           8
        .value_kind:     hidden_global_offset_z
      - .offset:         296
        .size:           2
        .value_kind:     hidden_grid_dims
      - .offset:         352
        .size:           4
        .value_kind:     hidden_dynamic_lds_size
    .group_segment_fixed_size: 0
    .kernarg_segment_align: 8
    .kernarg_segment_size: 488
    .language:       OpenCL C
    .language_version:
      - 2
      - 0
    .max_flat_workgroup_size: 512
    .name:           _Z10fwd_kernelILi5ELi6EEv4Args
    .private_segment_fixed_size: 0
    .sgpr_count:     76
    .sgpr_spill_count: 0
    .symbol:         _Z10fwd_kernelILi5ELi6EEv4Args.kd
    .uniform_work_group_size: 1
    .uses_dynamic_stack: false
    .vgpr_count:     256
    .vgpr_spill_count: 0
    .wavefront_size: 64
  - .agpr_count:     0
    .args:
      - .offset:         0
        .size:           232
        .value_kind:     by_value
      - .offset:         232
        .size:           4
        .value_kind:     hidden_block_count_x
      - .offset:         236
        .size:           4
        .value_kind:     hidden_block_count_y
      - .offset:         240
        .size:           4
        .value_kind:     hidden_block_count_z
      - .offset:         244
        .size:           2
        .value_kind:     hidden_group_size_x
      - .offset:         246
        .size:           2
        .value_kind:     hidden_group_size_y
      - .offset:         248
        .size:           2
        .value_kind:     hidden_group_size_z
      - .offset:         250
        .size:           2
        .value_kind:     hidden_remainder_x
      - .offset:         252
        .size:           2
        .value_kind:     hidden_remainder_y
      - .offset:         254
        .size:           2
        .value_kind:     hidden_remainder_z
      - .offset:         272
        .size:           8
        .value_kind:     hidden_global_offset_x
      - .offset:         280
        .size:           8
        .value_kind:     hidden_global_offset_y
      - .offset:         288
        .size:           8
        .value_kind:     hidden_global_offset_z
      - .offset:         296
        .size:           2
        .value_kind:     hidden_grid_dims
      - .offset:         352
        .size:           4
        .value_kind:     hidden_dynamic_lds_size
    .group_segment_fixed_size: 0
    .kernarg_segment_align: 8
    .kernarg_segment_size: 488
    .language:       OpenCL C
    .language_version:
      - 2
      - 0
    .max_flat_workgroup_size: 512
    .name:           _Z10fwd_kernelILi6ELi7EEv4Args
    .private_segment_fixed_size: 0
    .sgpr_count:     76
    .sgpr_spill_count: 0
    .symbol:         _Z10fwd_kernelILi6ELi7EEv4Args.kd
    .uniform_work_group_size: 1
    .uses_dynamic_stack: false
    .vgpr_count:     240
    .vgpr_spill_count: 0
    .wavefront_size: 64
  - .agpr_count:     0
    .args:
      - .offset:         0
        .size:           232
        .value_kind:     by_value
      - .offset:         232
        .size:           4
        .value_kind:     hidden_block_count_x
      - .offset:         236
        .size:           4
        .value_kind:     hidden_block_count_y
      - .offset:         240
        .size:           4
        .value_kind:     hidden_block_count_z
      - .offset:         244
        .size:           2
        .value_kind:     hidden_group_size_x
      - .offset:         246
        .size:           2
        .value_kind:     hidden_group_size_y
      - .offset:         248
        .size:           2
        .value_kind:     hidden_group_size_z
      - .offset:         250
        .size:           2
        .value_kind:     hidden_remainder_x
      - .offset:         252
        .size:           2
        .value_kind:     hidden_remainder_y
      - .offset:         254
        .size:           2
        .value_kind:     hidden_remainder_z
      - .offset:         272
        .size:           8
        .value_kind:     hidden_global_offset_x
      - .offset:         280
        .size:           8
        .value_kind:     hidden_global_offset_y
      - .offset:         288
        .size:           8
        .value_kind:     hidden_global_offset_z
      - .offset:         296
        .size:           2
        .value_kind:     hidden_grid_dims
    .group_segment_fixed_size: 0
    .kernarg_segment_align: 8
    .kernarg_segment_size: 488
    .language:       OpenCL C
    .language_version:
      - 2
      - 0
    .max_flat_workgroup_size: 512
    .name:           _Z10fwd_kernelILi7ELi8EEv4Args
    .private_segment_fixed_size: 0
    .sgpr_count:     66
    .sgpr_spill_count: 0
    .symbol:         _Z10fwd_kernelILi7ELi8EEv4Args.kd
    .uniform_work_group_size: 1
    .uses_dynamic_stack: false
    .vgpr_count:     256
    .vgpr_spill_count: 0
    .wavefront_size: 64
  - .agpr_count:     0
    .args:
      - .offset:         0
        .size:           232
        .value_kind:     by_value
      - .offset:         232
        .size:           4
        .value_kind:     hidden_block_count_x
      - .offset:         236
        .size:           4
        .value_kind:     hidden_block_count_y
      - .offset:         240
        .size:           4
        .value_kind:     hidden_block_count_z
      - .offset:         244
        .size:           2
        .value_kind:     hidden_group_size_x
      - .offset:         246
        .size:           2
        .value_kind:     hidden_group_size_y
      - .offset:         248
        .size:           2
        .value_kind:     hidden_group_size_z
      - .offset:         250
        .size:           2
        .value_kind:     hidden_remainder_x
      - .offset:         252
        .size:           2
        .value_kind:     hidden_remainder_y
      - .offset:         254
        .size:           2
        .value_kind:     hidden_remainder_z
      - .offset:         272
        .size:           8
        .value_kind:     hidden_global_offset_x
      - .offset:         280
        .size:           8
        .value_kind:     hidden_global_offset_y
      - .offset:         288
        .size:           8
        .value_kind:     hidden_global_offset_z
      - .offset:         296
        .size:           2
        .value_kind:     hidden_grid_dims
      - .offset:         352
        .size:           4
        .value_kind:     hidden_dynamic_lds_size
    .group_segment_fixed_size: 0
    .kernarg_segment_align: 8
    .kernarg_segment_size: 488
    .language:       OpenCL C
    .language_version:
      - 2
      - 0
    .max_flat_workgroup_size: 512
    .name:           _Z10fwd_kernelILi8ELi9EEv4Args
    .private_segment_fixed_size: 0
    .sgpr_count:     84
    .sgpr_spill_count: 0
    .symbol:         _Z10fwd_kernelILi8ELi9EEv4Args.kd
    .uniform_work_group_size: 1
    .uses_dynamic_stack: false
    .vgpr_count:     256
    .vgpr_spill_count: 0
    .wavefront_size: 64
  - .agpr_count:     0
    .args:
      - .offset:         0
        .size:           232
        .value_kind:     by_value
      - .offset:         232
        .size:           4
        .value_kind:     hidden_block_count_x
      - .offset:         236
        .size:           4
        .value_kind:     hidden_block_count_y
      - .offset:         240
        .size:           4
        .value_kind:     hidden_block_count_z
      - .offset:         244
        .size:           2
        .value_kind:     hidden_group_size_x
      - .offset:         246
        .size:           2
        .value_kind:     hidden_group_size_y
      - .offset:         248
        .size:           2
        .value_kind:     hidden_group_size_z
      - .offset:         250
        .size:           2
        .value_kind:     hidden_remainder_x
      - .offset:         252
        .size:           2
        .value_kind:     hidden_remainder_y
      - .offset:         254
        .size:           2
        .value_kind:     hidden_remainder_z
      - .offset:         272
        .size:           8
        .value_kind:     hidden_global_offset_x
      - .offset:         280
        .size:           8
        .value_kind:     hidden_global_offset_y
      - .offset:         288
        .size:           8
        .value_kind:     hidden_global_offset_z
      - .offset:         296
        .size:           2
        .value_kind:     hidden_grid_dims
      - .offset:         352
        .size:           4
        .value_kind:     hidden_dynamic_lds_size
    .group_segment_fixed_size: 0
    .kernarg_segment_align: 8
    .kernarg_segment_size: 488
    .language:       OpenCL C
    .language_version:
      - 2
      - 0
    .max_flat_workgroup_size: 512
    .name:           _Z10fwd_kernelILi9ELi10EEv4Args
    .private_segment_fixed_size: 0
    .sgpr_count:     82
    .sgpr_spill_count: 0
    .symbol:         _Z10fwd_kernelILi9ELi10EEv4Args.kd
    .uniform_work_group_size: 1
    .uses_dynamic_stack: false
    .vgpr_count:     200
    .vgpr_spill_count: 0
    .wavefront_size: 64
  - .agpr_count:     0
    .args:
      - .offset:         0
        .size:           232
        .value_kind:     by_value
      - .offset:         232
        .size:           4
        .value_kind:     hidden_block_count_x
      - .offset:         236
        .size:           4
        .value_kind:     hidden_block_count_y
      - .offset:         240
        .size:           4
        .value_kind:     hidden_block_count_z
      - .offset:         244
        .size:           2
        .value_kind:     hidden_group_size_x
      - .offset:         246
        .size:           2
        .value_kind:     hidden_group_size_y
      - .offset:         248
        .size:           2
        .value_kind:     hidden_group_size_z
      - .offset:         250
        .size:           2
        .value_kind:     hidden_remainder_x
      - .offset:         252
        .size:           2
        .value_kind:     hidden_remainder_y
      - .offset:         254
        .size:           2
        .value_kind:     hidden_remainder_z
      - .offset:         272
        .size:           8
        .value_kind:     hidden_global_offset_x
      - .offset:         280
        .size:           8
        .value_kind:     hidden_global_offset_y
      - .offset:         288
        .size:           8
        .value_kind:     hidden_global_offset_z
      - .offset:         296
        .size:           2
        .value_kind:     hidden_grid_dims
      - .offset:         352
        .size:           4
        .value_kind:     hidden_dynamic_lds_size
    .group_segment_fixed_size: 0
    .kernarg_segment_align: 8
    .kernarg_segment_size: 488
    .language:       OpenCL C
    .language_version:
      - 2
      - 0
    .max_flat_workgroup_size: 512
    .name:           _Z10fwd_kernelILi10ELi11EEv4Args
    .private_segment_fixed_size: 0
    .sgpr_count:     76
    .sgpr_spill_count: 0
    .symbol:         _Z10fwd_kernelILi10ELi11EEv4Args.kd
    .uniform_work_group_size: 1
    .uses_dynamic_stack: false
    .vgpr_count:     240
    .vgpr_spill_count: 0
    .wavefront_size: 64
  - .agpr_count:     0
    .args:
      - .offset:         0
        .size:           232
        .value_kind:     by_value
      - .offset:         232
        .size:           4
        .value_kind:     hidden_block_count_x
      - .offset:         236
        .size:           4
        .value_kind:     hidden_block_count_y
      - .offset:         240
        .size:           4
        .value_kind:     hidden_block_count_z
      - .offset:         244
        .size:           2
        .value_kind:     hidden_group_size_x
      - .offset:         246
        .size:           2
        .value_kind:     hidden_group_size_y
      - .offset:         248
        .size:           2
        .value_kind:     hidden_group_size_z
      - .offset:         250
        .size:           2
        .value_kind:     hidden_remainder_x
      - .offset:         252
        .size:           2
        .value_kind:     hidden_remainder_y
      - .offset:         254
        .size:           2
        .value_kind:     hidden_remainder_z
      - .offset:         272
        .size:           8
        .value_kind:     hidden_global_offset_x
      - .offset:         280
        .size:           8
        .value_kind:     hidden_global_offset_y
      - .offset:         288
        .size:           8
        .value_kind:     hidden_global_offset_z
      - .offset:         296
        .size:           2
        .value_kind:     hidden_grid_dims
    .group_segment_fixed_size: 0
    .kernarg_segment_align: 8
    .kernarg_segment_size: 488
    .language:       OpenCL C
    .language_version:
      - 2
      - 0
    .max_flat_workgroup_size: 512
    .name:           _Z10fwd_kernelILi11ELi12EEv4Args
    .private_segment_fixed_size: 0
    .sgpr_count:     66
    .sgpr_spill_count: 0
    .symbol:         _Z10fwd_kernelILi11ELi12EEv4Args.kd
    .uniform_work_group_size: 1
    .uses_dynamic_stack: false
    .vgpr_count:     256
    .vgpr_spill_count: 0
    .wavefront_size: 64
  - .agpr_count:     0
    .args:
      - .offset:         0
        .size:           232
        .value_kind:     by_value
      - .offset:         232
        .size:           4
        .value_kind:     hidden_block_count_x
      - .offset:         236
        .size:           4
        .value_kind:     hidden_block_count_y
      - .offset:         240
        .size:           4
        .value_kind:     hidden_block_count_z
      - .offset:         244
        .size:           2
        .value_kind:     hidden_group_size_x
      - .offset:         246
        .size:           2
        .value_kind:     hidden_group_size_y
      - .offset:         248
        .size:           2
        .value_kind:     hidden_group_size_z
      - .offset:         250
        .size:           2
        .value_kind:     hidden_remainder_x
      - .offset:         252
        .size:           2
        .value_kind:     hidden_remainder_y
      - .offset:         254
        .size:           2
        .value_kind:     hidden_remainder_z
      - .offset:         272
        .size:           8
        .value_kind:     hidden_global_offset_x
      - .offset:         280
        .size:           8
        .value_kind:     hidden_global_offset_y
      - .offset:         288
        .size:           8
        .value_kind:     hidden_global_offset_z
      - .offset:         296
        .size:           2
        .value_kind:     hidden_grid_dims
      - .offset:         352
        .size:           4
        .value_kind:     hidden_dynamic_lds_size
    .group_segment_fixed_size: 0
    .kernarg_segment_align: 8
    .kernarg_segment_size: 488
    .language:       OpenCL C
    .language_version:
      - 2
      - 0
    .max_flat_workgroup_size: 512
    .name:           _Z10fwd_kernelILi12ELi13EEv4Args
    .private_segment_fixed_size: 0
    .sgpr_count:     76
    .sgpr_spill_count: 0
    .symbol:         _Z10fwd_kernelILi12ELi13EEv4Args.kd
    .uniform_work_group_size: 1
    .uses_dynamic_stack: false
    .vgpr_count:     256
    .vgpr_spill_count: 0
    .wavefront_size: 64
  - .agpr_count:     0
    .args:
      - .offset:         0
        .size:           232
        .value_kind:     by_value
      - .offset:         232
        .size:           4
        .value_kind:     hidden_block_count_x
      - .offset:         236
        .size:           4
        .value_kind:     hidden_block_count_y
      - .offset:         240
        .size:           4
        .value_kind:     hidden_block_count_z
      - .offset:         244
        .size:           2
        .value_kind:     hidden_group_size_x
      - .offset:         246
        .size:           2
        .value_kind:     hidden_group_size_y
      - .offset:         248
        .size:           2
        .value_kind:     hidden_group_size_z
      - .offset:         250
        .size:           2
        .value_kind:     hidden_remainder_x
      - .offset:         252
        .size:           2
        .value_kind:     hidden_remainder_y
      - .offset:         254
        .size:           2
        .value_kind:     hidden_remainder_z
      - .offset:         272
        .size:           8
        .value_kind:     hidden_global_offset_x
      - .offset:         280
        .size:           8
        .value_kind:     hidden_global_offset_y
      - .offset:         288
        .size:           8
        .value_kind:     hidden_global_offset_z
      - .offset:         296
        .size:           2
        .value_kind:     hidden_grid_dims
      - .offset:         352
        .size:           4
        .value_kind:     hidden_dynamic_lds_size
    .group_segment_fixed_size: 0
    .kernarg_segment_align: 8
    .kernarg_segment_size: 488
    .language:       OpenCL C
    .language_version:
      - 2
      - 0
    .max_flat_workgroup_size: 512
    .name:           _Z10fwd_kernelILi13ELi14EEv4Args
    .private_segment_fixed_size: 0
    .sgpr_count:     76
    .sgpr_spill_count: 0
    .symbol:         _Z10fwd_kernelILi13ELi14EEv4Args.kd
    .uniform_work_group_size: 1
    .uses_dynamic_stack: false
    .vgpr_count:     240
    .vgpr_spill_count: 0
    .wavefront_size: 64
  - .agpr_count:     0
    .args:
      - .offset:         0
        .size:           232
        .value_kind:     by_value
      - .offset:         232
        .size:           4
        .value_kind:     hidden_block_count_x
      - .offset:         236
        .size:           4
        .value_kind:     hidden_block_count_y
      - .offset:         240
        .size:           4
        .value_kind:     hidden_block_count_z
      - .offset:         244
        .size:           2
        .value_kind:     hidden_group_size_x
      - .offset:         246
        .size:           2
        .value_kind:     hidden_group_size_y
      - .offset:         248
        .size:           2
        .value_kind:     hidden_group_size_z
      - .offset:         250
        .size:           2
        .value_kind:     hidden_remainder_x
      - .offset:         252
        .size:           2
        .value_kind:     hidden_remainder_y
      - .offset:         254
        .size:           2
        .value_kind:     hidden_remainder_z
      - .offset:         272
        .size:           8
        .value_kind:     hidden_global_offset_x
      - .offset:         280
        .size:           8
        .value_kind:     hidden_global_offset_y
      - .offset:         288
        .size:           8
        .value_kind:     hidden_global_offset_z
      - .offset:         296
        .size:           2
        .value_kind:     hidden_grid_dims
    .group_segment_fixed_size: 0
    .kernarg_segment_align: 8
    .kernarg_segment_size: 488
    .language:       OpenCL C
    .language_version:
      - 2
      - 0
    .max_flat_workgroup_size: 512
    .name:           _Z10fwd_kernelILi14ELi15EEv4Args
    .private_segment_fixed_size: 0
    .sgpr_count:     66
    .sgpr_spill_count: 0
    .symbol:         _Z10fwd_kernelILi14ELi15EEv4Args.kd
    .uniform_work_group_size: 1
    .uses_dynamic_stack: false
    .vgpr_count:     256
    .vgpr_spill_count: 0
    .wavefront_size: 64
